# P5 epilogue rewritten by hand: token rows interleaved over MFMA row blocks (A staging permuted) so conv neighbours are registers; gelu select replaced by max/fma; in-place scaling
# speedup vs baseline: 1.2015x; 1.2015x over previous
.LBB0_527:
	s_andn2_b64 vcc, exec, s[0:1]
	s_cbranch_vccnz .LBB0_629
	v_ashrrev_i32_e32 v1, 31, v12
	v_lshrrev_b32_e32 v1, 26, v1
	v_add_u32_e32 v1, v12, v1
	v_ashrrev_i32_e32 v8, 6, v1
	v_bfe_i32 v1, v12, 27, 1
	v_lshlrev_b32_e32 v0, 4, v12
	v_lshrrev_b32_e32 v1, 22, v1
	v_add_u32_e32 v1, v0, v1
	v_and_b32_e32 v1, 0xfffffc00, v1
	v_sub_u32_e32 v1, v0, v1
	v_lshrrev_b32_e32 v2, 4, v1
	v_bitop3_b32 v1, v2, v1, 32 bitop3:0x6c
	v_ashrrev_i32_e32 v3, 31, v1
	v_lshrrev_b32_e32 v3, 26, v3
	v_add_u32_e32 v3, v1, v3
	v_lshlrev_b32_e32 v2, 3, v8
	v_ashrrev_i32_e32 v9, 6, v3
	v_and_b32_e32 v3, 0xc0, v3
	v_and_b32_e32 v2, -16, v2
	v_sub_u32_e32 v1, v1, v3
	v_mov_b32_e32 v3, 1
	v_add_u32_e32 v2, v9, v2
	v_ashrrev_i16_sdwa v1, v3, sext(v1) dst_sel:DWORD dst_unused:UNUSED_PAD src0_sel:DWORD src1_sel:BYTE_0
	v_lshlrev_b32_e32 v4, 5, v8
	v_bfe_i32 v10, v1, 0, 16
	v_lshlrev_b32_e32 v1, 1, v2
	v_lshrrev_b32_e32 v5, 2, v2
	v_and_b32_e32 v6, 3, v9
	s_mov_b32 s3, 0x1fffe0
	v_and_b32_e32 v4, 32, v4
	v_and_b32_e32 v1, 24, v1
	v_and_b32_e32 v5, 4, v5
	v_and_or_b32 v6, v2, s3, v6
	v_or3_b32 v1, v6, v5, v1
	v_add_lshl_u32 v4, v4, v10, 1
	v_add_u32_e32 v0, 0x2000, v0
	v_lshl_add_u32 v138, v1, 11, v4
	v_ashrrev_i32_e32 v1, 31, v0
	v_lshrrev_b32_e32 v1, 22, v1
	v_add_u32_e32 v1, v0, v1
	v_ashrrev_i32_e32 v11, 10, v1
	v_mul_i32_i24_e32 v1, 0x400, v11
	v_sub_u32_e32 v0, v0, v1
	v_lshrrev_b32_e32 v1, 4, v0
	v_bitop3_b32 v0, v1, v0, 32 bitop3:0x6c
	v_lshl_add_u32 v136, v2, 11, v4
	v_bfe_u32 v200, v136, 11, 4
	v_bfe_u32 v201, v136, 15, 2
	v_lshl_or_b32 v200, v200, 2, v201
	v_and_b32_e32 v136, 0xfffe07ff, v136
	v_lshl_or_b32 v136, v200, 11, v136
	v_ashrrev_i32_e32 v2, 31, v0
	v_lshrrev_b32_e32 v2, 26, v2
	s_add_u32 s1, s74, 0xa00000
	v_add_u32_e32 v2, v0, v2
	s_mul_i32 s8, s33, 0xfe
	s_addc_u32 s5, s75, 0
	v_lshlrev_b32_e32 v1, 3, v11
	v_ashrrev_i32_e32 v13, 6, v2
	v_and_b32_e32 v2, 0xc0, v2
	s_ashr_i32 s4, s6, 6
	s_ashr_i32 s9, s8, 31
	s_ashr_i32 s11, s10, 31
	s_ashr_i32 s0, s6, 8
	v_and_b32_e32 v1, -16, v1
	v_sub_u32_e32 v0, v0, v2
	s_lshl_b32 s45, s4, 10
	s_lshl_b64 s[8:9], s[8:9], 11
	s_lshl_b64 s[12:13], s[10:11], 19
	v_add_u32_e32 v1, v13, v1
	v_ashrrev_i16_sdwa v0, v3, sext(v0) dst_sel:DWORD dst_unused:UNUSED_PAD src0_sel:DWORD src1_sel:BYTE_0
	s_add_u32 s12, s1, s12
	v_lshlrev_b32_e32 v4, 5, v11
	v_bfe_i32 v14, v0, 0, 16
	v_lshlrev_b32_e32 v0, 1, v1
	v_lshrrev_b32_e32 v2, 2, v1
	v_and_b32_e32 v3, 3, v13
	s_addc_u32 s13, s5, s13
	s_add_i32 s58, s45, 0
	v_and_b32_e32 v4, 32, v4
	v_and_b32_e32 v0, 24, v0
	v_and_b32_e32 v2, 4, v2
	v_and_or_b32 v3, v1, s3, v3
	s_add_i32 m0, s58, 0x10000
	v_or3_b32 v0, v3, v2, v0
	v_add_lshl_u32 v2, v4, v14, 1
	global_load_lds_dwordx4 v138, s[12:13]
	s_add_i32 m0, s58, 0x12000
	v_lshl_add_u32 v142, v0, 11, v2
	s_add_u32 s14, s12, 0x40000
	global_load_lds_dwordx4 v142, s[12:13]
	s_addc_u32 s15, s13, 0
	s_add_i32 m0, s58, 0x14000
	v_lshl_add_u32 v140, v1, 11, v2
	v_bfe_u32 v200, v140, 11, 4
	v_bfe_u32 v201, v140, 15, 2
	v_lshl_or_b32 v200, v200, 2, v201
	v_and_b32_e32 v140, 0xfffe07ff, v140
	v_lshl_or_b32 v140, v200, 11, v140
	global_load_lds_dwordx4 v138, s[14:15]
	s_add_i32 m0, s58, 0x16000
	s_add_u32 s3, s52, s8
	s_addc_u32 s7, s53, s9
	global_load_lds_dwordx4 v142, s[14:15]
	s_add_u32 s14, s3, 0xfffff800
	s_addc_u32 s15, s7, -1
	s_add_i32 s59, s58, 0x2000
	s_mov_b32 m0, s58
	s_add_u32 s8, s3, 0x3f800
	global_load_lds_dwordx4 v136, s[14:15]
	s_mov_b32 m0, s59
	s_addc_u32 s9, s7, 0
	s_add_i32 s69, s58, 0x4000
	global_load_lds_dwordx4 v140, s[14:15]
	s_mov_b32 m0, s69
	s_add_i32 s91, s58, 0x6000
	global_load_lds_dwordx4 v136, s[8:9]
	s_mov_b32 m0, s91
	v_writelane_b32 v244, s80, 42
	global_load_lds_dwordx4 v140, s[8:9]
	s_nop 0
	v_writelane_b32 v244, s81, 43
	v_writelane_b32 v244, s78, 44
	v_mov_b32_e32 v139, 0
	s_cmp_eq_u32 s0, 1
	v_writelane_b32 v244, s79, 45
	v_mov_b32_e32 v143, v139
	v_mov_b32_e32 v137, v139
	v_mov_b32_e32 v141, v139
	s_cselect_b64 s[8:9], -1, 0
	s_movk_i32 s48, 0x2000
	s_movk_i32 s64, 0xfe
	s_mov_b32 s97, 0
	v_lshl_add_u64 v[6:7], s[12:13], 0, v[138:139]
	v_lshl_add_u64 v[2:3], s[12:13], 0, v[142:143]
	v_lshl_add_u64 v[0:1], s[14:15], 0, v[136:137]
	v_writelane_b32 v244, s8, 46
	s_cmp_lg_u32 s0, 1
	v_lshl_add_u64 v[4:5], s[14:15], 0, v[140:141]
	v_writelane_b32 v244, s9, 47
	s_cbranch_scc1 .LBB0_530
	s_barrier
.LBB0_530:
	s_add_u32 s62, s74, 0x1f00000
	s_addc_u32 s63, s75, 0
	s_lshl_b32 s4, s4, 5
	s_mov_b64 s[74:75], 0x80
	s_and_b32 s60, s4, 0x60
	s_add_i32 m0, s58, 0x18000
	v_lshl_add_u64 v[6:7], v[6:7], 0, s[74:75]
	s_lshl_b32 s3, s0, 6
	v_and_b32_e32 v15, 48, v12
	s_lshl_b32 s7, s0, 13
	v_lshlrev_b32_e32 v16, 6, v12
	s_movk_i32 s8, 0x3c0
	s_lshl_b32 s4, s60, 7
	s_waitcnt vmcnt(2)
	s_barrier
	global_load_lds_dwordx4 v[6:7], off
	v_lshl_add_u64 v[2:3], v[2:3], 0, s[74:75]
	s_add_i32 m0, s58, 0x1a000
	s_add_i32 s93, s58, 0x8000
	s_add_i32 s95, s58, 0xa000
	v_and_or_b32 v15, v16, s8, v15
	global_load_lds_dwordx4 v[2:3], off
	v_lshl_add_u64 v[0:1], v[0:1], 0, s[74:75]
	s_mov_b32 m0, s93
	s_add_u32 s8, s12, 0x40080
	global_load_lds_dwordx4 v[0:1], off
	v_lshl_add_u64 v[0:1], v[4:5], 0, s[74:75]
	s_mov_b32 m0, s95
	s_addc_u32 s9, s13, 0
	global_load_lds_dwordx4 v[0:1], off
	s_add_i32 m0, s58, 0x1c000
	v_lshl_add_u64 v[0:1], s[8:9], 0, v[138:139]
	global_load_lds_dwordx4 v[0:1], off
	v_lshl_add_u64 v[0:1], s[8:9], 0, v[142:143]
	s_add_i32 m0, s58, 0x1e000
	v_lshlrev_b32_e32 v12, 2, v12
	global_load_lds_dwordx4 v[0:1], off
	v_and_b32_e32 v12, 32, v12
	s_cmpk_lt_u32 s6, 0x100
	v_bitop3_b32 v216, s4, v15, v12 bitop3:0xf6
	s_cselect_b64 s[70:71], -1, 0
	s_lshl_b32 s4, s0, 11
	s_add_i32 s6, 0, 0x20400
	s_add_i32 s78, s6, s4
	s_add_i32 s4, s0, 2
	v_bitop3_b32 v16, v15, s7, v12 bitop3:0xde
	s_lshl_b32 s7, s4, 11
	s_add_i32 s7, s6, s7
	s_mov_b32 s77, s7
	s_addk_i32 s7, 0x400
	v_writelane_b32 v244, s7, 0
	s_max_i32 s7, s0, 1
	s_min_i32 s0, s0, 2
	s_lshl_b32 s0, s0, 11
	s_add_i32 s0, s6, s0
	v_writelane_b32 v244, s0, 26
	s_max_i32 s0, s4, 1
	s_lshl_b32 s0, s0, 11
	s_add_i32 s82, s6, s0
	s_min_i32 s0, s4, 2
	s_lshl_b32 s0, s0, 11
	s_add_i32 s0, s6, s0
	s_lshl_b32 s7, s7, 11
	v_writelane_b32 v244, s0, 40
	s_add_i32 s81, s6, s7
	v_readlane_b32 s16, v244, 4
	s_add_i32 s79, s78, 0x400
	s_addk_i32 s81, 0xfc00
	s_addk_i32 s82, 0xfc00
	s_ashr_i32 s83, s66, 31
	s_ashr_i32 s85, s2, 31
	v_readlane_b32 s26, v244, 14
	v_readlane_b32 s27, v244, 15
	s_add_u32 s6, s26, 0x2c00
	s_addc_u32 s7, s27, 0
	v_readlane_b32 s17, v244, 5
	v_readlane_b32 s18, v244, 6
	v_readlane_b32 s19, v244, 7
	v_readlane_b32 s20, v244, 8
	v_readlane_b32 s21, v244, 9
	v_readlane_b32 s22, v244, 10
	v_readlane_b32 s23, v244, 11
	v_readlane_b32 s24, v244, 12
	v_readlane_b32 s25, v244, 13
	v_readlane_b32 s28, v244, 16
	v_readlane_b32 s29, v244, 17
	v_readlane_b32 s30, v244, 18
	v_readlane_b32 s31, v244, 19
	v_writelane_b32 v244, s6, 20
	v_lshlrev_b32_e32 v0, 14, v8
	v_and_b32_e32 v0, 0xffff8000, v0
	v_writelane_b32 v244, s7, 21
	s_add_u32 s6, s26, 0x5800
	s_addc_u32 s7, s27, 0
	v_writelane_b32 v244, s6, 22
	v_lshl_add_u32 v0, v9, 11, v0
	v_and_b32_e32 v1, 1, v8
	v_writelane_b32 v244, s7, 23
	s_add_u32 s6, s26, 0x8400
	s_addc_u32 s7, s27, 0
	v_writelane_b32 v244, s6, 48
	v_lshl_or_b32 v0, v1, 6, v0
	v_lshl_add_u32 v144, v10, 1, v0
	v_bfe_u32 v200, v144, 11, 4
	v_bfe_u32 v201, v144, 15, 2
	v_lshl_or_b32 v200, v200, 2, v201
	v_and_b32_e32 v144, 0xfffe07ff, v144
	v_lshl_or_b32 v144, v200, 11, v144
	v_writelane_b32 v244, s7, 49
	s_add_u32 s6, s26, 0xb000
	s_addc_u32 s7, s27, 0
	v_writelane_b32 v244, s6, 50
	v_lshlrev_b32_e32 v0, 14, v11
	v_and_b32_e32 v0, 0xffff8000, v0
	v_writelane_b32 v244, s7, 51
	s_add_u32 s6, s26, 0xdc00
	s_addc_u32 s7, s27, 0
	v_writelane_b32 v244, s6, 52
	s_waitcnt vmcnt(6)
	v_lshl_add_u32 v0, v13, 11, v0
	v_and_b32_e32 v1, 1, v11
	v_writelane_b32 v244, s7, 53
	s_add_u32 s6, s28, 0x2c00
	s_addc_u32 s7, s29, 0
	v_writelane_b32 v244, s6, 54
	v_lshl_or_b32 v0, v1, 6, v0
	s_add_i32 s86, 0, 0x10000
	v_writelane_b32 v244, s7, 55
	s_add_i32 s87, 0, 0x14000
	v_readlane_b32 s50, v244, 24
	s_mov_b32 s84, s66
	v_mov_b32_e32 v145, v139
	v_lshl_add_u32 v146, v14, 1, v0
	v_bfe_u32 v200, v146, 11, 4
	v_bfe_u32 v201, v146, 15, 2
	v_lshl_or_b32 v200, v200, 2, v201
	v_and_b32_e32 v146, 0xfffe07ff, v146
	v_lshl_or_b32 v146, v200, 11, v146
	v_mov_b32_e32 v147, v139
	v_mov_b64_e32 v[148:149], 0x10ac
	v_mov_b64_e32 v[150:151], 0x10ab
	v_add_u32_e32 v217, s86, v216
	v_add_u32_e32 v218, s87, v216
	v_add_u32_e32 v219, 0, v16
	s_mov_b32 s88, 0xc000
	s_movk_i32 s89, 0xff
	s_mov_b32 s90, 0x3e6d3388
	s_mov_b32 s92, 0x3f07dc22
	s_mov_b32 s94, 0xbf3a00e3
	s_mov_b32 s96, 0x3f35f0e3
	s_mov_b32 s0, 0xbe11a98e
	s_mov_b32 s4, 0x3e027906
	s_mov_b32 s44, 0xbf38aa3b
	s_movk_i32 s61, 0x1600
	s_movk_i32 s80, 0x3fff
	v_mov_b32_e32 v220, 0xbfff
	v_mov_b32_e32 v221, 0x7ff
	v_mov_b32_e32 v222, 0x3fff
	v_readlane_b32 s51, v244, 25
	s_barrier
	s_branch .LBB0_533

.LBB0_545:
	s_mul_i32 s28, s33, 0xfe
	s_add_i32 s8, s28, -1
	v_readlane_b32 s12, v244, 14
	v_readlane_b32 s13, v244, 15
	v_readlane_b32 s14, v244, 20
	v_readlane_b32 s15, v244, 21
	v_readlane_b32 s16, v244, 22
	v_readlane_b32 s17, v244, 23
	v_readlane_b32 s18, v244, 48
	v_readlane_b32 s19, v244, 49
	v_readlane_b32 s20, v244, 50
	v_readlane_b32 s21, v244, 51
	v_readlane_b32 s22, v244, 52
	v_readlane_b32 s23, v244, 53
	v_readlane_b32 s24, v244, 16
	v_readlane_b32 s25, v244, 17
	v_readlane_b32 s26, v244, 54
	v_readlane_b32 s27, v244, 55
	v_and_b32_e32 v223, 15, v214
	v_lshrrev_b32_e32 v225, 1, v214
	s_lshl_b32 s9, s3, 5
	v_and_or_b32 v225, v225, 24, s60
	s_add_i32 s9, s9, 0x20400
	v_lshl_or_b32 v226, s10, 7, v225
	v_lshl_add_u32 v227, v223, 2, s3
	v_lshl_add_u32 v229, v225, 2, s9
	v_add_u32_e32 v228, s8, v227
	v_lshlrev_b32_e32 v230, 1, v226
	v_mad_u32_u24 v230, v228, s61, v230
	v_lshlrev_b32_e32 v226, 2, v226
	v_mov_b32_e32 v168, v228
	v_med3_i32 v168, v168, 0, v220
	v_lshlrev_b32_e32 v168, 2, v168
	v_add_u32_e32 v169, 1, v228
	v_med3_i32 v169, v169, 0, v220
	v_lshlrev_b32_e32 v169, 2, v169
	v_add_u32_e32 v170, 2, v228
	v_med3_i32 v170, v170, 0, v220
	v_lshlrev_b32_e32 v170, 2, v170
	v_add_u32_e32 v171, 3, v228
	v_med3_i32 v171, v171, 0, v220
	v_lshlrev_b32_e32 v171, 2, v171
	v_add_u32_e32 v172, 128, v228
	v_med3_i32 v172, v172, 0, v220
	v_lshlrev_b32_e32 v172, 2, v172
	v_add_u32_e32 v173, 129, v228
	v_med3_i32 v173, v173, 0, v220
	v_lshlrev_b32_e32 v173, 2, v173
	v_add_u32_e32 v174, 130, v228
	v_med3_i32 v174, v174, 0, v220
	v_lshlrev_b32_e32 v174, 2, v174
	v_add_u32_e32 v175, 131, v228
	v_med3_i32 v175, v175, 0, v220
	v_lshlrev_b32_e32 v175, 2, v175
	global_load_dword v152, v168, s[62:63]
	global_load_dword v154, v169, s[62:63]
	global_load_dword v156, v170, s[62:63]
	global_load_dword v158, v171, s[62:63]
	global_load_dword v160, v172, s[62:63]
	global_load_dword v162, v173, s[62:63]
	global_load_dword v164, v174, s[62:63]
	global_load_dword v166, v175, s[62:63]
	global_load_dwordx4 v[176:179], v226, s[12:13]
	global_load_dwordx4 v[180:183], v226, s[14:15]
	global_load_dwordx4 v[184:187], v226, s[16:17]
	global_load_dwordx4 v[188:191], v226, s[18:19]
	global_load_dwordx4 v[192:195], v226, s[20:21]
	global_load_dwordx4 v[196:199], v226, s[22:23]
	global_load_dwordx4 v[200:203], v226, s[24:25]
	global_load_dwordx4 v[204:207], v226, s[26:27]
	s_lshr_b32 s11, s3, 6
	s_max_u32 s29, s11, 1
	s_lshl_b32 s29, s29, 11
	s_add_i32 s29, s29, 0x20000
	v_lshl_add_u32 v231, v225, 2, s29
	s_lshl_b32 s29, s11, 11
	s_add_i32 s29, s29, 0x21000
	v_lshl_add_u32 v232, v225, 2, s29
	s_addk_i32 s29, 0xfc00
	v_lshl_add_u32 v233, v225, 2, s29
	v_lshlrev_b32_e32 v234, 2, v225
	v_add_u32_e32 v234, 0x21c00, v234
	v_mov_b32_e32 v236, s94
	s_waitcnt vmcnt(8)
	v_pk_mul_f32 v[48:49], v[48:49], v[152:153] op_sel_hi:[1,0]
	v_pk_mul_f32 v[50:51], v[50:51], v[152:153] op_sel_hi:[1,0]
	v_pk_mul_f32 v[24:25], v[24:25], v[152:153] op_sel_hi:[1,0]
	v_pk_mul_f32 v[26:27], v[26:27], v[152:153] op_sel_hi:[1,0]
	v_pk_mul_f32 v[52:53], v[52:53], v[152:153] op_sel_hi:[1,0]
	v_pk_mul_f32 v[54:55], v[54:55], v[152:153] op_sel_hi:[1,0]
	v_pk_mul_f32 v[28:29], v[28:29], v[152:153] op_sel_hi:[1,0]
	v_pk_mul_f32 v[30:31], v[30:31], v[152:153] op_sel_hi:[1,0]
	v_pk_mul_f32 v[124:125], v[124:125], v[154:155] op_sel_hi:[1,0]
	v_pk_mul_f32 v[126:127], v[126:127], v[154:155] op_sel_hi:[1,0]
	v_pk_mul_f32 v[120:121], v[120:121], v[154:155] op_sel_hi:[1,0]
	v_pk_mul_f32 v[122:123], v[122:123], v[154:155] op_sel_hi:[1,0]
	v_pk_mul_f32 v[116:117], v[116:117], v[154:155] op_sel_hi:[1,0]
	v_pk_mul_f32 v[118:119], v[118:119], v[154:155] op_sel_hi:[1,0]
	v_pk_mul_f32 v[108:109], v[108:109], v[154:155] op_sel_hi:[1,0]
	v_pk_mul_f32 v[110:111], v[110:111], v[154:155] op_sel_hi:[1,0]
	v_pk_mul_f32 v[112:113], v[112:113], v[156:157] op_sel_hi:[1,0]
	v_pk_mul_f32 v[114:115], v[114:115], v[156:157] op_sel_hi:[1,0]
	v_pk_mul_f32 v[104:105], v[104:105], v[156:157] op_sel_hi:[1,0]
	v_pk_mul_f32 v[106:107], v[106:107], v[156:157] op_sel_hi:[1,0]
	v_pk_mul_f32 v[100:101], v[100:101], v[156:157] op_sel_hi:[1,0]
	v_pk_mul_f32 v[102:103], v[102:103], v[156:157] op_sel_hi:[1,0]
	v_pk_mul_f32 v[96:97], v[96:97], v[156:157] op_sel_hi:[1,0]
	v_pk_mul_f32 v[98:99], v[98:99], v[156:157] op_sel_hi:[1,0]
	v_pk_mul_f32 v[60:61], v[60:61], v[158:159] op_sel_hi:[1,0]
	v_pk_mul_f32 v[62:63], v[62:63], v[158:159] op_sel_hi:[1,0]
	v_pk_mul_f32 v[16:17], v[16:17], v[158:159] op_sel_hi:[1,0]
	v_pk_mul_f32 v[18:19], v[18:19], v[158:159] op_sel_hi:[1,0]
	v_pk_mul_f32 v[44:45], v[44:45], v[158:159] op_sel_hi:[1,0]
	v_pk_mul_f32 v[46:47], v[46:47], v[158:159] op_sel_hi:[1,0]
	v_pk_mul_f32 v[20:21], v[20:21], v[158:159] op_sel_hi:[1,0]
	v_pk_mul_f32 v[22:23], v[22:23], v[158:159] op_sel_hi:[1,0]
	v_pk_mul_f32 v[12:13], v[12:13], v[160:161] op_sel_hi:[1,0]
	v_pk_mul_f32 v[14:15], v[14:15], v[160:161] op_sel_hi:[1,0]
	v_pk_mul_f32 v[8:9], v[8:9], v[160:161] op_sel_hi:[1,0]
	v_pk_mul_f32 v[10:11], v[10:11], v[160:161] op_sel_hi:[1,0]
	v_pk_mul_f32 v[40:41], v[40:41], v[160:161] op_sel_hi:[1,0]
	v_pk_mul_f32 v[42:43], v[42:43], v[160:161] op_sel_hi:[1,0]
	v_pk_mul_f32 v[36:37], v[36:37], v[160:161] op_sel_hi:[1,0]
	v_pk_mul_f32 v[38:39], v[38:39], v[160:161] op_sel_hi:[1,0]
	v_pk_mul_f32 v[92:93], v[92:93], v[162:163] op_sel_hi:[1,0]
	v_pk_mul_f32 v[94:95], v[94:95], v[162:163] op_sel_hi:[1,0]
	v_pk_mul_f32 v[88:89], v[88:89], v[162:163] op_sel_hi:[1,0]
	v_pk_mul_f32 v[90:91], v[90:91], v[162:163] op_sel_hi:[1,0]
	v_pk_mul_f32 v[84:85], v[84:85], v[162:163] op_sel_hi:[1,0]
	v_pk_mul_f32 v[86:87], v[86:87], v[162:163] op_sel_hi:[1,0]
	v_pk_mul_f32 v[76:77], v[76:77], v[162:163] op_sel_hi:[1,0]
	v_pk_mul_f32 v[78:79], v[78:79], v[162:163] op_sel_hi:[1,0]
	v_pk_mul_f32 v[80:81], v[80:81], v[164:165] op_sel_hi:[1,0]
	v_pk_mul_f32 v[82:83], v[82:83], v[164:165] op_sel_hi:[1,0]
	v_pk_mul_f32 v[72:73], v[72:73], v[164:165] op_sel_hi:[1,0]
	v_pk_mul_f32 v[74:75], v[74:75], v[164:165] op_sel_hi:[1,0]
	v_pk_mul_f32 v[68:69], v[68:69], v[164:165] op_sel_hi:[1,0]
	v_pk_mul_f32 v[70:71], v[70:71], v[164:165] op_sel_hi:[1,0]
	v_pk_mul_f32 v[64:65], v[64:65], v[164:165] op_sel_hi:[1,0]
	v_pk_mul_f32 v[66:67], v[66:67], v[164:165] op_sel_hi:[1,0]
	v_pk_mul_f32 v[4:5], v[4:5], v[166:167] op_sel_hi:[1,0]
	v_pk_mul_f32 v[6:7], v[6:7], v[166:167] op_sel_hi:[1,0]
	v_pk_mul_f32 v[0:1], v[0:1], v[166:167] op_sel_hi:[1,0]
	v_pk_mul_f32 v[2:3], v[2:3], v[166:167] op_sel_hi:[1,0]
	v_pk_mul_f32 v[32:33], v[32:33], v[166:167] op_sel_hi:[1,0]
	v_pk_mul_f32 v[34:35], v[34:35], v[166:167] op_sel_hi:[1,0]
	v_pk_mul_f32 v[128:129], v[128:129], v[166:167] op_sel_hi:[1,0]
	v_pk_mul_f32 v[130:131], v[130:131], v[166:167] op_sel_hi:[1,0]
	v_cmp_eq_u32_e32 vcc, 0, v223
	s_and_saveexec_b64 s[30:31], vcc
	ds_write_b128 v229, v[48:51] offset:0
	ds_write_b128 v229, v[24:27] offset:16
	ds_write_b128 v229, v[52:55] offset:512
	ds_write_b128 v229, v[28:31] offset:528
	ds_write_b128 v229, v[12:15] offset:4096
	ds_write_b128 v229, v[8:11] offset:4112
	ds_write_b128 v229, v[40:43] offset:4608
	ds_write_b128 v229, v[36:39] offset:4624
	s_mov_b64 exec, s[30:31]
	v_cmp_eq_u32_e32 vcc, 15, v223
	s_and_saveexec_b64 s[30:31], vcc
	ds_write_b128 v229, v[60:63] offset:1024
	ds_write_b128 v229, v[16:19] offset:1040
	ds_write_b128 v229, v[44:47] offset:1536
	ds_write_b128 v229, v[20:23] offset:1552
	ds_write_b128 v229, v[4:7] offset:5120
	ds_write_b128 v229, v[0:3] offset:5136
	ds_write_b128 v229, v[32:35] offset:5632
	ds_write_b128 v229, v[128:131] offset:5648
	s_mov_b64 exec, s[30:31]
	s_waitcnt lgkmcnt(0)
	s_barrier
	s_cmp_eq_u32 s33, 64
	s_cbranch_scc1 .Lp5_edge
	s_cmp_lt_i32 s33, 64
	s_cselect_b32 s9, 11, 14
	s_lshl_b32 s11, 1, s9
	s_add_i32 s11, s11, s28
	s_add_i32 s11, s11, -2
	s_ashr_i32 s11, s11, s9
	s_add_i32 s29, s28, 0xff
	s_ashr_i32 s29, s29, s9
	s_cmp_lt_i32 s29, s11
	s_cbranch_scc0 .Lp5_edge
	s_waitcnt vmcnt(0)
	ds_read_b128 v[56:59], v231 offset:0
	ds_read_b128 v[132:135], v231 offset:512
	ds_read_b128 v[152:155], v233 offset:0
	ds_read_b128 v[156:159], v233 offset:512
	s_waitcnt lgkmcnt(0)
	v_mov_b32_dpp v56, v60 row_shr:1 row_mask:0xf bank_mask:0xf
	v_mov_b32_dpp v57, v61 row_shr:1 row_mask:0xf bank_mask:0xf
	v_mov_b32_dpp v58, v62 row_shr:1 row_mask:0xf bank_mask:0xf
	v_mov_b32_dpp v59, v63 row_shr:1 row_mask:0xf bank_mask:0xf
	v_mov_b32_dpp v132, v44 row_shr:1 row_mask:0xf bank_mask:0xf
	v_mov_b32_dpp v133, v45 row_shr:1 row_mask:0xf bank_mask:0xf
	v_mov_b32_dpp v134, v46 row_shr:1 row_mask:0xf bank_mask:0xf
	v_mov_b32_dpp v135, v47 row_shr:1 row_mask:0xf bank_mask:0xf
	v_mov_b32_dpp v152, v48 row_shl:1 row_mask:0xf bank_mask:0xf
	v_mov_b32_dpp v153, v49 row_shl:1 row_mask:0xf bank_mask:0xf
	v_mov_b32_dpp v154, v50 row_shl:1 row_mask:0xf bank_mask:0xf
	v_mov_b32_dpp v155, v51 row_shl:1 row_mask:0xf bank_mask:0xf
	v_mov_b32_dpp v156, v52 row_shl:1 row_mask:0xf bank_mask:0xf
	v_mov_b32_dpp v157, v53 row_shl:1 row_mask:0xf bank_mask:0xf
	v_mov_b32_dpp v158, v54 row_shl:1 row_mask:0xf bank_mask:0xf
	v_mov_b32_dpp v159, v55 row_shl:1 row_mask:0xf bank_mask:0xf
	v_pk_fma_f32 v[56:57], v[176:177], v[56:57], v[200:201]
	v_pk_fma_f32 v[58:59], v[178:179], v[58:59], v[202:203]
	v_pk_fma_f32 v[132:133], v[180:181], v[132:133], v[204:205]
	v_pk_fma_f32 v[134:135], v[182:183], v[134:135], v[206:207]
	v_pk_fma_f32 v[56:57], v[48:49], v[184:185], v[56:57]
	v_pk_fma_f32 v[58:59], v[50:51], v[186:187], v[58:59]
	v_pk_fma_f32 v[132:133], v[52:53], v[188:189], v[132:133]
	v_pk_fma_f32 v[134:135], v[54:55], v[190:191], v[134:135]
	v_pk_fma_f32 v[56:57], v[192:193], v[124:125], v[56:57]
	v_pk_fma_f32 v[58:59], v[194:195], v[126:127], v[58:59]
	v_pk_fma_f32 v[132:133], v[196:197], v[116:117], v[132:133]
	v_pk_fma_f32 v[134:135], v[198:199], v[118:119], v[134:135]
	v_and_b32_e32 v212, 0x7fffffff, v56
	v_and_b32_e32 v213, 0x7fffffff, v57
	v_and_b32_e32 v166, 0x7fffffff, v58
	v_and_b32_e32 v167, 0x7fffffff, v59
	v_pk_fma_f32 v[238:239], v[212:213], s[90:91], 1.0 op_sel_hi:[1,0,0]
	v_pk_fma_f32 v[168:169], v[166:167], s[90:91], 1.0 op_sel_hi:[1,0,0]
	v_pk_mul_f32 v[164:165], v[56:57], v[56:57]
	v_pk_mul_f32 v[172:173], v[58:59], v[58:59]
	v_rcp_f32_e32 v238, v238
	v_rcp_f32_e32 v239, v239
	v_rcp_f32_e32 v168, v168
	v_rcp_f32_e32 v169, v169
	v_pk_mul_f32 v[164:165], v[164:165], s[44:45] op_sel_hi:[1,0]
	v_pk_mul_f32 v[172:173], v[172:173], s[44:45] op_sel_hi:[1,0]
	v_pk_fma_f32 v[246:247], v[238:239], s[92:93], v[236:237] op_sel_hi:[1,0,0]
	v_pk_fma_f32 v[170:171], v[168:169], s[92:93], v[236:237] op_sel_hi:[1,0,0]
	v_exp_f32_e32 v164, v164
	v_exp_f32_e32 v165, v165
	v_exp_f32_e32 v172, v172
	v_exp_f32_e32 v173, v173
	v_pk_fma_f32 v[246:247], v[238:239], v[246:247], s[96:97] op_sel_hi:[1,1,0]
	v_pk_fma_f32 v[170:171], v[168:169], v[170:171], s[96:97] op_sel_hi:[1,1,0]
	v_pk_fma_f32 v[246:247], v[238:239], v[246:247], s[0:1] op_sel_hi:[1,1,0]
	v_pk_fma_f32 v[170:171], v[168:169], v[170:171], s[0:1] op_sel_hi:[1,1,0]
	v_pk_fma_f32 v[246:247], v[238:239], v[246:247], s[4:5] op_sel_hi:[1,1,0]
	v_pk_fma_f32 v[170:171], v[168:169], v[170:171], s[4:5] op_sel_hi:[1,1,0]
	v_pk_mul_f32 v[246:247], v[238:239], v[246:247]
	v_pk_mul_f32 v[170:171], v[168:169], v[170:171]
	v_max_f32_e32 v238, 0, v56
	v_max_f32_e32 v239, 0, v57
	v_max_f32_e32 v168, 0, v58
	v_max_f32_e32 v169, 0, v59
	v_pk_mul_f32 v[246:247], v[164:165], v[246:247]
	v_pk_mul_f32 v[170:171], v[172:173], v[170:171]
	v_pk_fma_f32 v[164:165], v[212:213], v[246:247], v[238:239] neg_lo:[1,0,0] neg_hi:[1,0,0]
	v_pk_fma_f32 v[172:173], v[166:167], v[170:171], v[168:169] neg_lo:[1,0,0] neg_hi:[1,0,0]
	v_pk_mul_f32 v[246:247], v[164:165], v[132:133]
	v_pk_mul_f32 v[170:171], v[172:173], v[134:135]
	v_cvt_pk_bf16_f32 v160, v246, v247
	v_cvt_pk_bf16_f32 v161, v170, v171
	v_pk_fma_f32 v[48:49], v[176:177], v[48:49], v[200:201]
	v_pk_fma_f32 v[50:51], v[178:179], v[50:51], v[202:203]
	v_pk_fma_f32 v[52:53], v[180:181], v[52:53], v[204:205]
	v_pk_fma_f32 v[54:55], v[182:183], v[54:55], v[206:207]
	v_pk_fma_f32 v[48:49], v[124:125], v[184:185], v[48:49]
	v_pk_fma_f32 v[50:51], v[126:127], v[186:187], v[50:51]
	v_pk_fma_f32 v[52:53], v[116:117], v[188:189], v[52:53]
	v_pk_fma_f32 v[54:55], v[118:119], v[190:191], v[54:55]
	v_pk_fma_f32 v[48:49], v[192:193], v[112:113], v[48:49]
	v_pk_fma_f32 v[50:51], v[194:195], v[114:115], v[50:51]
	v_pk_fma_f32 v[52:53], v[196:197], v[100:101], v[52:53]
	v_pk_fma_f32 v[54:55], v[198:199], v[102:103], v[54:55]
	v_and_b32_e32 v212, 0x7fffffff, v48
	v_and_b32_e32 v213, 0x7fffffff, v49
	v_and_b32_e32 v134, 0x7fffffff, v50
	v_and_b32_e32 v135, 0x7fffffff, v51
	v_pk_fma_f32 v[238:239], v[212:213], s[90:91], 1.0 op_sel_hi:[1,0,0]
	v_pk_fma_f32 v[164:165], v[134:135], s[90:91], 1.0 op_sel_hi:[1,0,0]
	v_pk_mul_f32 v[132:133], v[48:49], v[48:49]
	v_pk_mul_f32 v[168:169], v[50:51], v[50:51]
	v_rcp_f32_e32 v238, v238
	v_rcp_f32_e32 v239, v239
	v_rcp_f32_e32 v164, v164
	v_rcp_f32_e32 v165, v165
	v_pk_mul_f32 v[132:133], v[132:133], s[44:45] op_sel_hi:[1,0]
	v_pk_mul_f32 v[168:169], v[168:169], s[44:45] op_sel_hi:[1,0]
	v_pk_fma_f32 v[246:247], v[238:239], s[92:93], v[236:237] op_sel_hi:[1,0,0]
	v_pk_fma_f32 v[166:167], v[164:165], s[92:93], v[236:237] op_sel_hi:[1,0,0]
	v_exp_f32_e32 v132, v132
	v_exp_f32_e32 v133, v133
	v_exp_f32_e32 v168, v168
	v_exp_f32_e32 v169, v169
	v_pk_fma_f32 v[246:247], v[238:239], v[246:247], s[96:97] op_sel_hi:[1,1,0]
	v_pk_fma_f32 v[166:167], v[164:165], v[166:167], s[96:97] op_sel_hi:[1,1,0]
	v_pk_fma_f32 v[246:247], v[238:239], v[246:247], s[0:1] op_sel_hi:[1,1,0]
	v_pk_fma_f32 v[166:167], v[164:165], v[166:167], s[0:1] op_sel_hi:[1,1,0]
	v_pk_fma_f32 v[246:247], v[238:239], v[246:247], s[4:5] op_sel_hi:[1,1,0]
	v_pk_fma_f32 v[166:167], v[164:165], v[166:167], s[4:5] op_sel_hi:[1,1,0]
	v_pk_mul_f32 v[246:247], v[238:239], v[246:247]
	v_pk_mul_f32 v[166:167], v[164:165], v[166:167]
	v_max_f32_e32 v238, 0, v48
	v_max_f32_e32 v239, 0, v49
	v_max_f32_e32 v164, 0, v50
	v_max_f32_e32 v165, 0, v51
	v_pk_mul_f32 v[246:247], v[132:133], v[246:247]
	v_pk_mul_f32 v[166:167], v[168:169], v[166:167]
	v_pk_fma_f32 v[132:133], v[212:213], v[246:247], v[238:239] neg_lo:[1,0,0] neg_hi:[1,0,0]
	v_pk_fma_f32 v[168:169], v[134:135], v[166:167], v[164:165] neg_lo:[1,0,0] neg_hi:[1,0,0]
	v_pk_mul_f32 v[246:247], v[132:133], v[52:53]
	v_pk_mul_f32 v[166:167], v[168:169], v[54:55]
	v_cvt_pk_bf16_f32 v56, v246, v247
	v_cvt_pk_bf16_f32 v57, v166, v167
	v_pk_fma_f32 v[124:125], v[176:177], v[124:125], v[200:201]
	v_pk_fma_f32 v[126:127], v[178:179], v[126:127], v[202:203]
	v_pk_fma_f32 v[116:117], v[180:181], v[116:117], v[204:205]
	v_pk_fma_f32 v[118:119], v[182:183], v[118:119], v[206:207]
	v_pk_fma_f32 v[124:125], v[112:113], v[184:185], v[124:125]
	v_pk_fma_f32 v[126:127], v[114:115], v[186:187], v[126:127]
	v_pk_fma_f32 v[116:117], v[100:101], v[188:189], v[116:117]
	v_pk_fma_f32 v[118:119], v[102:103], v[190:191], v[118:119]
	v_pk_fma_f32 v[124:125], v[192:193], v[60:61], v[124:125]
	v_pk_fma_f32 v[126:127], v[194:195], v[62:63], v[126:127]
	v_pk_fma_f32 v[116:117], v[196:197], v[44:45], v[116:117]
	v_pk_fma_f32 v[118:119], v[198:199], v[46:47], v[118:119]
	v_and_b32_e32 v212, 0x7fffffff, v124
	v_and_b32_e32 v213, 0x7fffffff, v125
	v_and_b32_e32 v54, 0x7fffffff, v126
	v_and_b32_e32 v55, 0x7fffffff, v127
	v_pk_fma_f32 v[238:239], v[212:213], s[90:91], 1.0 op_sel_hi:[1,0,0]
	v_pk_fma_f32 v[132:133], v[54:55], s[90:91], 1.0 op_sel_hi:[1,0,0]
	v_pk_mul_f32 v[52:53], v[124:125], v[124:125]
	v_pk_mul_f32 v[164:165], v[126:127], v[126:127]
	v_rcp_f32_e32 v238, v238
	v_rcp_f32_e32 v239, v239
	v_rcp_f32_e32 v132, v132
	v_rcp_f32_e32 v133, v133
	v_pk_mul_f32 v[52:53], v[52:53], s[44:45] op_sel_hi:[1,0]
	v_pk_mul_f32 v[164:165], v[164:165], s[44:45] op_sel_hi:[1,0]
	v_pk_fma_f32 v[246:247], v[238:239], s[92:93], v[236:237] op_sel_hi:[1,0,0]
	v_pk_fma_f32 v[134:135], v[132:133], s[92:93], v[236:237] op_sel_hi:[1,0,0]
	v_exp_f32_e32 v52, v52
	v_exp_f32_e32 v53, v53
	v_exp_f32_e32 v164, v164
	v_exp_f32_e32 v165, v165
	v_pk_fma_f32 v[246:247], v[238:239], v[246:247], s[96:97] op_sel_hi:[1,1,0]
	v_pk_fma_f32 v[134:135], v[132:133], v[134:135], s[96:97] op_sel_hi:[1,1,0]
	v_pk_fma_f32 v[246:247], v[238:239], v[246:247], s[0:1] op_sel_hi:[1,1,0]
	v_pk_fma_f32 v[134:135], v[132:133], v[134:135], s[0:1] op_sel_hi:[1,1,0]
	v_pk_fma_f32 v[246:247], v[238:239], v[246:247], s[4:5] op_sel_hi:[1,1,0]
	v_pk_fma_f32 v[134:135], v[132:133], v[134:135], s[4:5] op_sel_hi:[1,1,0]
	v_pk_mul_f32 v[246:247], v[238:239], v[246:247]
	v_pk_mul_f32 v[134:135], v[132:133], v[134:135]
	v_max_f32_e32 v238, 0, v124
	v_max_f32_e32 v239, 0, v125
	v_max_f32_e32 v132, 0, v126
	v_max_f32_e32 v133, 0, v127
	v_pk_mul_f32 v[246:247], v[52:53], v[246:247]
	v_pk_mul_f32 v[134:135], v[164:165], v[134:135]
	v_pk_fma_f32 v[52:53], v[212:213], v[246:247], v[238:239] neg_lo:[1,0,0] neg_hi:[1,0,0]
	v_pk_fma_f32 v[164:165], v[54:55], v[134:135], v[132:133] neg_lo:[1,0,0] neg_hi:[1,0,0]
	v_pk_mul_f32 v[246:247], v[52:53], v[116:117]
	v_pk_mul_f32 v[134:135], v[164:165], v[118:119]
	v_cvt_pk_bf16_f32 v48, v246, v247
	v_cvt_pk_bf16_f32 v49, v134, v135
	v_pk_fma_f32 v[112:113], v[176:177], v[112:113], v[200:201]
	v_pk_fma_f32 v[114:115], v[178:179], v[114:115], v[202:203]
	v_pk_fma_f32 v[100:101], v[180:181], v[100:101], v[204:205]
	v_pk_fma_f32 v[102:103], v[182:183], v[102:103], v[206:207]
	v_pk_fma_f32 v[112:113], v[60:61], v[184:185], v[112:113]
	v_pk_fma_f32 v[114:115], v[62:63], v[186:187], v[114:115]
	v_pk_fma_f32 v[100:101], v[44:45], v[188:189], v[100:101]
	v_pk_fma_f32 v[102:103], v[46:47], v[190:191], v[102:103]
	v_pk_fma_f32 v[112:113], v[192:193], v[152:153], v[112:113]
	v_pk_fma_f32 v[114:115], v[194:195], v[154:155], v[114:115]
	v_pk_fma_f32 v[100:101], v[196:197], v[156:157], v[100:101]
	v_pk_fma_f32 v[102:103], v[198:199], v[158:159], v[102:103]
	v_and_b32_e32 v212, 0x7fffffff, v112
	v_and_b32_e32 v213, 0x7fffffff, v113
	v_and_b32_e32 v118, 0x7fffffff, v114
	v_and_b32_e32 v119, 0x7fffffff, v115
	v_pk_fma_f32 v[238:239], v[212:213], s[90:91], 1.0 op_sel_hi:[1,0,0]
	v_pk_fma_f32 v[124:125], v[118:119], s[90:91], 1.0 op_sel_hi:[1,0,0]
	v_pk_mul_f32 v[116:117], v[112:113], v[112:113]
	v_pk_mul_f32 v[132:133], v[114:115], v[114:115]
	v_rcp_f32_e32 v238, v238
	v_rcp_f32_e32 v239, v239
	v_rcp_f32_e32 v124, v124
	v_rcp_f32_e32 v125, v125
	v_pk_mul_f32 v[116:117], v[116:117], s[44:45] op_sel_hi:[1,0]
	v_pk_mul_f32 v[132:133], v[132:133], s[44:45] op_sel_hi:[1,0]
	v_pk_fma_f32 v[246:247], v[238:239], s[92:93], v[236:237] op_sel_hi:[1,0,0]
	v_pk_fma_f32 v[126:127], v[124:125], s[92:93], v[236:237] op_sel_hi:[1,0,0]
	v_exp_f32_e32 v116, v116
	v_exp_f32_e32 v117, v117
	v_exp_f32_e32 v132, v132
	v_exp_f32_e32 v133, v133
	v_pk_fma_f32 v[246:247], v[238:239], v[246:247], s[96:97] op_sel_hi:[1,1,0]
	v_pk_fma_f32 v[126:127], v[124:125], v[126:127], s[96:97] op_sel_hi:[1,1,0]
	v_pk_fma_f32 v[246:247], v[238:239], v[246:247], s[0:1] op_sel_hi:[1,1,0]
	v_pk_fma_f32 v[126:127], v[124:125], v[126:127], s[0:1] op_sel_hi:[1,1,0]
	v_pk_fma_f32 v[246:247], v[238:239], v[246:247], s[4:5] op_sel_hi:[1,1,0]
	v_pk_fma_f32 v[126:127], v[124:125], v[126:127], s[4:5] op_sel_hi:[1,1,0]
	v_pk_mul_f32 v[246:247], v[238:239], v[246:247]
	v_pk_mul_f32 v[126:127], v[124:125], v[126:127]
	v_max_f32_e32 v238, 0, v112
	v_max_f32_e32 v239, 0, v113
	v_max_f32_e32 v124, 0, v114
	v_max_f32_e32 v125, 0, v115
	v_pk_mul_f32 v[246:247], v[116:117], v[246:247]
	v_pk_mul_f32 v[126:127], v[132:133], v[126:127]
	v_pk_fma_f32 v[116:117], v[212:213], v[246:247], v[238:239] neg_lo:[1,0,0] neg_hi:[1,0,0]
	v_pk_fma_f32 v[132:133], v[118:119], v[126:127], v[124:125] neg_lo:[1,0,0] neg_hi:[1,0,0]
	v_pk_mul_f32 v[246:247], v[116:117], v[100:101]
	v_pk_mul_f32 v[126:127], v[132:133], v[102:103]
	v_cvt_pk_bf16_f32 v52, v246, v247
	v_cvt_pk_bf16_f32 v53, v126, v127
	ds_read_b128 v[44:47], v232 offset:0
	ds_read_b128 v[60:63], v232 offset:512
	ds_read_b128 v[100:103], v234 offset:0
	ds_read_b128 v[112:115], v234 offset:512
	s_waitcnt lgkmcnt(0)
	v_mov_b32_dpp v44, v4 row_shr:1 row_mask:0xf bank_mask:0xf
	v_mov_b32_dpp v45, v5 row_shr:1 row_mask:0xf bank_mask:0xf
	v_mov_b32_dpp v46, v6 row_shr:1 row_mask:0xf bank_mask:0xf
	v_mov_b32_dpp v47, v7 row_shr:1 row_mask:0xf bank_mask:0xf
	v_mov_b32_dpp v60, v32 row_shr:1 row_mask:0xf bank_mask:0xf
	v_mov_b32_dpp v61, v33 row_shr:1 row_mask:0xf bank_mask:0xf
	v_mov_b32_dpp v62, v34 row_shr:1 row_mask:0xf bank_mask:0xf
	v_mov_b32_dpp v63, v35 row_shr:1 row_mask:0xf bank_mask:0xf
	v_mov_b32_dpp v100, v12 row_shl:1 row_mask:0xf bank_mask:0xf
	v_mov_b32_dpp v101, v13 row_shl:1 row_mask:0xf bank_mask:0xf
	v_mov_b32_dpp v102, v14 row_shl:1 row_mask:0xf bank_mask:0xf
	v_mov_b32_dpp v103, v15 row_shl:1 row_mask:0xf bank_mask:0xf
	v_mov_b32_dpp v112, v40 row_shl:1 row_mask:0xf bank_mask:0xf
	v_mov_b32_dpp v113, v41 row_shl:1 row_mask:0xf bank_mask:0xf
	v_mov_b32_dpp v114, v42 row_shl:1 row_mask:0xf bank_mask:0xf
	v_mov_b32_dpp v115, v43 row_shl:1 row_mask:0xf bank_mask:0xf
	v_pk_fma_f32 v[44:45], v[176:177], v[44:45], v[200:201]
	v_pk_fma_f32 v[46:47], v[178:179], v[46:47], v[202:203]
	v_pk_fma_f32 v[60:61], v[180:181], v[60:61], v[204:205]
	v_pk_fma_f32 v[62:63], v[182:183], v[62:63], v[206:207]
	v_pk_fma_f32 v[44:45], v[12:13], v[184:185], v[44:45]
	v_pk_fma_f32 v[46:47], v[14:15], v[186:187], v[46:47]
	v_pk_fma_f32 v[60:61], v[40:41], v[188:189], v[60:61]
	v_pk_fma_f32 v[62:63], v[42:43], v[190:191], v[62:63]
	v_pk_fma_f32 v[44:45], v[192:193], v[92:93], v[44:45]
	v_pk_fma_f32 v[46:47], v[194:195], v[94:95], v[46:47]
	v_pk_fma_f32 v[60:61], v[196:197], v[84:85], v[60:61]
	v_pk_fma_f32 v[62:63], v[198:199], v[86:87], v[62:63]
	v_and_b32_e32 v212, 0x7fffffff, v44
	v_and_b32_e32 v213, 0x7fffffff, v45
	v_and_b32_e32 v126, 0x7fffffff, v46
	v_and_b32_e32 v127, 0x7fffffff, v47
	v_pk_fma_f32 v[238:239], v[212:213], s[90:91], 1.0 op_sel_hi:[1,0,0]
	v_pk_fma_f32 v[132:133], v[126:127], s[90:91], 1.0 op_sel_hi:[1,0,0]
	v_pk_mul_f32 v[124:125], v[44:45], v[44:45]
	v_pk_mul_f32 v[152:153], v[46:47], v[46:47]
	v_rcp_f32_e32 v238, v238
	v_rcp_f32_e32 v239, v239
	v_rcp_f32_e32 v132, v132
	v_rcp_f32_e32 v133, v133
	v_pk_mul_f32 v[124:125], v[124:125], s[44:45] op_sel_hi:[1,0]
	v_pk_mul_f32 v[152:153], v[152:153], s[44:45] op_sel_hi:[1,0]
	v_pk_fma_f32 v[246:247], v[238:239], s[92:93], v[236:237] op_sel_hi:[1,0,0]
	v_pk_fma_f32 v[134:135], v[132:133], s[92:93], v[236:237] op_sel_hi:[1,0,0]
	v_exp_f32_e32 v124, v124
	v_exp_f32_e32 v125, v125
	v_exp_f32_e32 v152, v152
	v_exp_f32_e32 v153, v153
	v_pk_fma_f32 v[246:247], v[238:239], v[246:247], s[96:97] op_sel_hi:[1,1,0]
	v_pk_fma_f32 v[134:135], v[132:133], v[134:135], s[96:97] op_sel_hi:[1,1,0]
	v_pk_fma_f32 v[246:247], v[238:239], v[246:247], s[0:1] op_sel_hi:[1,1,0]
	v_pk_fma_f32 v[134:135], v[132:133], v[134:135], s[0:1] op_sel_hi:[1,1,0]
	v_pk_fma_f32 v[246:247], v[238:239], v[246:247], s[4:5] op_sel_hi:[1,1,0]
	v_pk_fma_f32 v[134:135], v[132:133], v[134:135], s[4:5] op_sel_hi:[1,1,0]
	v_pk_mul_f32 v[246:247], v[238:239], v[246:247]
	v_pk_mul_f32 v[134:135], v[132:133], v[134:135]
	v_max_f32_e32 v238, 0, v44
	v_max_f32_e32 v239, 0, v45
	v_max_f32_e32 v132, 0, v46
	v_max_f32_e32 v133, 0, v47
	v_pk_mul_f32 v[246:247], v[124:125], v[246:247]
	v_pk_mul_f32 v[134:135], v[152:153], v[134:135]
	v_pk_fma_f32 v[124:125], v[212:213], v[246:247], v[238:239] neg_lo:[1,0,0] neg_hi:[1,0,0]
	v_pk_fma_f32 v[152:153], v[126:127], v[134:135], v[132:133] neg_lo:[1,0,0] neg_hi:[1,0,0]
	v_pk_mul_f32 v[246:247], v[124:125], v[60:61]
	v_pk_mul_f32 v[134:135], v[152:153], v[62:63]
	v_cvt_pk_bf16_f32 v116, v246, v247
	v_cvt_pk_bf16_f32 v117, v134, v135
	global_load_dwordx4 v[44:47], v226, s[12:13] offset:16
	global_load_dwordx4 v[60:63], v226, s[14:15] offset:16
	global_load_dwordx4 v[124:127], v226, s[16:17] offset:16
	global_load_dwordx4 v[132:135], v226, s[18:19] offset:16
	global_load_dwordx4 v[152:155], v226, s[20:21] offset:16
	global_load_dwordx4 v[156:159], v226, s[22:23] offset:16
	global_load_dwordx4 v[164:167], v226, s[24:25] offset:16
	global_load_dwordx4 v[168:171], v226, s[26:27] offset:16
	v_pk_fma_f32 v[12:13], v[176:177], v[12:13], v[200:201]
	v_pk_fma_f32 v[14:15], v[178:179], v[14:15], v[202:203]
	v_pk_fma_f32 v[40:41], v[180:181], v[40:41], v[204:205]
	v_pk_fma_f32 v[42:43], v[182:183], v[42:43], v[206:207]
	v_pk_fma_f32 v[12:13], v[92:93], v[184:185], v[12:13]
	v_pk_fma_f32 v[14:15], v[94:95], v[186:187], v[14:15]
	v_pk_fma_f32 v[40:41], v[84:85], v[188:189], v[40:41]
	v_pk_fma_f32 v[42:43], v[86:87], v[190:191], v[42:43]
	v_pk_fma_f32 v[12:13], v[192:193], v[80:81], v[12:13]
	v_pk_fma_f32 v[14:15], v[194:195], v[82:83], v[14:15]
	v_pk_fma_f32 v[40:41], v[196:197], v[68:69], v[40:41]
	v_pk_fma_f32 v[42:43], v[198:199], v[70:71], v[42:43]
	v_and_b32_e32 v212, 0x7fffffff, v12
	v_and_b32_e32 v213, 0x7fffffff, v13
	v_and_b32_e32 v210, 0x7fffffff, v14
	v_and_b32_e32 v211, 0x7fffffff, v15
	v_pk_fma_f32 v[238:239], v[212:213], s[90:91], 1.0 op_sel_hi:[1,0,0]
	v_pk_fma_f32 v[240:241], v[210:211], s[90:91], 1.0 op_sel_hi:[1,0,0]
	v_pk_mul_f32 v[208:209], v[12:13], v[12:13]
	v_pk_mul_f32 v[248:249], v[14:15], v[14:15]
	v_rcp_f32_e32 v238, v238
	v_rcp_f32_e32 v239, v239
	v_rcp_f32_e32 v240, v240
	v_rcp_f32_e32 v241, v241
	v_pk_mul_f32 v[208:209], v[208:209], s[44:45] op_sel_hi:[1,0]
	v_pk_mul_f32 v[248:249], v[248:249], s[44:45] op_sel_hi:[1,0]
	v_pk_fma_f32 v[246:247], v[238:239], s[92:93], v[236:237] op_sel_hi:[1,0,0]
	v_pk_fma_f32 v[242:243], v[240:241], s[92:93], v[236:237] op_sel_hi:[1,0,0]
	v_exp_f32_e32 v208, v208
	v_exp_f32_e32 v209, v209
	v_exp_f32_e32 v248, v248
	v_exp_f32_e32 v249, v249
	v_pk_fma_f32 v[246:247], v[238:239], v[246:247], s[96:97] op_sel_hi:[1,1,0]
	v_pk_fma_f32 v[242:243], v[240:241], v[242:243], s[96:97] op_sel_hi:[1,1,0]
	v_pk_fma_f32 v[246:247], v[238:239], v[246:247], s[0:1] op_sel_hi:[1,1,0]
	v_pk_fma_f32 v[242:243], v[240:241], v[242:243], s[0:1] op_sel_hi:[1,1,0]
	v_pk_fma_f32 v[246:247], v[238:239], v[246:247], s[4:5] op_sel_hi:[1,1,0]
	v_pk_fma_f32 v[242:243], v[240:241], v[242:243], s[4:5] op_sel_hi:[1,1,0]
	v_pk_mul_f32 v[246:247], v[238:239], v[246:247]
	v_pk_mul_f32 v[242:243], v[240:241], v[242:243]
	v_max_f32_e32 v238, 0, v12
	v_max_f32_e32 v239, 0, v13
	v_max_f32_e32 v240, 0, v14
	v_max_f32_e32 v241, 0, v15
	v_pk_mul_f32 v[246:247], v[208:209], v[246:247]
	v_pk_mul_f32 v[242:243], v[248:249], v[242:243]
	v_pk_fma_f32 v[208:209], v[212:213], v[246:247], v[238:239] neg_lo:[1,0,0] neg_hi:[1,0,0]
	v_pk_fma_f32 v[248:249], v[210:211], v[242:243], v[240:241] neg_lo:[1,0,0] neg_hi:[1,0,0]
	v_pk_mul_f32 v[246:247], v[208:209], v[40:41]
	v_pk_mul_f32 v[242:243], v[248:249], v[42:43]
	v_cvt_pk_bf16_f32 v172, v246, v247
	v_cvt_pk_bf16_f32 v173, v242, v243
	v_pk_fma_f32 v[92:93], v[176:177], v[92:93], v[200:201]
	v_pk_fma_f32 v[94:95], v[178:179], v[94:95], v[202:203]
	v_pk_fma_f32 v[84:85], v[180:181], v[84:85], v[204:205]
	v_pk_fma_f32 v[86:87], v[182:183], v[86:87], v[206:207]
	v_pk_fma_f32 v[92:93], v[80:81], v[184:185], v[92:93]
	v_pk_fma_f32 v[94:95], v[82:83], v[186:187], v[94:95]
	v_pk_fma_f32 v[84:85], v[68:69], v[188:189], v[84:85]
	v_pk_fma_f32 v[86:87], v[70:71], v[190:191], v[86:87]
	v_pk_fma_f32 v[92:93], v[192:193], v[4:5], v[92:93]
	v_pk_fma_f32 v[94:95], v[194:195], v[6:7], v[94:95]
	v_pk_fma_f32 v[84:85], v[196:197], v[32:33], v[84:85]
	v_pk_fma_f32 v[86:87], v[198:199], v[34:35], v[86:87]
	v_and_b32_e32 v212, 0x7fffffff, v92
	v_and_b32_e32 v213, 0x7fffffff, v93
	v_and_b32_e32 v42, 0x7fffffff, v94
	v_and_b32_e32 v43, 0x7fffffff, v95
	v_pk_fma_f32 v[238:239], v[212:213], s[90:91], 1.0 op_sel_hi:[1,0,0]
	v_pk_fma_f32 v[208:209], v[42:43], s[90:91], 1.0 op_sel_hi:[1,0,0]
	v_pk_mul_f32 v[40:41], v[92:93], v[92:93]
	v_pk_mul_f32 v[240:241], v[94:95], v[94:95]
	v_rcp_f32_e32 v238, v238
	v_rcp_f32_e32 v239, v239
	v_rcp_f32_e32 v208, v208
	v_rcp_f32_e32 v209, v209
	v_pk_mul_f32 v[40:41], v[40:41], s[44:45] op_sel_hi:[1,0]
	v_pk_mul_f32 v[240:241], v[240:241], s[44:45] op_sel_hi:[1,0]
	v_pk_fma_f32 v[246:247], v[238:239], s[92:93], v[236:237] op_sel_hi:[1,0,0]
	v_pk_fma_f32 v[210:211], v[208:209], s[92:93], v[236:237] op_sel_hi:[1,0,0]
	v_exp_f32_e32 v40, v40
	v_exp_f32_e32 v41, v41
	v_exp_f32_e32 v240, v240
	v_exp_f32_e32 v241, v241
	v_pk_fma_f32 v[246:247], v[238:239], v[246:247], s[96:97] op_sel_hi:[1,1,0]
	v_pk_fma_f32 v[210:211], v[208:209], v[210:211], s[96:97] op_sel_hi:[1,1,0]
	v_pk_fma_f32 v[246:247], v[238:239], v[246:247], s[0:1] op_sel_hi:[1,1,0]
	v_pk_fma_f32 v[210:211], v[208:209], v[210:211], s[0:1] op_sel_hi:[1,1,0]
	v_pk_fma_f32 v[246:247], v[238:239], v[246:247], s[4:5] op_sel_hi:[1,1,0]
	v_pk_fma_f32 v[210:211], v[208:209], v[210:211], s[4:5] op_sel_hi:[1,1,0]
	v_pk_mul_f32 v[246:247], v[238:239], v[246:247]
	v_pk_mul_f32 v[210:211], v[208:209], v[210:211]
	v_max_f32_e32 v238, 0, v92
	v_max_f32_e32 v239, 0, v93
	v_max_f32_e32 v208, 0, v94
	v_max_f32_e32 v209, 0, v95
	v_pk_mul_f32 v[246:247], v[40:41], v[246:247]
	v_pk_mul_f32 v[210:211], v[240:241], v[210:211]
	v_pk_fma_f32 v[40:41], v[212:213], v[246:247], v[238:239] neg_lo:[1,0,0] neg_hi:[1,0,0]
	v_pk_fma_f32 v[240:241], v[42:43], v[210:211], v[208:209] neg_lo:[1,0,0] neg_hi:[1,0,0]
	v_pk_mul_f32 v[246:247], v[40:41], v[84:85]
	v_pk_mul_f32 v[210:211], v[240:241], v[86:87]
	v_cvt_pk_bf16_f32 v12, v246, v247
	v_cvt_pk_bf16_f32 v13, v210, v211
	v_pk_fma_f32 v[80:81], v[176:177], v[80:81], v[200:201]
	v_pk_fma_f32 v[82:83], v[178:179], v[82:83], v[202:203]
	v_pk_fma_f32 v[68:69], v[180:181], v[68:69], v[204:205]
	v_pk_fma_f32 v[70:71], v[182:183], v[70:71], v[206:207]
	v_pk_fma_f32 v[80:81], v[4:5], v[184:185], v[80:81]
	v_pk_fma_f32 v[82:83], v[6:7], v[186:187], v[82:83]
	v_pk_fma_f32 v[68:69], v[32:33], v[188:189], v[68:69]
	v_pk_fma_f32 v[70:71], v[34:35], v[190:191], v[70:71]
	v_pk_fma_f32 v[80:81], v[192:193], v[100:101], v[80:81]
	v_pk_fma_f32 v[82:83], v[194:195], v[102:103], v[82:83]
	v_pk_fma_f32 v[68:69], v[196:197], v[112:113], v[68:69]
	v_pk_fma_f32 v[70:71], v[198:199], v[114:115], v[70:71]
	v_and_b32_e32 v212, 0x7fffffff, v80
	v_and_b32_e32 v213, 0x7fffffff, v81
	v_and_b32_e32 v86, 0x7fffffff, v82
	v_and_b32_e32 v87, 0x7fffffff, v83
	v_pk_fma_f32 v[238:239], v[212:213], s[90:91], 1.0 op_sel_hi:[1,0,0]
	v_pk_fma_f32 v[92:93], v[86:87], s[90:91], 1.0 op_sel_hi:[1,0,0]
	v_pk_mul_f32 v[84:85], v[80:81], v[80:81]
	v_pk_mul_f32 v[208:209], v[82:83], v[82:83]
	v_rcp_f32_e32 v238, v238
	v_rcp_f32_e32 v239, v239
	v_rcp_f32_e32 v92, v92
	v_rcp_f32_e32 v93, v93
	v_pk_mul_f32 v[84:85], v[84:85], s[44:45] op_sel_hi:[1,0]
	v_pk_mul_f32 v[208:209], v[208:209], s[44:45] op_sel_hi:[1,0]
	v_pk_fma_f32 v[246:247], v[238:239], s[92:93], v[236:237] op_sel_hi:[1,0,0]
	v_pk_fma_f32 v[94:95], v[92:93], s[92:93], v[236:237] op_sel_hi:[1,0,0]
	v_exp_f32_e32 v84, v84
	v_exp_f32_e32 v85, v85
	v_exp_f32_e32 v208, v208
	v_exp_f32_e32 v209, v209
	v_pk_fma_f32 v[246:247], v[238:239], v[246:247], s[96:97] op_sel_hi:[1,1,0]
	v_pk_fma_f32 v[94:95], v[92:93], v[94:95], s[96:97] op_sel_hi:[1,1,0]
	v_pk_fma_f32 v[246:247], v[238:239], v[246:247], s[0:1] op_sel_hi:[1,1,0]
	v_pk_fma_f32 v[94:95], v[92:93], v[94:95], s[0:1] op_sel_hi:[1,1,0]
	v_pk_fma_f32 v[246:247], v[238:239], v[246:247], s[4:5] op_sel_hi:[1,1,0]
	v_pk_fma_f32 v[94:95], v[92:93], v[94:95], s[4:5] op_sel_hi:[1,1,0]
	v_pk_mul_f32 v[246:247], v[238:239], v[246:247]
	v_pk_mul_f32 v[94:95], v[92:93], v[94:95]
	v_max_f32_e32 v238, 0, v80
	v_max_f32_e32 v239, 0, v81
	v_max_f32_e32 v92, 0, v82
	v_max_f32_e32 v93, 0, v83
	v_pk_mul_f32 v[246:247], v[84:85], v[246:247]
	v_pk_mul_f32 v[94:95], v[208:209], v[94:95]
	v_pk_fma_f32 v[84:85], v[212:213], v[246:247], v[238:239] neg_lo:[1,0,0] neg_hi:[1,0,0]
	v_pk_fma_f32 v[208:209], v[86:87], v[94:95], v[92:93] neg_lo:[1,0,0] neg_hi:[1,0,0]
	v_pk_mul_f32 v[246:247], v[84:85], v[68:69]
	v_pk_mul_f32 v[94:95], v[208:209], v[70:71]
	v_cvt_pk_bf16_f32 v40, v246, v247
	v_cvt_pk_bf16_f32 v41, v94, v95
	s_waitcnt vmcnt(0)
	ds_read_b128 v[4:7], v231 offset:16
	ds_read_b128 v[32:35], v231 offset:528
	ds_read_b128 v[68:71], v233 offset:16
	ds_read_b128 v[80:83], v233 offset:528
	s_waitcnt lgkmcnt(0)
	v_mov_b32_dpp v4, v16 row_shr:1 row_mask:0xf bank_mask:0xf
	v_mov_b32_dpp v5, v17 row_shr:1 row_mask:0xf bank_mask:0xf
	v_mov_b32_dpp v6, v18 row_shr:1 row_mask:0xf bank_mask:0xf
	v_mov_b32_dpp v7, v19 row_shr:1 row_mask:0xf bank_mask:0xf
	v_mov_b32_dpp v32, v20 row_shr:1 row_mask:0xf bank_mask:0xf
	v_mov_b32_dpp v33, v21 row_shr:1 row_mask:0xf bank_mask:0xf
	v_mov_b32_dpp v34, v22 row_shr:1 row_mask:0xf bank_mask:0xf
	v_mov_b32_dpp v35, v23 row_shr:1 row_mask:0xf bank_mask:0xf
	v_mov_b32_dpp v68, v24 row_shl:1 row_mask:0xf bank_mask:0xf
	v_mov_b32_dpp v69, v25 row_shl:1 row_mask:0xf bank_mask:0xf
	v_mov_b32_dpp v70, v26 row_shl:1 row_mask:0xf bank_mask:0xf
	v_mov_b32_dpp v71, v27 row_shl:1 row_mask:0xf bank_mask:0xf
	v_mov_b32_dpp v80, v28 row_shl:1 row_mask:0xf bank_mask:0xf
	v_mov_b32_dpp v81, v29 row_shl:1 row_mask:0xf bank_mask:0xf
	v_mov_b32_dpp v82, v30 row_shl:1 row_mask:0xf bank_mask:0xf
	v_mov_b32_dpp v83, v31 row_shl:1 row_mask:0xf bank_mask:0xf
	v_pk_fma_f32 v[4:5], v[44:45], v[4:5], v[164:165]
	v_pk_fma_f32 v[6:7], v[46:47], v[6:7], v[166:167]
	v_pk_fma_f32 v[32:33], v[60:61], v[32:33], v[168:169]
	v_pk_fma_f32 v[34:35], v[62:63], v[34:35], v[170:171]
	v_pk_fma_f32 v[4:5], v[24:25], v[124:125], v[4:5]
	v_pk_fma_f32 v[6:7], v[26:27], v[126:127], v[6:7]
	v_pk_fma_f32 v[32:33], v[28:29], v[132:133], v[32:33]
	v_pk_fma_f32 v[34:35], v[30:31], v[134:135], v[34:35]
	v_pk_fma_f32 v[4:5], v[152:153], v[120:121], v[4:5]
	v_pk_fma_f32 v[6:7], v[154:155], v[122:123], v[6:7]
	v_pk_fma_f32 v[32:33], v[156:157], v[108:109], v[32:33]
	v_pk_fma_f32 v[34:35], v[158:159], v[110:111], v[34:35]
	v_and_b32_e32 v212, 0x7fffffff, v4
	v_and_b32_e32 v213, 0x7fffffff, v5
	v_and_b32_e32 v86, 0x7fffffff, v6
	v_and_b32_e32 v87, 0x7fffffff, v7
	v_pk_fma_f32 v[238:239], v[212:213], s[90:91], 1.0 op_sel_hi:[1,0,0]
	v_pk_fma_f32 v[92:93], v[86:87], s[90:91], 1.0 op_sel_hi:[1,0,0]
	v_pk_mul_f32 v[84:85], v[4:5], v[4:5]
	v_pk_mul_f32 v[100:101], v[6:7], v[6:7]
	v_rcp_f32_e32 v238, v238
	v_rcp_f32_e32 v239, v239
	v_rcp_f32_e32 v92, v92
	v_rcp_f32_e32 v93, v93
	v_pk_mul_f32 v[84:85], v[84:85], s[44:45] op_sel_hi:[1,0]
	v_pk_mul_f32 v[100:101], v[100:101], s[44:45] op_sel_hi:[1,0]
	v_pk_fma_f32 v[246:247], v[238:239], s[92:93], v[236:237] op_sel_hi:[1,0,0]
	v_pk_fma_f32 v[94:95], v[92:93], s[92:93], v[236:237] op_sel_hi:[1,0,0]
	v_exp_f32_e32 v84, v84
	v_exp_f32_e32 v85, v85
	v_exp_f32_e32 v100, v100
	v_exp_f32_e32 v101, v101
	v_pk_fma_f32 v[246:247], v[238:239], v[246:247], s[96:97] op_sel_hi:[1,1,0]
	v_pk_fma_f32 v[94:95], v[92:93], v[94:95], s[96:97] op_sel_hi:[1,1,0]
	v_pk_fma_f32 v[246:247], v[238:239], v[246:247], s[0:1] op_sel_hi:[1,1,0]
	v_pk_fma_f32 v[94:95], v[92:93], v[94:95], s[0:1] op_sel_hi:[1,1,0]
	v_pk_fma_f32 v[246:247], v[238:239], v[246:247], s[4:5] op_sel_hi:[1,1,0]
	v_pk_fma_f32 v[94:95], v[92:93], v[94:95], s[4:5] op_sel_hi:[1,1,0]
	v_pk_mul_f32 v[246:247], v[238:239], v[246:247]
	v_pk_mul_f32 v[94:95], v[92:93], v[94:95]
	v_max_f32_e32 v238, 0, v4
	v_max_f32_e32 v239, 0, v5
	v_max_f32_e32 v92, 0, v6
	v_max_f32_e32 v93, 0, v7
	v_pk_mul_f32 v[246:247], v[84:85], v[246:247]
	v_pk_mul_f32 v[94:95], v[100:101], v[94:95]
	v_pk_fma_f32 v[84:85], v[212:213], v[246:247], v[238:239] neg_lo:[1,0,0] neg_hi:[1,0,0]
	v_pk_fma_f32 v[100:101], v[86:87], v[94:95], v[92:93] neg_lo:[1,0,0] neg_hi:[1,0,0]
	v_pk_mul_f32 v[246:247], v[84:85], v[32:33]
	v_pk_mul_f32 v[94:95], v[100:101], v[34:35]
	v_cvt_pk_bf16_f32 v162, v246, v247
	v_cvt_pk_bf16_f32 v163, v94, v95
	v_add_u32_e32 v235, -1, v227
	v_mov_b32_e32 v245, v228
	v_cmp_gt_u32_e64 s[38:39], s64, v235
	v_cmp_gt_u32_e32 vcc, s88, v245
	v_mov_b32_e32 v235, v230
	s_and_b64 s[38:39], s[38:39], vcc
	s_and_saveexec_b64 s[30:31], s[38:39]
	global_store_dwordx4 v235, v[160:163], s[50:51]
	s_mov_b64 exec, s[30:31]
	s_nop 1
	v_pk_fma_f32 v[24:25], v[44:45], v[24:25], v[164:165]
	v_pk_fma_f32 v[26:27], v[46:47], v[26:27], v[166:167]
	v_pk_fma_f32 v[28:29], v[60:61], v[28:29], v[168:169]
	v_pk_fma_f32 v[30:31], v[62:63], v[30:31], v[170:171]
	v_pk_fma_f32 v[24:25], v[120:121], v[124:125], v[24:25]
	v_pk_fma_f32 v[26:27], v[122:123], v[126:127], v[26:27]
	v_pk_fma_f32 v[28:29], v[108:109], v[132:133], v[28:29]
	v_pk_fma_f32 v[30:31], v[110:111], v[134:135], v[30:31]
	v_pk_fma_f32 v[24:25], v[152:153], v[104:105], v[24:25]
	v_pk_fma_f32 v[26:27], v[154:155], v[106:107], v[26:27]
	v_pk_fma_f32 v[28:29], v[156:157], v[96:97], v[28:29]
	v_pk_fma_f32 v[30:31], v[158:159], v[98:99], v[30:31]
	v_and_b32_e32 v212, 0x7fffffff, v24
	v_and_b32_e32 v213, 0x7fffffff, v25
	v_and_b32_e32 v6, 0x7fffffff, v26
	v_and_b32_e32 v7, 0x7fffffff, v27
	v_pk_fma_f32 v[238:239], v[212:213], s[90:91], 1.0 op_sel_hi:[1,0,0]
	v_pk_fma_f32 v[32:33], v[6:7], s[90:91], 1.0 op_sel_hi:[1,0,0]
	v_pk_mul_f32 v[4:5], v[24:25], v[24:25]
	v_pk_mul_f32 v[84:85], v[26:27], v[26:27]
	v_rcp_f32_e32 v238, v238
	v_rcp_f32_e32 v239, v239
	v_rcp_f32_e32 v32, v32
	v_rcp_f32_e32 v33, v33
	v_pk_mul_f32 v[4:5], v[4:5], s[44:45] op_sel_hi:[1,0]
	v_pk_mul_f32 v[84:85], v[84:85], s[44:45] op_sel_hi:[1,0]
	v_pk_fma_f32 v[246:247], v[238:239], s[92:93], v[236:237] op_sel_hi:[1,0,0]
	v_pk_fma_f32 v[34:35], v[32:33], s[92:93], v[236:237] op_sel_hi:[1,0,0]
	v_exp_f32_e32 v4, v4
	v_exp_f32_e32 v5, v5
	v_exp_f32_e32 v84, v84
	v_exp_f32_e32 v85, v85
	v_pk_fma_f32 v[246:247], v[238:239], v[246:247], s[96:97] op_sel_hi:[1,1,0]
	v_pk_fma_f32 v[34:35], v[32:33], v[34:35], s[96:97] op_sel_hi:[1,1,0]
	v_pk_fma_f32 v[246:247], v[238:239], v[246:247], s[0:1] op_sel_hi:[1,1,0]
	v_pk_fma_f32 v[34:35], v[32:33], v[34:35], s[0:1] op_sel_hi:[1,1,0]
	v_pk_fma_f32 v[246:247], v[238:239], v[246:247], s[4:5] op_sel_hi:[1,1,0]
	v_pk_fma_f32 v[34:35], v[32:33], v[34:35], s[4:5] op_sel_hi:[1,1,0]
	v_pk_mul_f32 v[246:247], v[238:239], v[246:247]
	v_pk_mul_f32 v[34:35], v[32:33], v[34:35]
	v_max_f32_e32 v238, 0, v24
	v_max_f32_e32 v239, 0, v25
	v_max_f32_e32 v32, 0, v26
	v_max_f32_e32 v33, 0, v27
	v_pk_mul_f32 v[246:247], v[4:5], v[246:247]
	v_pk_mul_f32 v[34:35], v[84:85], v[34:35]
	v_pk_fma_f32 v[4:5], v[212:213], v[246:247], v[238:239] neg_lo:[1,0,0] neg_hi:[1,0,0]
	v_pk_fma_f32 v[84:85], v[6:7], v[34:35], v[32:33] neg_lo:[1,0,0] neg_hi:[1,0,0]
	v_pk_mul_f32 v[246:247], v[4:5], v[28:29]
	v_pk_mul_f32 v[34:35], v[84:85], v[30:31]
	v_cvt_pk_bf16_f32 v58, v246, v247
	v_cvt_pk_bf16_f32 v59, v34, v35
	v_add_u32_e32 v235, 0, v227
	v_add_u32_e32 v245, 1, v228
	v_cmp_gt_u32_e64 s[38:39], s64, v235
	v_cmp_gt_u32_e32 vcc, s88, v245
	v_add_u32_e32 v235, 5632, v230
	s_and_b64 s[38:39], s[38:39], vcc
	s_and_saveexec_b64 s[30:31], s[38:39]
	global_store_dwordx4 v235, v[56:59], s[50:51]
	s_mov_b64 exec, s[30:31]
	s_nop 1
	v_pk_fma_f32 v[120:121], v[44:45], v[120:121], v[164:165]
	v_pk_fma_f32 v[122:123], v[46:47], v[122:123], v[166:167]
	v_pk_fma_f32 v[108:109], v[60:61], v[108:109], v[168:169]
	v_pk_fma_f32 v[110:111], v[62:63], v[110:111], v[170:171]
	v_pk_fma_f32 v[120:121], v[104:105], v[124:125], v[120:121]
	v_pk_fma_f32 v[122:123], v[106:107], v[126:127], v[122:123]
	v_pk_fma_f32 v[108:109], v[96:97], v[132:133], v[108:109]
	v_pk_fma_f32 v[110:111], v[98:99], v[134:135], v[110:111]
	v_pk_fma_f32 v[120:121], v[152:153], v[16:17], v[120:121]
	v_pk_fma_f32 v[122:123], v[154:155], v[18:19], v[122:123]
	v_pk_fma_f32 v[108:109], v[156:157], v[20:21], v[108:109]
	v_pk_fma_f32 v[110:111], v[158:159], v[22:23], v[110:111]
	v_and_b32_e32 v212, 0x7fffffff, v120
	v_and_b32_e32 v213, 0x7fffffff, v121
	v_and_b32_e32 v6, 0x7fffffff, v122
	v_and_b32_e32 v7, 0x7fffffff, v123
	v_pk_fma_f32 v[238:239], v[212:213], s[90:91], 1.0 op_sel_hi:[1,0,0]
	v_pk_fma_f32 v[24:25], v[6:7], s[90:91], 1.0 op_sel_hi:[1,0,0]
	v_pk_mul_f32 v[4:5], v[120:121], v[120:121]
	v_pk_mul_f32 v[28:29], v[122:123], v[122:123]
	v_rcp_f32_e32 v238, v238
	v_rcp_f32_e32 v239, v239
	v_rcp_f32_e32 v24, v24
	v_rcp_f32_e32 v25, v25
	v_pk_mul_f32 v[4:5], v[4:5], s[44:45] op_sel_hi:[1,0]
	v_pk_mul_f32 v[28:29], v[28:29], s[44:45] op_sel_hi:[1,0]
	v_pk_fma_f32 v[246:247], v[238:239], s[92:93], v[236:237] op_sel_hi:[1,0,0]
	v_pk_fma_f32 v[26:27], v[24:25], s[92:93], v[236:237] op_sel_hi:[1,0,0]
	v_exp_f32_e32 v4, v4
	v_exp_f32_e32 v5, v5
	v_exp_f32_e32 v28, v28
	v_exp_f32_e32 v29, v29
	v_pk_fma_f32 v[246:247], v[238:239], v[246:247], s[96:97] op_sel_hi:[1,1,0]
	v_pk_fma_f32 v[26:27], v[24:25], v[26:27], s[96:97] op_sel_hi:[1,1,0]
	v_pk_fma_f32 v[246:247], v[238:239], v[246:247], s[0:1] op_sel_hi:[1,1,0]
	v_pk_fma_f32 v[26:27], v[24:25], v[26:27], s[0:1] op_sel_hi:[1,1,0]
	v_pk_fma_f32 v[246:247], v[238:239], v[246:247], s[4:5] op_sel_hi:[1,1,0]
	v_pk_fma_f32 v[26:27], v[24:25], v[26:27], s[4:5] op_sel_hi:[1,1,0]
	v_pk_mul_f32 v[246:247], v[238:239], v[246:247]
	v_pk_mul_f32 v[26:27], v[24:25], v[26:27]
	v_max_f32_e32 v238, 0, v120
	v_max_f32_e32 v239, 0, v121
	v_max_f32_e32 v24, 0, v122
	v_max_f32_e32 v25, 0, v123
	v_pk_mul_f32 v[246:247], v[4:5], v[246:247]
	v_pk_mul_f32 v[26:27], v[28:29], v[26:27]
	v_pk_fma_f32 v[4:5], v[212:213], v[246:247], v[238:239] neg_lo:[1,0,0] neg_hi:[1,0,0]
	v_pk_fma_f32 v[28:29], v[6:7], v[26:27], v[24:25] neg_lo:[1,0,0] neg_hi:[1,0,0]
	v_pk_mul_f32 v[246:247], v[4:5], v[108:109]
	v_pk_mul_f32 v[26:27], v[28:29], v[110:111]
	v_cvt_pk_bf16_f32 v50, v246, v247
	v_cvt_pk_bf16_f32 v51, v26, v27
	v_add_u32_e32 v235, 1, v227
	v_add_u32_e32 v245, 2, v228
	v_cmp_gt_u32_e64 s[38:39], s64, v235
	v_cmp_gt_u32_e32 vcc, s88, v245
	v_add_u32_e32 v235, 11264, v230
	s_and_b64 s[38:39], s[38:39], vcc
	s_and_saveexec_b64 s[30:31], s[38:39]
	global_store_dwordx4 v235, v[48:51], s[50:51]
	s_mov_b64 exec, s[30:31]
	s_nop 1
	v_pk_fma_f32 v[104:105], v[44:45], v[104:105], v[164:165]
	v_pk_fma_f32 v[106:107], v[46:47], v[106:107], v[166:167]
	v_pk_fma_f32 v[96:97], v[60:61], v[96:97], v[168:169]
	v_pk_fma_f32 v[98:99], v[62:63], v[98:99], v[170:171]
	v_pk_fma_f32 v[104:105], v[16:17], v[124:125], v[104:105]
	v_pk_fma_f32 v[106:107], v[18:19], v[126:127], v[106:107]
	v_pk_fma_f32 v[96:97], v[20:21], v[132:133], v[96:97]
	v_pk_fma_f32 v[98:99], v[22:23], v[134:135], v[98:99]
	v_pk_fma_f32 v[104:105], v[152:153], v[68:69], v[104:105]
	v_pk_fma_f32 v[106:107], v[154:155], v[70:71], v[106:107]
	v_pk_fma_f32 v[96:97], v[156:157], v[80:81], v[96:97]
	v_pk_fma_f32 v[98:99], v[158:159], v[82:83], v[98:99]
	v_and_b32_e32 v212, 0x7fffffff, v104
	v_and_b32_e32 v213, 0x7fffffff, v105
	v_and_b32_e32 v6, 0x7fffffff, v106
	v_and_b32_e32 v7, 0x7fffffff, v107
	v_pk_fma_f32 v[238:239], v[212:213], s[90:91], 1.0 op_sel_hi:[1,0,0]
	v_pk_fma_f32 v[24:25], v[6:7], s[90:91], 1.0 op_sel_hi:[1,0,0]
	v_pk_mul_f32 v[4:5], v[104:105], v[104:105]
	v_pk_mul_f32 v[28:29], v[106:107], v[106:107]
	v_rcp_f32_e32 v238, v238
	v_rcp_f32_e32 v239, v239
	v_rcp_f32_e32 v24, v24
	v_rcp_f32_e32 v25, v25
	v_pk_mul_f32 v[4:5], v[4:5], s[44:45] op_sel_hi:[1,0]
	v_pk_mul_f32 v[28:29], v[28:29], s[44:45] op_sel_hi:[1,0]
	v_pk_fma_f32 v[246:247], v[238:239], s[92:93], v[236:237] op_sel_hi:[1,0,0]
	v_pk_fma_f32 v[26:27], v[24:25], s[92:93], v[236:237] op_sel_hi:[1,0,0]
	v_exp_f32_e32 v4, v4
	v_exp_f32_e32 v5, v5
	v_exp_f32_e32 v28, v28
	v_exp_f32_e32 v29, v29
	v_pk_fma_f32 v[246:247], v[238:239], v[246:247], s[96:97] op_sel_hi:[1,1,0]
	v_pk_fma_f32 v[26:27], v[24:25], v[26:27], s[96:97] op_sel_hi:[1,1,0]
	v_pk_fma_f32 v[246:247], v[238:239], v[246:247], s[0:1] op_sel_hi:[1,1,0]
	v_pk_fma_f32 v[26:27], v[24:25], v[26:27], s[0:1] op_sel_hi:[1,1,0]
	v_pk_fma_f32 v[246:247], v[238:239], v[246:247], s[4:5] op_sel_hi:[1,1,0]
	v_pk_fma_f32 v[26:27], v[24:25], v[26:27], s[4:5] op_sel_hi:[1,1,0]
	v_pk_mul_f32 v[246:247], v[238:239], v[246:247]
	v_pk_mul_f32 v[26:27], v[24:25], v[26:27]
	v_max_f32_e32 v238, 0, v104
	v_max_f32_e32 v239, 0, v105
	v_max_f32_e32 v24, 0, v106
	v_max_f32_e32 v25, 0, v107
	v_pk_mul_f32 v[246:247], v[4:5], v[246:247]
	v_pk_mul_f32 v[26:27], v[28:29], v[26:27]
	v_pk_fma_f32 v[4:5], v[212:213], v[246:247], v[238:239] neg_lo:[1,0,0] neg_hi:[1,0,0]
	v_pk_fma_f32 v[28:29], v[6:7], v[26:27], v[24:25] neg_lo:[1,0,0] neg_hi:[1,0,0]
	v_pk_mul_f32 v[246:247], v[4:5], v[96:97]
	v_pk_mul_f32 v[26:27], v[28:29], v[98:99]
	v_cvt_pk_bf16_f32 v54, v246, v247
	v_cvt_pk_bf16_f32 v55, v26, v27
	v_add_u32_e32 v235, 2, v227
	v_add_u32_e32 v245, 3, v228
	v_cmp_gt_u32_e64 s[38:39], s64, v235
	v_cmp_gt_u32_e32 vcc, s88, v245
	v_add_u32_e32 v235, 16896, v230
	s_and_b64 s[38:39], s[38:39], vcc
	s_and_saveexec_b64 s[30:31], s[38:39]
	global_store_dwordx4 v235, v[52:55], s[50:51]
	s_mov_b64 exec, s[30:31]
	s_nop 1
	ds_read_b128 v[4:7], v232 offset:16
	ds_read_b128 v[16:19], v232 offset:528
	ds_read_b128 v[20:23], v234 offset:16
	ds_read_b128 v[24:27], v234 offset:528
	s_waitcnt lgkmcnt(0)
	v_mov_b32_dpp v4, v0 row_shr:1 row_mask:0xf bank_mask:0xf
	v_mov_b32_dpp v5, v1 row_shr:1 row_mask:0xf bank_mask:0xf
	v_mov_b32_dpp v6, v2 row_shr:1 row_mask:0xf bank_mask:0xf
	v_mov_b32_dpp v7, v3 row_shr:1 row_mask:0xf bank_mask:0xf
	v_mov_b32_dpp v16, v128 row_shr:1 row_mask:0xf bank_mask:0xf
	v_mov_b32_dpp v17, v129 row_shr:1 row_mask:0xf bank_mask:0xf
	v_mov_b32_dpp v18, v130 row_shr:1 row_mask:0xf bank_mask:0xf
	v_mov_b32_dpp v19, v131 row_shr:1 row_mask:0xf bank_mask:0xf
	v_mov_b32_dpp v20, v8 row_shl:1 row_mask:0xf bank_mask:0xf
	v_mov_b32_dpp v21, v9 row_shl:1 row_mask:0xf bank_mask:0xf
	v_mov_b32_dpp v22, v10 row_shl:1 row_mask:0xf bank_mask:0xf
	v_mov_b32_dpp v23, v11 row_shl:1 row_mask:0xf bank_mask:0xf
	v_mov_b32_dpp v24, v36 row_shl:1 row_mask:0xf bank_mask:0xf
	v_mov_b32_dpp v25, v37 row_shl:1 row_mask:0xf bank_mask:0xf
	v_mov_b32_dpp v26, v38 row_shl:1 row_mask:0xf bank_mask:0xf
	v_mov_b32_dpp v27, v39 row_shl:1 row_mask:0xf bank_mask:0xf
	v_pk_fma_f32 v[4:5], v[44:45], v[4:5], v[164:165]
	v_pk_fma_f32 v[6:7], v[46:47], v[6:7], v[166:167]
	v_pk_fma_f32 v[16:17], v[60:61], v[16:17], v[168:169]
	v_pk_fma_f32 v[18:19], v[62:63], v[18:19], v[170:171]
	v_pk_fma_f32 v[4:5], v[8:9], v[124:125], v[4:5]
	v_pk_fma_f32 v[6:7], v[10:11], v[126:127], v[6:7]
	v_pk_fma_f32 v[16:17], v[36:37], v[132:133], v[16:17]
	v_pk_fma_f32 v[18:19], v[38:39], v[134:135], v[18:19]
	v_pk_fma_f32 v[4:5], v[152:153], v[88:89], v[4:5]
	v_pk_fma_f32 v[6:7], v[154:155], v[90:91], v[6:7]
	v_pk_fma_f32 v[16:17], v[156:157], v[76:77], v[16:17]
	v_pk_fma_f32 v[18:19], v[158:159], v[78:79], v[18:19]
	v_and_b32_e32 v212, 0x7fffffff, v4
	v_and_b32_e32 v213, 0x7fffffff, v5
	v_and_b32_e32 v30, 0x7fffffff, v6
	v_and_b32_e32 v31, 0x7fffffff, v7
	v_pk_fma_f32 v[238:239], v[212:213], s[90:91], 1.0 op_sel_hi:[1,0,0]
	v_pk_fma_f32 v[32:33], v[30:31], s[90:91], 1.0 op_sel_hi:[1,0,0]
	v_pk_mul_f32 v[28:29], v[4:5], v[4:5]
	v_pk_mul_f32 v[48:49], v[6:7], v[6:7]
	v_rcp_f32_e32 v238, v238
	v_rcp_f32_e32 v239, v239
	v_rcp_f32_e32 v32, v32
	v_rcp_f32_e32 v33, v33
	v_pk_mul_f32 v[28:29], v[28:29], s[44:45] op_sel_hi:[1,0]
	v_pk_mul_f32 v[48:49], v[48:49], s[44:45] op_sel_hi:[1,0]
	v_pk_fma_f32 v[246:247], v[238:239], s[92:93], v[236:237] op_sel_hi:[1,0,0]
	v_pk_fma_f32 v[34:35], v[32:33], s[92:93], v[236:237] op_sel_hi:[1,0,0]
	v_exp_f32_e32 v28, v28
	v_exp_f32_e32 v29, v29
	v_exp_f32_e32 v48, v48
	v_exp_f32_e32 v49, v49
	v_pk_fma_f32 v[246:247], v[238:239], v[246:247], s[96:97] op_sel_hi:[1,1,0]
	v_pk_fma_f32 v[34:35], v[32:33], v[34:35], s[96:97] op_sel_hi:[1,1,0]
	v_pk_fma_f32 v[246:247], v[238:239], v[246:247], s[0:1] op_sel_hi:[1,1,0]
	v_pk_fma_f32 v[34:35], v[32:33], v[34:35], s[0:1] op_sel_hi:[1,1,0]
	v_pk_fma_f32 v[246:247], v[238:239], v[246:247], s[4:5] op_sel_hi:[1,1,0]
	v_pk_fma_f32 v[34:35], v[32:33], v[34:35], s[4:5] op_sel_hi:[1,1,0]
	v_pk_mul_f32 v[246:247], v[238:239], v[246:247]
	v_pk_mul_f32 v[34:35], v[32:33], v[34:35]
	v_max_f32_e32 v238, 0, v4
	v_max_f32_e32 v239, 0, v5
	v_max_f32_e32 v32, 0, v6
	v_max_f32_e32 v33, 0, v7
	v_pk_mul_f32 v[246:247], v[28:29], v[246:247]
	v_pk_mul_f32 v[34:35], v[48:49], v[34:35]
	v_pk_fma_f32 v[28:29], v[212:213], v[246:247], v[238:239] neg_lo:[1,0,0] neg_hi:[1,0,0]
	v_pk_fma_f32 v[48:49], v[30:31], v[34:35], v[32:33] neg_lo:[1,0,0] neg_hi:[1,0,0]
	v_pk_mul_f32 v[246:247], v[28:29], v[16:17]
	v_pk_mul_f32 v[34:35], v[48:49], v[18:19]
	v_cvt_pk_bf16_f32 v118, v246, v247
	v_cvt_pk_bf16_f32 v119, v34, v35
	v_add_u32_e32 v235, 127, v227
	v_add_u32_e32 v245, 128, v228
	v_cmp_gt_u32_e64 s[38:39], s64, v235
	v_cmp_gt_u32_e32 vcc, s88, v245
	v_add_u32_e32 v235, 720896, v230
	s_and_b64 s[38:39], s[38:39], vcc
	s_and_saveexec_b64 s[30:31], s[38:39]
	global_store_dwordx4 v235, v[116:119], s[50:51]
	s_mov_b64 exec, s[30:31]
	s_nop 1
	v_pk_fma_f32 v[8:9], v[44:45], v[8:9], v[164:165]
	v_pk_fma_f32 v[10:11], v[46:47], v[10:11], v[166:167]
	v_pk_fma_f32 v[36:37], v[60:61], v[36:37], v[168:169]
	v_pk_fma_f32 v[38:39], v[62:63], v[38:39], v[170:171]
	v_pk_fma_f32 v[8:9], v[88:89], v[124:125], v[8:9]
	v_pk_fma_f32 v[10:11], v[90:91], v[126:127], v[10:11]
	v_pk_fma_f32 v[36:37], v[76:77], v[132:133], v[36:37]
	v_pk_fma_f32 v[38:39], v[78:79], v[134:135], v[38:39]
	v_pk_fma_f32 v[8:9], v[152:153], v[72:73], v[8:9]
	v_pk_fma_f32 v[10:11], v[154:155], v[74:75], v[10:11]
	v_pk_fma_f32 v[36:37], v[156:157], v[64:65], v[36:37]
	v_pk_fma_f32 v[38:39], v[158:159], v[66:67], v[38:39]
	v_and_b32_e32 v212, 0x7fffffff, v8
	v_and_b32_e32 v213, 0x7fffffff, v9
	v_and_b32_e32 v6, 0x7fffffff, v10
	v_and_b32_e32 v7, 0x7fffffff, v11
	v_pk_fma_f32 v[238:239], v[212:213], s[90:91], 1.0 op_sel_hi:[1,0,0]
	v_pk_fma_f32 v[16:17], v[6:7], s[90:91], 1.0 op_sel_hi:[1,0,0]
	v_pk_mul_f32 v[4:5], v[8:9], v[8:9]
	v_pk_mul_f32 v[28:29], v[10:11], v[10:11]
	v_rcp_f32_e32 v238, v238
	v_rcp_f32_e32 v239, v239
	v_rcp_f32_e32 v16, v16
	v_rcp_f32_e32 v17, v17
	v_pk_mul_f32 v[4:5], v[4:5], s[44:45] op_sel_hi:[1,0]
	v_pk_mul_f32 v[28:29], v[28:29], s[44:45] op_sel_hi:[1,0]
	v_pk_fma_f32 v[246:247], v[238:239], s[92:93], v[236:237] op_sel_hi:[1,0,0]
	v_pk_fma_f32 v[18:19], v[16:17], s[92:93], v[236:237] op_sel_hi:[1,0,0]
	v_exp_f32_e32 v4, v4
	v_exp_f32_e32 v5, v5
	v_exp_f32_e32 v28, v28
	v_exp_f32_e32 v29, v29
	v_pk_fma_f32 v[246:247], v[238:239], v[246:247], s[96:97] op_sel_hi:[1,1,0]
	v_pk_fma_f32 v[18:19], v[16:17], v[18:19], s[96:97] op_sel_hi:[1,1,0]
	v_pk_fma_f32 v[246:247], v[238:239], v[246:247], s[0:1] op_sel_hi:[1,1,0]
	v_pk_fma_f32 v[18:19], v[16:17], v[18:19], s[0:1] op_sel_hi:[1,1,0]
	v_pk_fma_f32 v[246:247], v[238:239], v[246:247], s[4:5] op_sel_hi:[1,1,0]
	v_pk_fma_f32 v[18:19], v[16:17], v[18:19], s[4:5] op_sel_hi:[1,1,0]
	v_pk_mul_f32 v[246:247], v[238:239], v[246:247]
	v_pk_mul_f32 v[18:19], v[16:17], v[18:19]
	v_max_f32_e32 v238, 0, v8
	v_max_f32_e32 v239, 0, v9
	v_max_f32_e32 v16, 0, v10
	v_max_f32_e32 v17, 0, v11
	v_pk_mul_f32 v[246:247], v[4:5], v[246:247]
	v_pk_mul_f32 v[18:19], v[28:29], v[18:19]
	v_pk_fma_f32 v[4:5], v[212:213], v[246:247], v[238:239] neg_lo:[1,0,0] neg_hi:[1,0,0]
	v_pk_fma_f32 v[28:29], v[6:7], v[18:19], v[16:17] neg_lo:[1,0,0] neg_hi:[1,0,0]
	v_pk_mul_f32 v[246:247], v[4:5], v[36:37]
	v_pk_mul_f32 v[18:19], v[28:29], v[38:39]
	v_cvt_pk_bf16_f32 v174, v246, v247
	v_cvt_pk_bf16_f32 v175, v18, v19
	v_add_u32_e32 v235, 128, v227
	v_add_u32_e32 v245, 129, v228
	v_cmp_gt_u32_e64 s[38:39], s64, v235
	v_cmp_gt_u32_e32 vcc, s88, v245
	v_add_u32_e32 v235, 726528, v230
	s_and_b64 s[38:39], s[38:39], vcc
	s_and_saveexec_b64 s[30:31], s[38:39]
	global_store_dwordx4 v235, v[172:175], s[50:51]
	s_mov_b64 exec, s[30:31]
	s_nop 1
	v_pk_fma_f32 v[88:89], v[44:45], v[88:89], v[164:165]
	v_pk_fma_f32 v[90:91], v[46:47], v[90:91], v[166:167]
	v_pk_fma_f32 v[76:77], v[60:61], v[76:77], v[168:169]
	v_pk_fma_f32 v[78:79], v[62:63], v[78:79], v[170:171]
	v_pk_fma_f32 v[88:89], v[72:73], v[124:125], v[88:89]
	v_pk_fma_f32 v[90:91], v[74:75], v[126:127], v[90:91]
	v_pk_fma_f32 v[76:77], v[64:65], v[132:133], v[76:77]
	v_pk_fma_f32 v[78:79], v[66:67], v[134:135], v[78:79]
	v_pk_fma_f32 v[88:89], v[152:153], v[0:1], v[88:89]
	v_pk_fma_f32 v[90:91], v[154:155], v[2:3], v[90:91]
	v_pk_fma_f32 v[76:77], v[156:157], v[128:129], v[76:77]
	v_pk_fma_f32 v[78:79], v[158:159], v[130:131], v[78:79]
	v_and_b32_e32 v212, 0x7fffffff, v88
	v_and_b32_e32 v213, 0x7fffffff, v89
	v_and_b32_e32 v6, 0x7fffffff, v90
	v_and_b32_e32 v7, 0x7fffffff, v91
	v_pk_fma_f32 v[238:239], v[212:213], s[90:91], 1.0 op_sel_hi:[1,0,0]
	v_pk_fma_f32 v[8:9], v[6:7], s[90:91], 1.0 op_sel_hi:[1,0,0]
	v_pk_mul_f32 v[4:5], v[88:89], v[88:89]
	v_pk_mul_f32 v[16:17], v[90:91], v[90:91]
	v_rcp_f32_e32 v238, v238
	v_rcp_f32_e32 v239, v239
	v_rcp_f32_e32 v8, v8
	v_rcp_f32_e32 v9, v9
	v_pk_mul_f32 v[4:5], v[4:5], s[44:45] op_sel_hi:[1,0]
	v_pk_mul_f32 v[16:17], v[16:17], s[44:45] op_sel_hi:[1,0]
	v_pk_fma_f32 v[246:247], v[238:239], s[92:93], v[236:237] op_sel_hi:[1,0,0]
	v_pk_fma_f32 v[10:11], v[8:9], s[92:93], v[236:237] op_sel_hi:[1,0,0]
	v_exp_f32_e32 v4, v4
	v_exp_f32_e32 v5, v5
	v_exp_f32_e32 v16, v16
	v_exp_f32_e32 v17, v17
	v_pk_fma_f32 v[246:247], v[238:239], v[246:247], s[96:97] op_sel_hi:[1,1,0]
	v_pk_fma_f32 v[10:11], v[8:9], v[10:11], s[96:97] op_sel_hi:[1,1,0]
	v_pk_fma_f32 v[246:247], v[238:239], v[246:247], s[0:1] op_sel_hi:[1,1,0]
	v_pk_fma_f32 v[10:11], v[8:9], v[10:11], s[0:1] op_sel_hi:[1,1,0]
	v_pk_fma_f32 v[246:247], v[238:239], v[246:247], s[4:5] op_sel_hi:[1,1,0]
	v_pk_fma_f32 v[10:11], v[8:9], v[10:11], s[4:5] op_sel_hi:[1,1,0]
	v_pk_mul_f32 v[246:247], v[238:239], v[246:247]
	v_pk_mul_f32 v[10:11], v[8:9], v[10:11]
	v_max_f32_e32 v238, 0, v88
	v_max_f32_e32 v239, 0, v89
	v_max_f32_e32 v8, 0, v90
	v_max_f32_e32 v9, 0, v91
	v_pk_mul_f32 v[246:247], v[4:5], v[246:247]
	v_pk_mul_f32 v[10:11], v[16:17], v[10:11]
	v_pk_fma_f32 v[4:5], v[212:213], v[246:247], v[238:239] neg_lo:[1,0,0] neg_hi:[1,0,0]
	v_pk_fma_f32 v[16:17], v[6:7], v[10:11], v[8:9] neg_lo:[1,0,0] neg_hi:[1,0,0]
	v_pk_mul_f32 v[246:247], v[4:5], v[76:77]
	v_pk_mul_f32 v[10:11], v[16:17], v[78:79]
	v_cvt_pk_bf16_f32 v14, v246, v247
	v_cvt_pk_bf16_f32 v15, v10, v11
	v_add_u32_e32 v235, 129, v227
	v_add_u32_e32 v245, 130, v228
	v_cmp_gt_u32_e64 s[38:39], s64, v235
	v_cmp_gt_u32_e32 vcc, s88, v245
	v_add_u32_e32 v235, 732160, v230
	s_and_b64 s[38:39], s[38:39], vcc
	s_and_saveexec_b64 s[30:31], s[38:39]
	global_store_dwordx4 v235, v[12:15], s[50:51]
	s_mov_b64 exec, s[30:31]
	s_nop 1
	v_pk_fma_f32 v[72:73], v[44:45], v[72:73], v[164:165]
	v_pk_fma_f32 v[74:75], v[46:47], v[74:75], v[166:167]
	v_pk_fma_f32 v[64:65], v[60:61], v[64:65], v[168:169]
	v_pk_fma_f32 v[66:67], v[62:63], v[66:67], v[170:171]
	v_pk_fma_f32 v[72:73], v[0:1], v[124:125], v[72:73]
	v_pk_fma_f32 v[74:75], v[2:3], v[126:127], v[74:75]
	v_pk_fma_f32 v[64:65], v[128:129], v[132:133], v[64:65]
	v_pk_fma_f32 v[66:67], v[130:131], v[134:135], v[66:67]
	v_pk_fma_f32 v[72:73], v[152:153], v[20:21], v[72:73]
	v_pk_fma_f32 v[74:75], v[154:155], v[22:23], v[74:75]
	v_pk_fma_f32 v[64:65], v[156:157], v[24:25], v[64:65]
	v_pk_fma_f32 v[66:67], v[158:159], v[26:27], v[66:67]
	v_and_b32_e32 v212, 0x7fffffff, v72
	v_and_b32_e32 v213, 0x7fffffff, v73
	v_and_b32_e32 v6, 0x7fffffff, v74
	v_and_b32_e32 v7, 0x7fffffff, v75
	v_pk_fma_f32 v[238:239], v[212:213], s[90:91], 1.0 op_sel_hi:[1,0,0]
	v_pk_fma_f32 v[8:9], v[6:7], s[90:91], 1.0 op_sel_hi:[1,0,0]
	v_pk_mul_f32 v[4:5], v[72:73], v[72:73]
	v_pk_mul_f32 v[12:13], v[74:75], v[74:75]
	v_rcp_f32_e32 v238, v238
	v_rcp_f32_e32 v239, v239
	v_rcp_f32_e32 v8, v8
	v_rcp_f32_e32 v9, v9
	v_pk_mul_f32 v[4:5], v[4:5], s[44:45] op_sel_hi:[1,0]
	v_pk_mul_f32 v[12:13], v[12:13], s[44:45] op_sel_hi:[1,0]
	v_pk_fma_f32 v[246:247], v[238:239], s[92:93], v[236:237] op_sel_hi:[1,0,0]
	v_pk_fma_f32 v[10:11], v[8:9], s[92:93], v[236:237] op_sel_hi:[1,0,0]
	v_exp_f32_e32 v4, v4
	v_exp_f32_e32 v5, v5
	v_exp_f32_e32 v12, v12
	v_exp_f32_e32 v13, v13
	v_pk_fma_f32 v[246:247], v[238:239], v[246:247], s[96:97] op_sel_hi:[1,1,0]
	v_pk_fma_f32 v[10:11], v[8:9], v[10:11], s[96:97] op_sel_hi:[1,1,0]
	v_pk_fma_f32 v[246:247], v[238:239], v[246:247], s[0:1] op_sel_hi:[1,1,0]
	v_pk_fma_f32 v[10:11], v[8:9], v[10:11], s[0:1] op_sel_hi:[1,1,0]
	v_pk_fma_f32 v[246:247], v[238:239], v[246:247], s[4:5] op_sel_hi:[1,1,0]
	v_pk_fma_f32 v[10:11], v[8:9], v[10:11], s[4:5] op_sel_hi:[1,1,0]
	v_pk_mul_f32 v[246:247], v[238:239], v[246:247]
	v_pk_mul_f32 v[10:11], v[8:9], v[10:11]
	v_max_f32_e32 v238, 0, v72
	v_max_f32_e32 v239, 0, v73
	v_max_f32_e32 v8, 0, v74
	v_max_f32_e32 v9, 0, v75
	v_pk_mul_f32 v[246:247], v[4:5], v[246:247]
	v_pk_mul_f32 v[10:11], v[12:13], v[10:11]
	v_pk_fma_f32 v[4:5], v[212:213], v[246:247], v[238:239] neg_lo:[1,0,0] neg_hi:[1,0,0]
	v_pk_fma_f32 v[12:13], v[6:7], v[10:11], v[8:9] neg_lo:[1,0,0] neg_hi:[1,0,0]
	v_pk_mul_f32 v[246:247], v[4:5], v[64:65]
	v_pk_mul_f32 v[10:11], v[12:13], v[66:67]
	v_cvt_pk_bf16_f32 v42, v246, v247
	v_cvt_pk_bf16_f32 v43, v10, v11
	v_add_u32_e32 v235, 130, v227
	v_add_u32_e32 v245, 131, v228
	v_cmp_gt_u32_e64 s[38:39], s64, v235
	v_cmp_gt_u32_e32 vcc, s88, v245
	v_add_u32_e32 v235, 737792, v230
	s_and_b64 s[38:39], s[38:39], vcc
	s_and_saveexec_b64 s[30:31], s[38:39]
	global_store_dwordx4 v235, v[40:43], s[50:51]
	s_mov_b64 exec, s[30:31]
	s_nop 1
	s_branch .Lp5_done
.Lp5_edge:
	s_waitcnt vmcnt(0)
	ds_read_b128 v[56:59], v231 offset:0
	ds_read_b128 v[132:135], v231 offset:512
	ds_read_b128 v[152:155], v233 offset:0
	ds_read_b128 v[156:159], v233 offset:512
	s_waitcnt lgkmcnt(0)
	v_mov_b32_dpp v56, v60 row_shr:1 row_mask:0xf bank_mask:0xf
	v_mov_b32_dpp v57, v61 row_shr:1 row_mask:0xf bank_mask:0xf
	v_mov_b32_dpp v58, v62 row_shr:1 row_mask:0xf bank_mask:0xf
	v_mov_b32_dpp v59, v63 row_shr:1 row_mask:0xf bank_mask:0xf
	v_mov_b32_dpp v132, v44 row_shr:1 row_mask:0xf bank_mask:0xf
	v_mov_b32_dpp v133, v45 row_shr:1 row_mask:0xf bank_mask:0xf
	v_mov_b32_dpp v134, v46 row_shr:1 row_mask:0xf bank_mask:0xf
	v_mov_b32_dpp v135, v47 row_shr:1 row_mask:0xf bank_mask:0xf
	v_mov_b32_dpp v152, v48 row_shl:1 row_mask:0xf bank_mask:0xf
	v_mov_b32_dpp v153, v49 row_shl:1 row_mask:0xf bank_mask:0xf
	v_mov_b32_dpp v154, v50 row_shl:1 row_mask:0xf bank_mask:0xf
	v_mov_b32_dpp v155, v51 row_shl:1 row_mask:0xf bank_mask:0xf
	v_mov_b32_dpp v156, v52 row_shl:1 row_mask:0xf bank_mask:0xf
	v_mov_b32_dpp v157, v53 row_shl:1 row_mask:0xf bank_mask:0xf
	v_mov_b32_dpp v158, v54 row_shl:1 row_mask:0xf bank_mask:0xf
	v_mov_b32_dpp v159, v55 row_shl:1 row_mask:0xf bank_mask:0xf
	v_mov_b32_e32 v235, v228
	v_cmp_gt_i32_e32 vcc, 0x4000, v235
	s_nop 1
	v_cndmask_b32_e32 v245, v222, v221, vcc
	v_and_b32_e32 v235, v235, v245
	v_cmp_eq_u32_e64 s[34:35], 0, v235
	v_cmp_eq_u32_e64 s[36:37], v235, v245
	s_nop 1
	v_cndmask_b32_e64 v56, v56, 0, s[34:35]
	v_cndmask_b32_e64 v57, v57, 0, s[34:35]
	v_cndmask_b32_e64 v58, v58, 0, s[34:35]
	v_cndmask_b32_e64 v59, v59, 0, s[34:35]
	v_cndmask_b32_e64 v132, v132, 0, s[34:35]
	v_cndmask_b32_e64 v133, v133, 0, s[34:35]
	v_cndmask_b32_e64 v134, v134, 0, s[34:35]
	v_cndmask_b32_e64 v135, v135, 0, s[34:35]
	v_pk_fma_f32 v[56:57], v[176:177], v[56:57], v[200:201]
	v_pk_fma_f32 v[58:59], v[178:179], v[58:59], v[202:203]
	v_pk_fma_f32 v[132:133], v[180:181], v[132:133], v[204:205]
	v_pk_fma_f32 v[134:135], v[182:183], v[134:135], v[206:207]
	v_pk_fma_f32 v[56:57], v[48:49], v[184:185], v[56:57]
	v_pk_fma_f32 v[58:59], v[50:51], v[186:187], v[58:59]
	v_pk_fma_f32 v[132:133], v[52:53], v[188:189], v[132:133]
	v_pk_fma_f32 v[134:135], v[54:55], v[190:191], v[134:135]
	s_mov_b64 s[30:31], exec
	s_andn2_b64 exec, exec, s[36:37]
	v_pk_fma_f32 v[56:57], v[192:193], v[124:125], v[56:57]
	v_pk_fma_f32 v[58:59], v[194:195], v[126:127], v[58:59]
	v_pk_fma_f32 v[132:133], v[196:197], v[116:117], v[132:133]
	v_pk_fma_f32 v[134:135], v[198:199], v[118:119], v[134:135]
	s_mov_b64 exec, s[30:31]
	v_and_b32_e32 v212, 0x7fffffff, v56
	v_and_b32_e32 v213, 0x7fffffff, v57
	v_and_b32_e32 v166, 0x7fffffff, v58
	v_and_b32_e32 v167, 0x7fffffff, v59
	v_pk_fma_f32 v[238:239], v[212:213], s[90:91], 1.0 op_sel_hi:[1,0,0]
	v_pk_fma_f32 v[168:169], v[166:167], s[90:91], 1.0 op_sel_hi:[1,0,0]
	v_pk_mul_f32 v[164:165], v[56:57], v[56:57]
	v_pk_mul_f32 v[172:173], v[58:59], v[58:59]
	v_rcp_f32_e32 v238, v238
	v_rcp_f32_e32 v239, v239
	v_rcp_f32_e32 v168, v168
	v_rcp_f32_e32 v169, v169
	v_pk_mul_f32 v[164:165], v[164:165], s[44:45] op_sel_hi:[1,0]
	v_pk_mul_f32 v[172:173], v[172:173], s[44:45] op_sel_hi:[1,0]
	v_pk_fma_f32 v[246:247], v[238:239], s[92:93], v[236:237] op_sel_hi:[1,0,0]
	v_pk_fma_f32 v[170:171], v[168:169], s[92:93], v[236:237] op_sel_hi:[1,0,0]
	v_exp_f32_e32 v164, v164
	v_exp_f32_e32 v165, v165
	v_exp_f32_e32 v172, v172
	v_exp_f32_e32 v173, v173
	v_pk_fma_f32 v[246:247], v[238:239], v[246:247], s[96:97] op_sel_hi:[1,1,0]
	v_pk_fma_f32 v[170:171], v[168:169], v[170:171], s[96:97] op_sel_hi:[1,1,0]
	v_pk_fma_f32 v[246:247], v[238:239], v[246:247], s[0:1] op_sel_hi:[1,1,0]
	v_pk_fma_f32 v[170:171], v[168:169], v[170:171], s[0:1] op_sel_hi:[1,1,0]
	v_pk_fma_f32 v[246:247], v[238:239], v[246:247], s[4:5] op_sel_hi:[1,1,0]
	v_pk_fma_f32 v[170:171], v[168:169], v[170:171], s[4:5] op_sel_hi:[1,1,0]
	v_pk_mul_f32 v[246:247], v[238:239], v[246:247]
	v_pk_mul_f32 v[170:171], v[168:169], v[170:171]
	v_max_f32_e32 v238, 0, v56
	v_max_f32_e32 v239, 0, v57
	v_max_f32_e32 v168, 0, v58
	v_max_f32_e32 v169, 0, v59
	v_pk_mul_f32 v[246:247], v[164:165], v[246:247]
	v_pk_mul_f32 v[170:171], v[172:173], v[170:171]
	v_pk_fma_f32 v[164:165], v[212:213], v[246:247], v[238:239] neg_lo:[1,0,0] neg_hi:[1,0,0]
	v_pk_fma_f32 v[172:173], v[166:167], v[170:171], v[168:169] neg_lo:[1,0,0] neg_hi:[1,0,0]
	v_pk_mul_f32 v[246:247], v[164:165], v[132:133]
	v_pk_mul_f32 v[170:171], v[172:173], v[134:135]
	v_cvt_pk_bf16_f32 v160, v246, v247
	v_cvt_pk_bf16_f32 v161, v170, v171
	v_add_u32_e32 v235, 1, v228
	v_cmp_gt_i32_e32 vcc, 0x4000, v235
	s_nop 1
	v_cndmask_b32_e32 v245, v222, v221, vcc
	v_and_b32_e32 v235, v235, v245
	v_cmp_eq_u32_e64 s[34:35], 0, v235
	v_cmp_eq_u32_e64 s[36:37], v235, v245
	s_nop 1
	v_cndmask_b32_e64 v48, v48, 0, s[34:35]
	v_cndmask_b32_e64 v49, v49, 0, s[34:35]
	v_cndmask_b32_e64 v50, v50, 0, s[34:35]
	v_cndmask_b32_e64 v51, v51, 0, s[34:35]
	v_cndmask_b32_e64 v52, v52, 0, s[34:35]
	v_cndmask_b32_e64 v53, v53, 0, s[34:35]
	v_cndmask_b32_e64 v54, v54, 0, s[34:35]
	v_cndmask_b32_e64 v55, v55, 0, s[34:35]
	v_pk_fma_f32 v[48:49], v[176:177], v[48:49], v[200:201]
	v_pk_fma_f32 v[50:51], v[178:179], v[50:51], v[202:203]
	v_pk_fma_f32 v[52:53], v[180:181], v[52:53], v[204:205]
	v_pk_fma_f32 v[54:55], v[182:183], v[54:55], v[206:207]
	v_pk_fma_f32 v[48:49], v[124:125], v[184:185], v[48:49]
	v_pk_fma_f32 v[50:51], v[126:127], v[186:187], v[50:51]
	v_pk_fma_f32 v[52:53], v[116:117], v[188:189], v[52:53]
	v_pk_fma_f32 v[54:55], v[118:119], v[190:191], v[54:55]
	s_mov_b64 s[30:31], exec
	s_andn2_b64 exec, exec, s[36:37]
	v_pk_fma_f32 v[48:49], v[192:193], v[112:113], v[48:49]
	v_pk_fma_f32 v[50:51], v[194:195], v[114:115], v[50:51]
	v_pk_fma_f32 v[52:53], v[196:197], v[100:101], v[52:53]
	v_pk_fma_f32 v[54:55], v[198:199], v[102:103], v[54:55]
	s_mov_b64 exec, s[30:31]
	v_and_b32_e32 v212, 0x7fffffff, v48
	v_and_b32_e32 v213, 0x7fffffff, v49
	v_and_b32_e32 v134, 0x7fffffff, v50
	v_and_b32_e32 v135, 0x7fffffff, v51
	v_pk_fma_f32 v[238:239], v[212:213], s[90:91], 1.0 op_sel_hi:[1,0,0]
	v_pk_fma_f32 v[164:165], v[134:135], s[90:91], 1.0 op_sel_hi:[1,0,0]
	v_pk_mul_f32 v[132:133], v[48:49], v[48:49]
	v_pk_mul_f32 v[168:169], v[50:51], v[50:51]
	v_rcp_f32_e32 v238, v238
	v_rcp_f32_e32 v239, v239
	v_rcp_f32_e32 v164, v164
	v_rcp_f32_e32 v165, v165
	v_pk_mul_f32 v[132:133], v[132:133], s[44:45] op_sel_hi:[1,0]
	v_pk_mul_f32 v[168:169], v[168:169], s[44:45] op_sel_hi:[1,0]
	v_pk_fma_f32 v[246:247], v[238:239], s[92:93], v[236:237] op_sel_hi:[1,0,0]
	v_pk_fma_f32 v[166:167], v[164:165], s[92:93], v[236:237] op_sel_hi:[1,0,0]
	v_exp_f32_e32 v132, v132
	v_exp_f32_e32 v133, v133
	v_exp_f32_e32 v168, v168
	v_exp_f32_e32 v169, v169
	v_pk_fma_f32 v[246:247], v[238:239], v[246:247], s[96:97] op_sel_hi:[1,1,0]
	v_pk_fma_f32 v[166:167], v[164:165], v[166:167], s[96:97] op_sel_hi:[1,1,0]
	v_pk_fma_f32 v[246:247], v[238:239], v[246:247], s[0:1] op_sel_hi:[1,1,0]
	v_pk_fma_f32 v[166:167], v[164:165], v[166:167], s[0:1] op_sel_hi:[1,1,0]
	v_pk_fma_f32 v[246:247], v[238:239], v[246:247], s[4:5] op_sel_hi:[1,1,0]
	v_pk_fma_f32 v[166:167], v[164:165], v[166:167], s[4:5] op_sel_hi:[1,1,0]
	v_pk_mul_f32 v[246:247], v[238:239], v[246:247]
	v_pk_mul_f32 v[166:167], v[164:165], v[166:167]
	v_max_f32_e32 v238, 0, v48
	v_max_f32_e32 v239, 0, v49
	v_max_f32_e32 v164, 0, v50
	v_max_f32_e32 v165, 0, v51
	v_pk_mul_f32 v[246:247], v[132:133], v[246:247]
	v_pk_mul_f32 v[166:167], v[168:169], v[166:167]
	v_pk_fma_f32 v[132:133], v[212:213], v[246:247], v[238:239] neg_lo:[1,0,0] neg_hi:[1,0,0]
	v_pk_fma_f32 v[168:169], v[134:135], v[166:167], v[164:165] neg_lo:[1,0,0] neg_hi:[1,0,0]
	v_pk_mul_f32 v[246:247], v[132:133], v[52:53]
	v_pk_mul_f32 v[166:167], v[168:169], v[54:55]
	v_cvt_pk_bf16_f32 v56, v246, v247
	v_cvt_pk_bf16_f32 v57, v166, v167
	v_add_u32_e32 v235, 2, v228
	v_cmp_gt_i32_e32 vcc, 0x4000, v235
	s_nop 1
	v_cndmask_b32_e32 v245, v222, v221, vcc
	v_and_b32_e32 v235, v235, v245
	v_cmp_eq_u32_e64 s[34:35], 0, v235
	v_cmp_eq_u32_e64 s[36:37], v235, v245
	s_nop 1
	v_cndmask_b32_e64 v124, v124, 0, s[34:35]
	v_cndmask_b32_e64 v125, v125, 0, s[34:35]
	v_cndmask_b32_e64 v126, v126, 0, s[34:35]
	v_cndmask_b32_e64 v127, v127, 0, s[34:35]
	v_cndmask_b32_e64 v116, v116, 0, s[34:35]
	v_cndmask_b32_e64 v117, v117, 0, s[34:35]
	v_cndmask_b32_e64 v118, v118, 0, s[34:35]
	v_cndmask_b32_e64 v119, v119, 0, s[34:35]
	v_pk_fma_f32 v[124:125], v[176:177], v[124:125], v[200:201]
	v_pk_fma_f32 v[126:127], v[178:179], v[126:127], v[202:203]
	v_pk_fma_f32 v[116:117], v[180:181], v[116:117], v[204:205]
	v_pk_fma_f32 v[118:119], v[182:183], v[118:119], v[206:207]
	v_pk_fma_f32 v[124:125], v[112:113], v[184:185], v[124:125]
	v_pk_fma_f32 v[126:127], v[114:115], v[186:187], v[126:127]
	v_pk_fma_f32 v[116:117], v[100:101], v[188:189], v[116:117]
	v_pk_fma_f32 v[118:119], v[102:103], v[190:191], v[118:119]
	s_mov_b64 s[30:31], exec
	s_andn2_b64 exec, exec, s[36:37]
	v_pk_fma_f32 v[124:125], v[192:193], v[60:61], v[124:125]
	v_pk_fma_f32 v[126:127], v[194:195], v[62:63], v[126:127]
	v_pk_fma_f32 v[116:117], v[196:197], v[44:45], v[116:117]
	v_pk_fma_f32 v[118:119], v[198:199], v[46:47], v[118:119]
	s_mov_b64 exec, s[30:31]
	v_and_b32_e32 v212, 0x7fffffff, v124
	v_and_b32_e32 v213, 0x7fffffff, v125
	v_and_b32_e32 v54, 0x7fffffff, v126
	v_and_b32_e32 v55, 0x7fffffff, v127
	v_pk_fma_f32 v[238:239], v[212:213], s[90:91], 1.0 op_sel_hi:[1,0,0]
	v_pk_fma_f32 v[132:133], v[54:55], s[90:91], 1.0 op_sel_hi:[1,0,0]
	v_pk_mul_f32 v[52:53], v[124:125], v[124:125]
	v_pk_mul_f32 v[164:165], v[126:127], v[126:127]
	v_rcp_f32_e32 v238, v238
	v_rcp_f32_e32 v239, v239
	v_rcp_f32_e32 v132, v132
	v_rcp_f32_e32 v133, v133
	v_pk_mul_f32 v[52:53], v[52:53], s[44:45] op_sel_hi:[1,0]
	v_pk_mul_f32 v[164:165], v[164:165], s[44:45] op_sel_hi:[1,0]
	v_pk_fma_f32 v[246:247], v[238:239], s[92:93], v[236:237] op_sel_hi:[1,0,0]
	v_pk_fma_f32 v[134:135], v[132:133], s[92:93], v[236:237] op_sel_hi:[1,0,0]
	v_exp_f32_e32 v52, v52
	v_exp_f32_e32 v53, v53
	v_exp_f32_e32 v164, v164
	v_exp_f32_e32 v165, v165
	v_pk_fma_f32 v[246:247], v[238:239], v[246:247], s[96:97] op_sel_hi:[1,1,0]
	v_pk_fma_f32 v[134:135], v[132:133], v[134:135], s[96:97] op_sel_hi:[1,1,0]
	v_pk_fma_f32 v[246:247], v[238:239], v[246:247], s[0:1] op_sel_hi:[1,1,0]
	v_pk_fma_f32 v[134:135], v[132:133], v[134:135], s[0:1] op_sel_hi:[1,1,0]
	v_pk_fma_f32 v[246:247], v[238:239], v[246:247], s[4:5] op_sel_hi:[1,1,0]
	v_pk_fma_f32 v[134:135], v[132:133], v[134:135], s[4:5] op_sel_hi:[1,1,0]
	v_pk_mul_f32 v[246:247], v[238:239], v[246:247]
	v_pk_mul_f32 v[134:135], v[132:133], v[134:135]
	v_max_f32_e32 v238, 0, v124
	v_max_f32_e32 v239, 0, v125
	v_max_f32_e32 v132, 0, v126
	v_max_f32_e32 v133, 0, v127
	v_pk_mul_f32 v[246:247], v[52:53], v[246:247]
	v_pk_mul_f32 v[134:135], v[164:165], v[134:135]
	v_pk_fma_f32 v[52:53], v[212:213], v[246:247], v[238:239] neg_lo:[1,0,0] neg_hi:[1,0,0]
	v_pk_fma_f32 v[164:165], v[54:55], v[134:135], v[132:133] neg_lo:[1,0,0] neg_hi:[1,0,0]
	v_pk_mul_f32 v[246:247], v[52:53], v[116:117]
	v_pk_mul_f32 v[134:135], v[164:165], v[118:119]
	v_cvt_pk_bf16_f32 v48, v246, v247
	v_cvt_pk_bf16_f32 v49, v134, v135
	v_add_u32_e32 v235, 3, v228
	v_cmp_gt_i32_e32 vcc, 0x4000, v235
	s_nop 1
	v_cndmask_b32_e32 v245, v222, v221, vcc
	v_and_b32_e32 v235, v235, v245
	v_cmp_eq_u32_e64 s[34:35], 0, v235
	v_cmp_eq_u32_e64 s[36:37], v235, v245
	s_nop 1
	v_cndmask_b32_e64 v112, v112, 0, s[34:35]
	v_cndmask_b32_e64 v113, v113, 0, s[34:35]
	v_cndmask_b32_e64 v114, v114, 0, s[34:35]
	v_cndmask_b32_e64 v115, v115, 0, s[34:35]
	v_cndmask_b32_e64 v100, v100, 0, s[34:35]
	v_cndmask_b32_e64 v101, v101, 0, s[34:35]
	v_cndmask_b32_e64 v102, v102, 0, s[34:35]
	v_cndmask_b32_e64 v103, v103, 0, s[34:35]
	v_pk_fma_f32 v[112:113], v[176:177], v[112:113], v[200:201]
	v_pk_fma_f32 v[114:115], v[178:179], v[114:115], v[202:203]
	v_pk_fma_f32 v[100:101], v[180:181], v[100:101], v[204:205]
	v_pk_fma_f32 v[102:103], v[182:183], v[102:103], v[206:207]
	v_pk_fma_f32 v[112:113], v[60:61], v[184:185], v[112:113]
	v_pk_fma_f32 v[114:115], v[62:63], v[186:187], v[114:115]
	v_pk_fma_f32 v[100:101], v[44:45], v[188:189], v[100:101]
	v_pk_fma_f32 v[102:103], v[46:47], v[190:191], v[102:103]
	s_mov_b64 s[30:31], exec
	s_andn2_b64 exec, exec, s[36:37]
	v_pk_fma_f32 v[112:113], v[192:193], v[152:153], v[112:113]
	v_pk_fma_f32 v[114:115], v[194:195], v[154:155], v[114:115]
	v_pk_fma_f32 v[100:101], v[196:197], v[156:157], v[100:101]
	v_pk_fma_f32 v[102:103], v[198:199], v[158:159], v[102:103]
	s_mov_b64 exec, s[30:31]
	v_and_b32_e32 v212, 0x7fffffff, v112
	v_and_b32_e32 v213, 0x7fffffff, v113
	v_and_b32_e32 v118, 0x7fffffff, v114
	v_and_b32_e32 v119, 0x7fffffff, v115
	v_pk_fma_f32 v[238:239], v[212:213], s[90:91], 1.0 op_sel_hi:[1,0,0]
	v_pk_fma_f32 v[124:125], v[118:119], s[90:91], 1.0 op_sel_hi:[1,0,0]
	v_pk_mul_f32 v[116:117], v[112:113], v[112:113]
	v_pk_mul_f32 v[132:133], v[114:115], v[114:115]
	v_rcp_f32_e32 v238, v238
	v_rcp_f32_e32 v239, v239
	v_rcp_f32_e32 v124, v124
	v_rcp_f32_e32 v125, v125
	v_pk_mul_f32 v[116:117], v[116:117], s[44:45] op_sel_hi:[1,0]
	v_pk_mul_f32 v[132:133], v[132:133], s[44:45] op_sel_hi:[1,0]
	v_pk_fma_f32 v[246:247], v[238:239], s[92:93], v[236:237] op_sel_hi:[1,0,0]
	v_pk_fma_f32 v[126:127], v[124:125], s[92:93], v[236:237] op_sel_hi:[1,0,0]
	v_exp_f32_e32 v116, v116
	v_exp_f32_e32 v117, v117
	v_exp_f32_e32 v132, v132
	v_exp_f32_e32 v133, v133
	v_pk_fma_f32 v[246:247], v[238:239], v[246:247], s[96:97] op_sel_hi:[1,1,0]
	v_pk_fma_f32 v[126:127], v[124:125], v[126:127], s[96:97] op_sel_hi:[1,1,0]
	v_pk_fma_f32 v[246:247], v[238:239], v[246:247], s[0:1] op_sel_hi:[1,1,0]
	v_pk_fma_f32 v[126:127], v[124:125], v[126:127], s[0:1] op_sel_hi:[1,1,0]
	v_pk_fma_f32 v[246:247], v[238:239], v[246:247], s[4:5] op_sel_hi:[1,1,0]
	v_pk_fma_f32 v[126:127], v[124:125], v[126:127], s[4:5] op_sel_hi:[1,1,0]
	v_pk_mul_f32 v[246:247], v[238:239], v[246:247]
	v_pk_mul_f32 v[126:127], v[124:125], v[126:127]
	v_max_f32_e32 v238, 0, v112
	v_max_f32_e32 v239, 0, v113
	v_max_f32_e32 v124, 0, v114
	v_max_f32_e32 v125, 0, v115
	v_pk_mul_f32 v[246:247], v[116:117], v[246:247]
	v_pk_mul_f32 v[126:127], v[132:133], v[126:127]
	v_pk_fma_f32 v[116:117], v[212:213], v[246:247], v[238:239] neg_lo:[1,0,0] neg_hi:[1,0,0]
	v_pk_fma_f32 v[132:133], v[118:119], v[126:127], v[124:125] neg_lo:[1,0,0] neg_hi:[1,0,0]
	v_pk_mul_f32 v[246:247], v[116:117], v[100:101]
	v_pk_mul_f32 v[126:127], v[132:133], v[102:103]
	v_cvt_pk_bf16_f32 v52, v246, v247
	v_cvt_pk_bf16_f32 v53, v126, v127
	ds_read_b128 v[44:47], v232 offset:0
	ds_read_b128 v[60:63], v232 offset:512
	ds_read_b128 v[100:103], v234 offset:0
	ds_read_b128 v[112:115], v234 offset:512
	s_waitcnt lgkmcnt(0)
	v_mov_b32_dpp v44, v4 row_shr:1 row_mask:0xf bank_mask:0xf
	v_mov_b32_dpp v45, v5 row_shr:1 row_mask:0xf bank_mask:0xf
	v_mov_b32_dpp v46, v6 row_shr:1 row_mask:0xf bank_mask:0xf
	v_mov_b32_dpp v47, v7 row_shr:1 row_mask:0xf bank_mask:0xf
	v_mov_b32_dpp v60, v32 row_shr:1 row_mask:0xf bank_mask:0xf
	v_mov_b32_dpp v61, v33 row_shr:1 row_mask:0xf bank_mask:0xf
	v_mov_b32_dpp v62, v34 row_shr:1 row_mask:0xf bank_mask:0xf
	v_mov_b32_dpp v63, v35 row_shr:1 row_mask:0xf bank_mask:0xf
	v_mov_b32_dpp v100, v12 row_shl:1 row_mask:0xf bank_mask:0xf
	v_mov_b32_dpp v101, v13 row_shl:1 row_mask:0xf bank_mask:0xf
	v_mov_b32_dpp v102, v14 row_shl:1 row_mask:0xf bank_mask:0xf
	v_mov_b32_dpp v103, v15 row_shl:1 row_mask:0xf bank_mask:0xf
	v_mov_b32_dpp v112, v40 row_shl:1 row_mask:0xf bank_mask:0xf
	v_mov_b32_dpp v113, v41 row_shl:1 row_mask:0xf bank_mask:0xf
	v_mov_b32_dpp v114, v42 row_shl:1 row_mask:0xf bank_mask:0xf
	v_mov_b32_dpp v115, v43 row_shl:1 row_mask:0xf bank_mask:0xf
	v_add_u32_e32 v235, 128, v228
	v_cmp_gt_i32_e32 vcc, 0x4000, v235
	s_nop 1
	v_cndmask_b32_e32 v245, v222, v221, vcc
	v_and_b32_e32 v235, v235, v245
	v_cmp_eq_u32_e64 s[34:35], 0, v235
	v_cmp_eq_u32_e64 s[36:37], v235, v245
	s_nop 1
	v_cndmask_b32_e64 v44, v44, 0, s[34:35]
	v_cndmask_b32_e64 v45, v45, 0, s[34:35]
	v_cndmask_b32_e64 v46, v46, 0, s[34:35]
	v_cndmask_b32_e64 v47, v47, 0, s[34:35]
	v_cndmask_b32_e64 v60, v60, 0, s[34:35]
	v_cndmask_b32_e64 v61, v61, 0, s[34:35]
	v_cndmask_b32_e64 v62, v62, 0, s[34:35]
	v_cndmask_b32_e64 v63, v63, 0, s[34:35]
	v_pk_fma_f32 v[44:45], v[176:177], v[44:45], v[200:201]
	v_pk_fma_f32 v[46:47], v[178:179], v[46:47], v[202:203]
	v_pk_fma_f32 v[60:61], v[180:181], v[60:61], v[204:205]
	v_pk_fma_f32 v[62:63], v[182:183], v[62:63], v[206:207]
	v_pk_fma_f32 v[44:45], v[12:13], v[184:185], v[44:45]
	v_pk_fma_f32 v[46:47], v[14:15], v[186:187], v[46:47]
	v_pk_fma_f32 v[60:61], v[40:41], v[188:189], v[60:61]
	v_pk_fma_f32 v[62:63], v[42:43], v[190:191], v[62:63]
	s_mov_b64 s[30:31], exec
	s_andn2_b64 exec, exec, s[36:37]
	v_pk_fma_f32 v[44:45], v[192:193], v[92:93], v[44:45]
	v_pk_fma_f32 v[46:47], v[194:195], v[94:95], v[46:47]
	v_pk_fma_f32 v[60:61], v[196:197], v[84:85], v[60:61]
	v_pk_fma_f32 v[62:63], v[198:199], v[86:87], v[62:63]
	s_mov_b64 exec, s[30:31]
	v_and_b32_e32 v212, 0x7fffffff, v44
	v_and_b32_e32 v213, 0x7fffffff, v45
	v_and_b32_e32 v126, 0x7fffffff, v46
	v_and_b32_e32 v127, 0x7fffffff, v47
	v_pk_fma_f32 v[238:239], v[212:213], s[90:91], 1.0 op_sel_hi:[1,0,0]
	v_pk_fma_f32 v[132:133], v[126:127], s[90:91], 1.0 op_sel_hi:[1,0,0]
	v_pk_mul_f32 v[124:125], v[44:45], v[44:45]
	v_pk_mul_f32 v[152:153], v[46:47], v[46:47]
	v_rcp_f32_e32 v238, v238
	v_rcp_f32_e32 v239, v239
	v_rcp_f32_e32 v132, v132
	v_rcp_f32_e32 v133, v133
	v_pk_mul_f32 v[124:125], v[124:125], s[44:45] op_sel_hi:[1,0]
	v_pk_mul_f32 v[152:153], v[152:153], s[44:45] op_sel_hi:[1,0]
	v_pk_fma_f32 v[246:247], v[238:239], s[92:93], v[236:237] op_sel_hi:[1,0,0]
	v_pk_fma_f32 v[134:135], v[132:133], s[92:93], v[236:237] op_sel_hi:[1,0,0]
	v_exp_f32_e32 v124, v124
	v_exp_f32_e32 v125, v125
	v_exp_f32_e32 v152, v152
	v_exp_f32_e32 v153, v153
	v_pk_fma_f32 v[246:247], v[238:239], v[246:247], s[96:97] op_sel_hi:[1,1,0]
	v_pk_fma_f32 v[134:135], v[132:133], v[134:135], s[96:97] op_sel_hi:[1,1,0]
	v_pk_fma_f32 v[246:247], v[238:239], v[246:247], s[0:1] op_sel_hi:[1,1,0]
	v_pk_fma_f32 v[134:135], v[132:133], v[134:135], s[0:1] op_sel_hi:[1,1,0]
	v_pk_fma_f32 v[246:247], v[238:239], v[246:247], s[4:5] op_sel_hi:[1,1,0]
	v_pk_fma_f32 v[134:135], v[132:133], v[134:135], s[4:5] op_sel_hi:[1,1,0]
	v_pk_mul_f32 v[246:247], v[238:239], v[246:247]
	v_pk_mul_f32 v[134:135], v[132:133], v[134:135]
	v_max_f32_e32 v238, 0, v44
	v_max_f32_e32 v239, 0, v45
	v_max_f32_e32 v132, 0, v46
	v_max_f32_e32 v133, 0, v47
	v_pk_mul_f32 v[246:247], v[124:125], v[246:247]
	v_pk_mul_f32 v[134:135], v[152:153], v[134:135]
	v_pk_fma_f32 v[124:125], v[212:213], v[246:247], v[238:239] neg_lo:[1,0,0] neg_hi:[1,0,0]
	v_pk_fma_f32 v[152:153], v[126:127], v[134:135], v[132:133] neg_lo:[1,0,0] neg_hi:[1,0,0]
	v_pk_mul_f32 v[246:247], v[124:125], v[60:61]
	v_pk_mul_f32 v[134:135], v[152:153], v[62:63]
	v_cvt_pk_bf16_f32 v116, v246, v247
	v_cvt_pk_bf16_f32 v117, v134, v135
	global_load_dwordx4 v[44:47], v226, s[12:13] offset:16
	global_load_dwordx4 v[60:63], v226, s[14:15] offset:16
	global_load_dwordx4 v[124:127], v226, s[16:17] offset:16
	global_load_dwordx4 v[132:135], v226, s[18:19] offset:16
	global_load_dwordx4 v[152:155], v226, s[20:21] offset:16
	global_load_dwordx4 v[156:159], v226, s[22:23] offset:16
	global_load_dwordx4 v[164:167], v226, s[24:25] offset:16
	global_load_dwordx4 v[168:171], v226, s[26:27] offset:16
	v_add_u32_e32 v235, 129, v228
	v_cmp_gt_i32_e32 vcc, 0x4000, v235
	s_nop 1
	v_cndmask_b32_e32 v245, v222, v221, vcc
	v_and_b32_e32 v235, v235, v245
	v_cmp_eq_u32_e64 s[34:35], 0, v235
	v_cmp_eq_u32_e64 s[36:37], v235, v245
	s_nop 1
	v_cndmask_b32_e64 v12, v12, 0, s[34:35]
	v_cndmask_b32_e64 v13, v13, 0, s[34:35]
	v_cndmask_b32_e64 v14, v14, 0, s[34:35]
	v_cndmask_b32_e64 v15, v15, 0, s[34:35]
	v_cndmask_b32_e64 v40, v40, 0, s[34:35]
	v_cndmask_b32_e64 v41, v41, 0, s[34:35]
	v_cndmask_b32_e64 v42, v42, 0, s[34:35]
	v_cndmask_b32_e64 v43, v43, 0, s[34:35]
	v_pk_fma_f32 v[12:13], v[176:177], v[12:13], v[200:201]
	v_pk_fma_f32 v[14:15], v[178:179], v[14:15], v[202:203]
	v_pk_fma_f32 v[40:41], v[180:181], v[40:41], v[204:205]
	v_pk_fma_f32 v[42:43], v[182:183], v[42:43], v[206:207]
	v_pk_fma_f32 v[12:13], v[92:93], v[184:185], v[12:13]
	v_pk_fma_f32 v[14:15], v[94:95], v[186:187], v[14:15]
	v_pk_fma_f32 v[40:41], v[84:85], v[188:189], v[40:41]
	v_pk_fma_f32 v[42:43], v[86:87], v[190:191], v[42:43]
	s_mov_b64 s[30:31], exec
	s_andn2_b64 exec, exec, s[36:37]
	v_pk_fma_f32 v[12:13], v[192:193], v[80:81], v[12:13]
	v_pk_fma_f32 v[14:15], v[194:195], v[82:83], v[14:15]
	v_pk_fma_f32 v[40:41], v[196:197], v[68:69], v[40:41]
	v_pk_fma_f32 v[42:43], v[198:199], v[70:71], v[42:43]
	s_mov_b64 exec, s[30:31]
	v_and_b32_e32 v212, 0x7fffffff, v12
	v_and_b32_e32 v213, 0x7fffffff, v13
	v_and_b32_e32 v210, 0x7fffffff, v14
	v_and_b32_e32 v211, 0x7fffffff, v15
	v_pk_fma_f32 v[238:239], v[212:213], s[90:91], 1.0 op_sel_hi:[1,0,0]
	v_pk_fma_f32 v[240:241], v[210:211], s[90:91], 1.0 op_sel_hi:[1,0,0]
	v_pk_mul_f32 v[208:209], v[12:13], v[12:13]
	v_pk_mul_f32 v[248:249], v[14:15], v[14:15]
	v_rcp_f32_e32 v238, v238
	v_rcp_f32_e32 v239, v239
	v_rcp_f32_e32 v240, v240
	v_rcp_f32_e32 v241, v241
	v_pk_mul_f32 v[208:209], v[208:209], s[44:45] op_sel_hi:[1,0]
	v_pk_mul_f32 v[248:249], v[248:249], s[44:45] op_sel_hi:[1,0]
	v_pk_fma_f32 v[246:247], v[238:239], s[92:93], v[236:237] op_sel_hi:[1,0,0]
	v_pk_fma_f32 v[242:243], v[240:241], s[92:93], v[236:237] op_sel_hi:[1,0,0]
	v_exp_f32_e32 v208, v208
	v_exp_f32_e32 v209, v209
	v_exp_f32_e32 v248, v248
	v_exp_f32_e32 v249, v249
	v_pk_fma_f32 v[246:247], v[238:239], v[246:247], s[96:97] op_sel_hi:[1,1,0]
	v_pk_fma_f32 v[242:243], v[240:241], v[242:243], s[96:97] op_sel_hi:[1,1,0]
	v_pk_fma_f32 v[246:247], v[238:239], v[246:247], s[0:1] op_sel_hi:[1,1,0]
	v_pk_fma_f32 v[242:243], v[240:241], v[242:243], s[0:1] op_sel_hi:[1,1,0]
	v_pk_fma_f32 v[246:247], v[238:239], v[246:247], s[4:5] op_sel_hi:[1,1,0]
	v_pk_fma_f32 v[242:243], v[240:241], v[242:243], s[4:5] op_sel_hi:[1,1,0]
	v_pk_mul_f32 v[246:247], v[238:239], v[246:247]
	v_pk_mul_f32 v[242:243], v[240:241], v[242:243]
	v_max_f32_e32 v238, 0, v12
	v_max_f32_e32 v239, 0, v13
	v_max_f32_e32 v240, 0, v14
	v_max_f32_e32 v241, 0, v15
	v_pk_mul_f32 v[246:247], v[208:209], v[246:247]
	v_pk_mul_f32 v[242:243], v[248:249], v[242:243]
	v_pk_fma_f32 v[208:209], v[212:213], v[246:247], v[238:239] neg_lo:[1,0,0] neg_hi:[1,0,0]
	v_pk_fma_f32 v[248:249], v[210:211], v[242:243], v[240:241] neg_lo:[1,0,0] neg_hi:[1,0,0]
	v_pk_mul_f32 v[246:247], v[208:209], v[40:41]
	v_pk_mul_f32 v[242:243], v[248:249], v[42:43]
	v_cvt_pk_bf16_f32 v172, v246, v247
	v_cvt_pk_bf16_f32 v173, v242, v243
	v_add_u32_e32 v235, 130, v228
	v_cmp_gt_i32_e32 vcc, 0x4000, v235
	s_nop 1
	v_cndmask_b32_e32 v245, v222, v221, vcc
	v_and_b32_e32 v235, v235, v245
	v_cmp_eq_u32_e64 s[34:35], 0, v235
	v_cmp_eq_u32_e64 s[36:37], v235, v245
	s_nop 1
	v_cndmask_b32_e64 v92, v92, 0, s[34:35]
	v_cndmask_b32_e64 v93, v93, 0, s[34:35]
	v_cndmask_b32_e64 v94, v94, 0, s[34:35]
	v_cndmask_b32_e64 v95, v95, 0, s[34:35]
	v_cndmask_b32_e64 v84, v84, 0, s[34:35]
	v_cndmask_b32_e64 v85, v85, 0, s[34:35]
	v_cndmask_b32_e64 v86, v86, 0, s[34:35]
	v_cndmask_b32_e64 v87, v87, 0, s[34:35]
	v_pk_fma_f32 v[92:93], v[176:177], v[92:93], v[200:201]
	v_pk_fma_f32 v[94:95], v[178:179], v[94:95], v[202:203]
	v_pk_fma_f32 v[84:85], v[180:181], v[84:85], v[204:205]
	v_pk_fma_f32 v[86:87], v[182:183], v[86:87], v[206:207]
	v_pk_fma_f32 v[92:93], v[80:81], v[184:185], v[92:93]
	v_pk_fma_f32 v[94:95], v[82:83], v[186:187], v[94:95]
	v_pk_fma_f32 v[84:85], v[68:69], v[188:189], v[84:85]
	v_pk_fma_f32 v[86:87], v[70:71], v[190:191], v[86:87]
	s_mov_b64 s[30:31], exec
	s_andn2_b64 exec, exec, s[36:37]
	v_pk_fma_f32 v[92:93], v[192:193], v[4:5], v[92:93]
	v_pk_fma_f32 v[94:95], v[194:195], v[6:7], v[94:95]
	v_pk_fma_f32 v[84:85], v[196:197], v[32:33], v[84:85]
	v_pk_fma_f32 v[86:87], v[198:199], v[34:35], v[86:87]
	s_mov_b64 exec, s[30:31]
	v_and_b32_e32 v212, 0x7fffffff, v92
	v_and_b32_e32 v213, 0x7fffffff, v93
	v_and_b32_e32 v42, 0x7fffffff, v94
	v_and_b32_e32 v43, 0x7fffffff, v95
	v_pk_fma_f32 v[238:239], v[212:213], s[90:91], 1.0 op_sel_hi:[1,0,0]
	v_pk_fma_f32 v[208:209], v[42:43], s[90:91], 1.0 op_sel_hi:[1,0,0]
	v_pk_mul_f32 v[40:41], v[92:93], v[92:93]
	v_pk_mul_f32 v[240:241], v[94:95], v[94:95]
	v_rcp_f32_e32 v238, v238
	v_rcp_f32_e32 v239, v239
	v_rcp_f32_e32 v208, v208
	v_rcp_f32_e32 v209, v209
	v_pk_mul_f32 v[40:41], v[40:41], s[44:45] op_sel_hi:[1,0]
	v_pk_mul_f32 v[240:241], v[240:241], s[44:45] op_sel_hi:[1,0]
	v_pk_fma_f32 v[246:247], v[238:239], s[92:93], v[236:237] op_sel_hi:[1,0,0]
	v_pk_fma_f32 v[210:211], v[208:209], s[92:93], v[236:237] op_sel_hi:[1,0,0]
	v_exp_f32_e32 v40, v40
	v_exp_f32_e32 v41, v41
	v_exp_f32_e32 v240, v240
	v_exp_f32_e32 v241, v241
	v_pk_fma_f32 v[246:247], v[238:239], v[246:247], s[96:97] op_sel_hi:[1,1,0]
	v_pk_fma_f32 v[210:211], v[208:209], v[210:211], s[96:97] op_sel_hi:[1,1,0]
	v_pk_fma_f32 v[246:247], v[238:239], v[246:247], s[0:1] op_sel_hi:[1,1,0]
	v_pk_fma_f32 v[210:211], v[208:209], v[210:211], s[0:1] op_sel_hi:[1,1,0]
	v_pk_fma_f32 v[246:247], v[238:239], v[246:247], s[4:5] op_sel_hi:[1,1,0]
	v_pk_fma_f32 v[210:211], v[208:209], v[210:211], s[4:5] op_sel_hi:[1,1,0]
	v_pk_mul_f32 v[246:247], v[238:239], v[246:247]
	v_pk_mul_f32 v[210:211], v[208:209], v[210:211]
	v_max_f32_e32 v238, 0, v92
	v_max_f32_e32 v239, 0, v93
	v_max_f32_e32 v208, 0, v94
	v_max_f32_e32 v209, 0, v95
	v_pk_mul_f32 v[246:247], v[40:41], v[246:247]
	v_pk_mul_f32 v[210:211], v[240:241], v[210:211]
	v_pk_fma_f32 v[40:41], v[212:213], v[246:247], v[238:239] neg_lo:[1,0,0] neg_hi:[1,0,0]
	v_pk_fma_f32 v[240:241], v[42:43], v[210:211], v[208:209] neg_lo:[1,0,0] neg_hi:[1,0,0]
	v_pk_mul_f32 v[246:247], v[40:41], v[84:85]
	v_pk_mul_f32 v[210:211], v[240:241], v[86:87]
	v_cvt_pk_bf16_f32 v12, v246, v247
	v_cvt_pk_bf16_f32 v13, v210, v211
	v_add_u32_e32 v235, 131, v228
	v_cmp_gt_i32_e32 vcc, 0x4000, v235
	s_nop 1
	v_cndmask_b32_e32 v245, v222, v221, vcc
	v_and_b32_e32 v235, v235, v245
	v_cmp_eq_u32_e64 s[34:35], 0, v235
	v_cmp_eq_u32_e64 s[36:37], v235, v245
	s_nop 1
	v_cndmask_b32_e64 v80, v80, 0, s[34:35]
	v_cndmask_b32_e64 v81, v81, 0, s[34:35]
	v_cndmask_b32_e64 v82, v82, 0, s[34:35]
	v_cndmask_b32_e64 v83, v83, 0, s[34:35]
	v_cndmask_b32_e64 v68, v68, 0, s[34:35]
	v_cndmask_b32_e64 v69, v69, 0, s[34:35]
	v_cndmask_b32_e64 v70, v70, 0, s[34:35]
	v_cndmask_b32_e64 v71, v71, 0, s[34:35]
	v_pk_fma_f32 v[80:81], v[176:177], v[80:81], v[200:201]
	v_pk_fma_f32 v[82:83], v[178:179], v[82:83], v[202:203]
	v_pk_fma_f32 v[68:69], v[180:181], v[68:69], v[204:205]
	v_pk_fma_f32 v[70:71], v[182:183], v[70:71], v[206:207]
	v_pk_fma_f32 v[80:81], v[4:5], v[184:185], v[80:81]
	v_pk_fma_f32 v[82:83], v[6:7], v[186:187], v[82:83]
	v_pk_fma_f32 v[68:69], v[32:33], v[188:189], v[68:69]
	v_pk_fma_f32 v[70:71], v[34:35], v[190:191], v[70:71]
	s_mov_b64 s[30:31], exec
	s_andn2_b64 exec, exec, s[36:37]
	v_pk_fma_f32 v[80:81], v[192:193], v[100:101], v[80:81]
	v_pk_fma_f32 v[82:83], v[194:195], v[102:103], v[82:83]
	v_pk_fma_f32 v[68:69], v[196:197], v[112:113], v[68:69]
	v_pk_fma_f32 v[70:71], v[198:199], v[114:115], v[70:71]
	s_mov_b64 exec, s[30:31]
	v_and_b32_e32 v212, 0x7fffffff, v80
	v_and_b32_e32 v213, 0x7fffffff, v81
	v_and_b32_e32 v86, 0x7fffffff, v82
	v_and_b32_e32 v87, 0x7fffffff, v83
	v_pk_fma_f32 v[238:239], v[212:213], s[90:91], 1.0 op_sel_hi:[1,0,0]
	v_pk_fma_f32 v[92:93], v[86:87], s[90:91], 1.0 op_sel_hi:[1,0,0]
	v_pk_mul_f32 v[84:85], v[80:81], v[80:81]
	v_pk_mul_f32 v[208:209], v[82:83], v[82:83]
	v_rcp_f32_e32 v238, v238
	v_rcp_f32_e32 v239, v239
	v_rcp_f32_e32 v92, v92
	v_rcp_f32_e32 v93, v93
	v_pk_mul_f32 v[84:85], v[84:85], s[44:45] op_sel_hi:[1,0]
	v_pk_mul_f32 v[208:209], v[208:209], s[44:45] op_sel_hi:[1,0]
	v_pk_fma_f32 v[246:247], v[238:239], s[92:93], v[236:237] op_sel_hi:[1,0,0]
	v_pk_fma_f32 v[94:95], v[92:93], s[92:93], v[236:237] op_sel_hi:[1,0,0]
	v_exp_f32_e32 v84, v84
	v_exp_f32_e32 v85, v85
	v_exp_f32_e32 v208, v208
	v_exp_f32_e32 v209, v209
	v_pk_fma_f32 v[246:247], v[238:239], v[246:247], s[96:97] op_sel_hi:[1,1,0]
	v_pk_fma_f32 v[94:95], v[92:93], v[94:95], s[96:97] op_sel_hi:[1,1,0]
	v_pk_fma_f32 v[246:247], v[238:239], v[246:247], s[0:1] op_sel_hi:[1,1,0]
	v_pk_fma_f32 v[94:95], v[92:93], v[94:95], s[0:1] op_sel_hi:[1,1,0]
	v_pk_fma_f32 v[246:247], v[238:239], v[246:247], s[4:5] op_sel_hi:[1,1,0]
	v_pk_fma_f32 v[94:95], v[92:93], v[94:95], s[4:5] op_sel_hi:[1,1,0]
	v_pk_mul_f32 v[246:247], v[238:239], v[246:247]
	v_pk_mul_f32 v[94:95], v[92:93], v[94:95]
	v_max_f32_e32 v238, 0, v80
	v_max_f32_e32 v239, 0, v81
	v_max_f32_e32 v92, 0, v82
	v_max_f32_e32 v93, 0, v83
	v_pk_mul_f32 v[246:247], v[84:85], v[246:247]
	v_pk_mul_f32 v[94:95], v[208:209], v[94:95]
	v_pk_fma_f32 v[84:85], v[212:213], v[246:247], v[238:239] neg_lo:[1,0,0] neg_hi:[1,0,0]
	v_pk_fma_f32 v[208:209], v[86:87], v[94:95], v[92:93] neg_lo:[1,0,0] neg_hi:[1,0,0]
	v_pk_mul_f32 v[246:247], v[84:85], v[68:69]
	v_pk_mul_f32 v[94:95], v[208:209], v[70:71]
	v_cvt_pk_bf16_f32 v40, v246, v247
	v_cvt_pk_bf16_f32 v41, v94, v95
	s_waitcnt vmcnt(0)
	ds_read_b128 v[4:7], v231 offset:16
	ds_read_b128 v[32:35], v231 offset:528
	ds_read_b128 v[68:71], v233 offset:16
	ds_read_b128 v[80:83], v233 offset:528
	s_waitcnt lgkmcnt(0)
	v_mov_b32_dpp v4, v16 row_shr:1 row_mask:0xf bank_mask:0xf
	v_mov_b32_dpp v5, v17 row_shr:1 row_mask:0xf bank_mask:0xf
	v_mov_b32_dpp v6, v18 row_shr:1 row_mask:0xf bank_mask:0xf
	v_mov_b32_dpp v7, v19 row_shr:1 row_mask:0xf bank_mask:0xf
	v_mov_b32_dpp v32, v20 row_shr:1 row_mask:0xf bank_mask:0xf
	v_mov_b32_dpp v33, v21 row_shr:1 row_mask:0xf bank_mask:0xf
	v_mov_b32_dpp v34, v22 row_shr:1 row_mask:0xf bank_mask:0xf
	v_mov_b32_dpp v35, v23 row_shr:1 row_mask:0xf bank_mask:0xf
	v_mov_b32_dpp v68, v24 row_shl:1 row_mask:0xf bank_mask:0xf
	v_mov_b32_dpp v69, v25 row_shl:1 row_mask:0xf bank_mask:0xf
	v_mov_b32_dpp v70, v26 row_shl:1 row_mask:0xf bank_mask:0xf
	v_mov_b32_dpp v71, v27 row_shl:1 row_mask:0xf bank_mask:0xf
	v_mov_b32_dpp v80, v28 row_shl:1 row_mask:0xf bank_mask:0xf
	v_mov_b32_dpp v81, v29 row_shl:1 row_mask:0xf bank_mask:0xf
	v_mov_b32_dpp v82, v30 row_shl:1 row_mask:0xf bank_mask:0xf
	v_mov_b32_dpp v83, v31 row_shl:1 row_mask:0xf bank_mask:0xf
	v_mov_b32_e32 v235, v228
	v_cmp_gt_i32_e32 vcc, 0x4000, v235
	s_nop 1
	v_cndmask_b32_e32 v245, v222, v221, vcc
	v_and_b32_e32 v235, v235, v245
	v_cmp_eq_u32_e64 s[34:35], 0, v235
	v_cmp_eq_u32_e64 s[36:37], v235, v245
	s_nop 1
	v_cndmask_b32_e64 v4, v4, 0, s[34:35]
	v_cndmask_b32_e64 v5, v5, 0, s[34:35]
	v_cndmask_b32_e64 v6, v6, 0, s[34:35]
	v_cndmask_b32_e64 v7, v7, 0, s[34:35]
	v_cndmask_b32_e64 v32, v32, 0, s[34:35]
	v_cndmask_b32_e64 v33, v33, 0, s[34:35]
	v_cndmask_b32_e64 v34, v34, 0, s[34:35]
	v_cndmask_b32_e64 v35, v35, 0, s[34:35]
	v_pk_fma_f32 v[4:5], v[44:45], v[4:5], v[164:165]
	v_pk_fma_f32 v[6:7], v[46:47], v[6:7], v[166:167]
	v_pk_fma_f32 v[32:33], v[60:61], v[32:33], v[168:169]
	v_pk_fma_f32 v[34:35], v[62:63], v[34:35], v[170:171]
	v_pk_fma_f32 v[4:5], v[24:25], v[124:125], v[4:5]
	v_pk_fma_f32 v[6:7], v[26:27], v[126:127], v[6:7]
	v_pk_fma_f32 v[32:33], v[28:29], v[132:133], v[32:33]
	v_pk_fma_f32 v[34:35], v[30:31], v[134:135], v[34:35]
	s_mov_b64 s[30:31], exec
	s_andn2_b64 exec, exec, s[36:37]
	v_pk_fma_f32 v[4:5], v[152:153], v[120:121], v[4:5]
	v_pk_fma_f32 v[6:7], v[154:155], v[122:123], v[6:7]
	v_pk_fma_f32 v[32:33], v[156:157], v[108:109], v[32:33]
	v_pk_fma_f32 v[34:35], v[158:159], v[110:111], v[34:35]
	s_mov_b64 exec, s[30:31]
	v_and_b32_e32 v212, 0x7fffffff, v4
	v_and_b32_e32 v213, 0x7fffffff, v5
	v_and_b32_e32 v86, 0x7fffffff, v6
	v_and_b32_e32 v87, 0x7fffffff, v7
	v_pk_fma_f32 v[238:239], v[212:213], s[90:91], 1.0 op_sel_hi:[1,0,0]
	v_pk_fma_f32 v[92:93], v[86:87], s[90:91], 1.0 op_sel_hi:[1,0,0]
	v_pk_mul_f32 v[84:85], v[4:5], v[4:5]
	v_pk_mul_f32 v[100:101], v[6:7], v[6:7]
	v_rcp_f32_e32 v238, v238
	v_rcp_f32_e32 v239, v239
	v_rcp_f32_e32 v92, v92
	v_rcp_f32_e32 v93, v93
	v_pk_mul_f32 v[84:85], v[84:85], s[44:45] op_sel_hi:[1,0]
	v_pk_mul_f32 v[100:101], v[100:101], s[44:45] op_sel_hi:[1,0]
	v_pk_fma_f32 v[246:247], v[238:239], s[92:93], v[236:237] op_sel_hi:[1,0,0]
	v_pk_fma_f32 v[94:95], v[92:93], s[92:93], v[236:237] op_sel_hi:[1,0,0]
	v_exp_f32_e32 v84, v84
	v_exp_f32_e32 v85, v85
	v_exp_f32_e32 v100, v100
	v_exp_f32_e32 v101, v101
	v_pk_fma_f32 v[246:247], v[238:239], v[246:247], s[96:97] op_sel_hi:[1,1,0]
	v_pk_fma_f32 v[94:95], v[92:93], v[94:95], s[96:97] op_sel_hi:[1,1,0]
	v_pk_fma_f32 v[246:247], v[238:239], v[246:247], s[0:1] op_sel_hi:[1,1,0]
	v_pk_fma_f32 v[94:95], v[92:93], v[94:95], s[0:1] op_sel_hi:[1,1,0]
	v_pk_fma_f32 v[246:247], v[238:239], v[246:247], s[4:5] op_sel_hi:[1,1,0]
	v_pk_fma_f32 v[94:95], v[92:93], v[94:95], s[4:5] op_sel_hi:[1,1,0]
	v_pk_mul_f32 v[246:247], v[238:239], v[246:247]
	v_pk_mul_f32 v[94:95], v[92:93], v[94:95]
	v_max_f32_e32 v238, 0, v4
	v_max_f32_e32 v239, 0, v5
	v_max_f32_e32 v92, 0, v6
	v_max_f32_e32 v93, 0, v7
	v_pk_mul_f32 v[246:247], v[84:85], v[246:247]
	v_pk_mul_f32 v[94:95], v[100:101], v[94:95]
	v_pk_fma_f32 v[84:85], v[212:213], v[246:247], v[238:239] neg_lo:[1,0,0] neg_hi:[1,0,0]
	v_pk_fma_f32 v[100:101], v[86:87], v[94:95], v[92:93] neg_lo:[1,0,0] neg_hi:[1,0,0]
	v_pk_mul_f32 v[246:247], v[84:85], v[32:33]
	v_pk_mul_f32 v[94:95], v[100:101], v[34:35]
	v_cvt_pk_bf16_f32 v162, v246, v247
	v_cvt_pk_bf16_f32 v163, v94, v95
	v_add_u32_e32 v235, -1, v227
	v_mov_b32_e32 v245, v228
	v_cmp_gt_u32_e64 s[38:39], s64, v235
	v_cmp_gt_u32_e32 vcc, s88, v245
	v_mov_b32_e32 v235, v230
	s_and_b64 s[38:39], s[38:39], vcc
	s_and_saveexec_b64 s[30:31], s[38:39]
	global_store_dwordx4 v235, v[160:163], s[50:51]
	s_mov_b64 exec, s[30:31]
	s_nop 1
	v_add_u32_e32 v235, 1, v228
	v_cmp_gt_i32_e32 vcc, 0x4000, v235
	s_nop 1
	v_cndmask_b32_e32 v245, v222, v221, vcc
	v_and_b32_e32 v235, v235, v245
	v_cmp_eq_u32_e64 s[34:35], 0, v235
	v_cmp_eq_u32_e64 s[36:37], v235, v245
	s_nop 1
	v_cndmask_b32_e64 v24, v24, 0, s[34:35]
	v_cndmask_b32_e64 v25, v25, 0, s[34:35]
	v_cndmask_b32_e64 v26, v26, 0, s[34:35]
	v_cndmask_b32_e64 v27, v27, 0, s[34:35]
	v_cndmask_b32_e64 v28, v28, 0, s[34:35]
	v_cndmask_b32_e64 v29, v29, 0, s[34:35]
	v_cndmask_b32_e64 v30, v30, 0, s[34:35]
	v_cndmask_b32_e64 v31, v31, 0, s[34:35]
	v_pk_fma_f32 v[24:25], v[44:45], v[24:25], v[164:165]
	v_pk_fma_f32 v[26:27], v[46:47], v[26:27], v[166:167]
	v_pk_fma_f32 v[28:29], v[60:61], v[28:29], v[168:169]
	v_pk_fma_f32 v[30:31], v[62:63], v[30:31], v[170:171]
	v_pk_fma_f32 v[24:25], v[120:121], v[124:125], v[24:25]
	v_pk_fma_f32 v[26:27], v[122:123], v[126:127], v[26:27]
	v_pk_fma_f32 v[28:29], v[108:109], v[132:133], v[28:29]
	v_pk_fma_f32 v[30:31], v[110:111], v[134:135], v[30:31]
	s_mov_b64 s[30:31], exec
	s_andn2_b64 exec, exec, s[36:37]
	v_pk_fma_f32 v[24:25], v[152:153], v[104:105], v[24:25]
	v_pk_fma_f32 v[26:27], v[154:155], v[106:107], v[26:27]
	v_pk_fma_f32 v[28:29], v[156:157], v[96:97], v[28:29]
	v_pk_fma_f32 v[30:31], v[158:159], v[98:99], v[30:31]
	s_mov_b64 exec, s[30:31]
	v_and_b32_e32 v212, 0x7fffffff, v24
	v_and_b32_e32 v213, 0x7fffffff, v25
	v_and_b32_e32 v6, 0x7fffffff, v26
	v_and_b32_e32 v7, 0x7fffffff, v27
	v_pk_fma_f32 v[238:239], v[212:213], s[90:91], 1.0 op_sel_hi:[1,0,0]
	v_pk_fma_f32 v[32:33], v[6:7], s[90:91], 1.0 op_sel_hi:[1,0,0]
	v_pk_mul_f32 v[4:5], v[24:25], v[24:25]
	v_pk_mul_f32 v[84:85], v[26:27], v[26:27]
	v_rcp_f32_e32 v238, v238
	v_rcp_f32_e32 v239, v239
	v_rcp_f32_e32 v32, v32
	v_rcp_f32_e32 v33, v33
	v_pk_mul_f32 v[4:5], v[4:5], s[44:45] op_sel_hi:[1,0]
	v_pk_mul_f32 v[84:85], v[84:85], s[44:45] op_sel_hi:[1,0]
	v_pk_fma_f32 v[246:247], v[238:239], s[92:93], v[236:237] op_sel_hi:[1,0,0]
	v_pk_fma_f32 v[34:35], v[32:33], s[92:93], v[236:237] op_sel_hi:[1,0,0]
	v_exp_f32_e32 v4, v4
	v_exp_f32_e32 v5, v5
	v_exp_f32_e32 v84, v84
	v_exp_f32_e32 v85, v85
	v_pk_fma_f32 v[246:247], v[238:239], v[246:247], s[96:97] op_sel_hi:[1,1,0]
	v_pk_fma_f32 v[34:35], v[32:33], v[34:35], s[96:97] op_sel_hi:[1,1,0]
	v_pk_fma_f32 v[246:247], v[238:239], v[246:247], s[0:1] op_sel_hi:[1,1,0]
	v_pk_fma_f32 v[34:35], v[32:33], v[34:35], s[0:1] op_sel_hi:[1,1,0]
	v_pk_fma_f32 v[246:247], v[238:239], v[246:247], s[4:5] op_sel_hi:[1,1,0]
	v_pk_fma_f32 v[34:35], v[32:33], v[34:35], s[4:5] op_sel_hi:[1,1,0]
	v_pk_mul_f32 v[246:247], v[238:239], v[246:247]
	v_pk_mul_f32 v[34:35], v[32:33], v[34:35]
	v_max_f32_e32 v238, 0, v24
	v_max_f32_e32 v239, 0, v25
	v_max_f32_e32 v32, 0, v26
	v_max_f32_e32 v33, 0, v27
	v_pk_mul_f32 v[246:247], v[4:5], v[246:247]
	v_pk_mul_f32 v[34:35], v[84:85], v[34:35]
	v_pk_fma_f32 v[4:5], v[212:213], v[246:247], v[238:239] neg_lo:[1,0,0] neg_hi:[1,0,0]
	v_pk_fma_f32 v[84:85], v[6:7], v[34:35], v[32:33] neg_lo:[1,0,0] neg_hi:[1,0,0]
	v_pk_mul_f32 v[246:247], v[4:5], v[28:29]
	v_pk_mul_f32 v[34:35], v[84:85], v[30:31]
	v_cvt_pk_bf16_f32 v58, v246, v247
	v_cvt_pk_bf16_f32 v59, v34, v35
	v_add_u32_e32 v235, 0, v227
	v_add_u32_e32 v245, 1, v228
	v_cmp_gt_u32_e64 s[38:39], s64, v235
	v_cmp_gt_u32_e32 vcc, s88, v245
	v_add_u32_e32 v235, 5632, v230
	s_and_b64 s[38:39], s[38:39], vcc
	s_and_saveexec_b64 s[30:31], s[38:39]
	global_store_dwordx4 v235, v[56:59], s[50:51]
	s_mov_b64 exec, s[30:31]
	s_nop 1
	v_add_u32_e32 v235, 2, v228
	v_cmp_gt_i32_e32 vcc, 0x4000, v235
	s_nop 1
	v_cndmask_b32_e32 v245, v222, v221, vcc
	v_and_b32_e32 v235, v235, v245
	v_cmp_eq_u32_e64 s[34:35], 0, v235
	v_cmp_eq_u32_e64 s[36:37], v235, v245
	s_nop 1
	v_cndmask_b32_e64 v120, v120, 0, s[34:35]
	v_cndmask_b32_e64 v121, v121, 0, s[34:35]
	v_cndmask_b32_e64 v122, v122, 0, s[34:35]
	v_cndmask_b32_e64 v123, v123, 0, s[34:35]
	v_cndmask_b32_e64 v108, v108, 0, s[34:35]
	v_cndmask_b32_e64 v109, v109, 0, s[34:35]
	v_cndmask_b32_e64 v110, v110, 0, s[34:35]
	v_cndmask_b32_e64 v111, v111, 0, s[34:35]
	v_pk_fma_f32 v[120:121], v[44:45], v[120:121], v[164:165]
	v_pk_fma_f32 v[122:123], v[46:47], v[122:123], v[166:167]
	v_pk_fma_f32 v[108:109], v[60:61], v[108:109], v[168:169]
	v_pk_fma_f32 v[110:111], v[62:63], v[110:111], v[170:171]
	v_pk_fma_f32 v[120:121], v[104:105], v[124:125], v[120:121]
	v_pk_fma_f32 v[122:123], v[106:107], v[126:127], v[122:123]
	v_pk_fma_f32 v[108:109], v[96:97], v[132:133], v[108:109]
	v_pk_fma_f32 v[110:111], v[98:99], v[134:135], v[110:111]
	s_mov_b64 s[30:31], exec
	s_andn2_b64 exec, exec, s[36:37]
	v_pk_fma_f32 v[120:121], v[152:153], v[16:17], v[120:121]
	v_pk_fma_f32 v[122:123], v[154:155], v[18:19], v[122:123]
	v_pk_fma_f32 v[108:109], v[156:157], v[20:21], v[108:109]
	v_pk_fma_f32 v[110:111], v[158:159], v[22:23], v[110:111]
	s_mov_b64 exec, s[30:31]
	v_and_b32_e32 v212, 0x7fffffff, v120
	v_and_b32_e32 v213, 0x7fffffff, v121
	v_and_b32_e32 v6, 0x7fffffff, v122
	v_and_b32_e32 v7, 0x7fffffff, v123
	v_pk_fma_f32 v[238:239], v[212:213], s[90:91], 1.0 op_sel_hi:[1,0,0]
	v_pk_fma_f32 v[24:25], v[6:7], s[90:91], 1.0 op_sel_hi:[1,0,0]
	v_pk_mul_f32 v[4:5], v[120:121], v[120:121]
	v_pk_mul_f32 v[28:29], v[122:123], v[122:123]
	v_rcp_f32_e32 v238, v238
	v_rcp_f32_e32 v239, v239
	v_rcp_f32_e32 v24, v24
	v_rcp_f32_e32 v25, v25
	v_pk_mul_f32 v[4:5], v[4:5], s[44:45] op_sel_hi:[1,0]
	v_pk_mul_f32 v[28:29], v[28:29], s[44:45] op_sel_hi:[1,0]
	v_pk_fma_f32 v[246:247], v[238:239], s[92:93], v[236:237] op_sel_hi:[1,0,0]
	v_pk_fma_f32 v[26:27], v[24:25], s[92:93], v[236:237] op_sel_hi:[1,0,0]
	v_exp_f32_e32 v4, v4
	v_exp_f32_e32 v5, v5
	v_exp_f32_e32 v28, v28
	v_exp_f32_e32 v29, v29
	v_pk_fma_f32 v[246:247], v[238:239], v[246:247], s[96:97] op_sel_hi:[1,1,0]
	v_pk_fma_f32 v[26:27], v[24:25], v[26:27], s[96:97] op_sel_hi:[1,1,0]
	v_pk_fma_f32 v[246:247], v[238:239], v[246:247], s[0:1] op_sel_hi:[1,1,0]
	v_pk_fma_f32 v[26:27], v[24:25], v[26:27], s[0:1] op_sel_hi:[1,1,0]
	v_pk_fma_f32 v[246:247], v[238:239], v[246:247], s[4:5] op_sel_hi:[1,1,0]
	v_pk_fma_f32 v[26:27], v[24:25], v[26:27], s[4:5] op_sel_hi:[1,1,0]
	v_pk_mul_f32 v[246:247], v[238:239], v[246:247]
	v_pk_mul_f32 v[26:27], v[24:25], v[26:27]
	v_max_f32_e32 v238, 0, v120
	v_max_f32_e32 v239, 0, v121
	v_max_f32_e32 v24, 0, v122
	v_max_f32_e32 v25, 0, v123
	v_pk_mul_f32 v[246:247], v[4:5], v[246:247]
	v_pk_mul_f32 v[26:27], v[28:29], v[26:27]
	v_pk_fma_f32 v[4:5], v[212:213], v[246:247], v[238:239] neg_lo:[1,0,0] neg_hi:[1,0,0]
	v_pk_fma_f32 v[28:29], v[6:7], v[26:27], v[24:25] neg_lo:[1,0,0] neg_hi:[1,0,0]
	v_pk_mul_f32 v[246:247], v[4:5], v[108:109]
	v_pk_mul_f32 v[26:27], v[28:29], v[110:111]
	v_cvt_pk_bf16_f32 v50, v246, v247
	v_cvt_pk_bf16_f32 v51, v26, v27
	v_add_u32_e32 v235, 1, v227
	v_add_u32_e32 v245, 2, v228
	v_cmp_gt_u32_e64 s[38:39], s64, v235
	v_cmp_gt_u32_e32 vcc, s88, v245
	v_add_u32_e32 v235, 11264, v230
	s_and_b64 s[38:39], s[38:39], vcc
	s_and_saveexec_b64 s[30:31], s[38:39]
	global_store_dwordx4 v235, v[48:51], s[50:51]
	s_mov_b64 exec, s[30:31]
	s_nop 1
	v_add_u32_e32 v235, 3, v228
	v_cmp_gt_i32_e32 vcc, 0x4000, v235
	s_nop 1
	v_cndmask_b32_e32 v245, v222, v221, vcc
	v_and_b32_e32 v235, v235, v245
	v_cmp_eq_u32_e64 s[34:35], 0, v235
	v_cmp_eq_u32_e64 s[36:37], v235, v245
	s_nop 1
	v_cndmask_b32_e64 v104, v104, 0, s[34:35]
	v_cndmask_b32_e64 v105, v105, 0, s[34:35]
	v_cndmask_b32_e64 v106, v106, 0, s[34:35]
	v_cndmask_b32_e64 v107, v107, 0, s[34:35]
	v_cndmask_b32_e64 v96, v96, 0, s[34:35]
	v_cndmask_b32_e64 v97, v97, 0, s[34:35]
	v_cndmask_b32_e64 v98, v98, 0, s[34:35]
	v_cndmask_b32_e64 v99, v99, 0, s[34:35]
	v_pk_fma_f32 v[104:105], v[44:45], v[104:105], v[164:165]
	v_pk_fma_f32 v[106:107], v[46:47], v[106:107], v[166:167]
	v_pk_fma_f32 v[96:97], v[60:61], v[96:97], v[168:169]
	v_pk_fma_f32 v[98:99], v[62:63], v[98:99], v[170:171]
	v_pk_fma_f32 v[104:105], v[16:17], v[124:125], v[104:105]
	v_pk_fma_f32 v[106:107], v[18:19], v[126:127], v[106:107]
	v_pk_fma_f32 v[96:97], v[20:21], v[132:133], v[96:97]
	v_pk_fma_f32 v[98:99], v[22:23], v[134:135], v[98:99]
	s_mov_b64 s[30:31], exec
	s_andn2_b64 exec, exec, s[36:37]
	v_pk_fma_f32 v[104:105], v[152:153], v[68:69], v[104:105]
	v_pk_fma_f32 v[106:107], v[154:155], v[70:71], v[106:107]
	v_pk_fma_f32 v[96:97], v[156:157], v[80:81], v[96:97]
	v_pk_fma_f32 v[98:99], v[158:159], v[82:83], v[98:99]
	s_mov_b64 exec, s[30:31]
	v_and_b32_e32 v212, 0x7fffffff, v104
	v_and_b32_e32 v213, 0x7fffffff, v105
	v_and_b32_e32 v6, 0x7fffffff, v106
	v_and_b32_e32 v7, 0x7fffffff, v107
	v_pk_fma_f32 v[238:239], v[212:213], s[90:91], 1.0 op_sel_hi:[1,0,0]
	v_pk_fma_f32 v[24:25], v[6:7], s[90:91], 1.0 op_sel_hi:[1,0,0]
	v_pk_mul_f32 v[4:5], v[104:105], v[104:105]
	v_pk_mul_f32 v[28:29], v[106:107], v[106:107]
	v_rcp_f32_e32 v238, v238
	v_rcp_f32_e32 v239, v239
	v_rcp_f32_e32 v24, v24
	v_rcp_f32_e32 v25, v25
	v_pk_mul_f32 v[4:5], v[4:5], s[44:45] op_sel_hi:[1,0]
	v_pk_mul_f32 v[28:29], v[28:29], s[44:45] op_sel_hi:[1,0]
	v_pk_fma_f32 v[246:247], v[238:239], s[92:93], v[236:237] op_sel_hi:[1,0,0]
	v_pk_fma_f32 v[26:27], v[24:25], s[92:93], v[236:237] op_sel_hi:[1,0,0]
	v_exp_f32_e32 v4, v4
	v_exp_f32_e32 v5, v5
	v_exp_f32_e32 v28, v28
	v_exp_f32_e32 v29, v29
	v_pk_fma_f32 v[246:247], v[238:239], v[246:247], s[96:97] op_sel_hi:[1,1,0]
	v_pk_fma_f32 v[26:27], v[24:25], v[26:27], s[96:97] op_sel_hi:[1,1,0]
	v_pk_fma_f32 v[246:247], v[238:239], v[246:247], s[0:1] op_sel_hi:[1,1,0]
	v_pk_fma_f32 v[26:27], v[24:25], v[26:27], s[0:1] op_sel_hi:[1,1,0]
	v_pk_fma_f32 v[246:247], v[238:239], v[246:247], s[4:5] op_sel_hi:[1,1,0]
	v_pk_fma_f32 v[26:27], v[24:25], v[26:27], s[4:5] op_sel_hi:[1,1,0]
	v_pk_mul_f32 v[246:247], v[238:239], v[246:247]
	v_pk_mul_f32 v[26:27], v[24:25], v[26:27]
	v_max_f32_e32 v238, 0, v104
	v_max_f32_e32 v239, 0, v105
	v_max_f32_e32 v24, 0, v106
	v_max_f32_e32 v25, 0, v107
	v_pk_mul_f32 v[246:247], v[4:5], v[246:247]
	v_pk_mul_f32 v[26:27], v[28:29], v[26:27]
	v_pk_fma_f32 v[4:5], v[212:213], v[246:247], v[238:239] neg_lo:[1,0,0] neg_hi:[1,0,0]
	v_pk_fma_f32 v[28:29], v[6:7], v[26:27], v[24:25] neg_lo:[1,0,0] neg_hi:[1,0,0]
	v_pk_mul_f32 v[246:247], v[4:5], v[96:97]
	v_pk_mul_f32 v[26:27], v[28:29], v[98:99]
	v_cvt_pk_bf16_f32 v54, v246, v247
	v_cvt_pk_bf16_f32 v55, v26, v27
	v_add_u32_e32 v235, 2, v227
	v_add_u32_e32 v245, 3, v228
	v_cmp_gt_u32_e64 s[38:39], s64, v235
	v_cmp_gt_u32_e32 vcc, s88, v245
	v_add_u32_e32 v235, 16896, v230
	s_and_b64 s[38:39], s[38:39], vcc
	s_and_saveexec_b64 s[30:31], s[38:39]
	global_store_dwordx4 v235, v[52:55], s[50:51]
	s_mov_b64 exec, s[30:31]
	s_nop 1
	ds_read_b128 v[4:7], v232 offset:16
	ds_read_b128 v[16:19], v232 offset:528
	ds_read_b128 v[20:23], v234 offset:16
	ds_read_b128 v[24:27], v234 offset:528
	s_waitcnt lgkmcnt(0)
	v_mov_b32_dpp v4, v0 row_shr:1 row_mask:0xf bank_mask:0xf
	v_mov_b32_dpp v5, v1 row_shr:1 row_mask:0xf bank_mask:0xf
	v_mov_b32_dpp v6, v2 row_shr:1 row_mask:0xf bank_mask:0xf
	v_mov_b32_dpp v7, v3 row_shr:1 row_mask:0xf bank_mask:0xf
	v_mov_b32_dpp v16, v128 row_shr:1 row_mask:0xf bank_mask:0xf
	v_mov_b32_dpp v17, v129 row_shr:1 row_mask:0xf bank_mask:0xf
	v_mov_b32_dpp v18, v130 row_shr:1 row_mask:0xf bank_mask:0xf
	v_mov_b32_dpp v19, v131 row_shr:1 row_mask:0xf bank_mask:0xf
	v_mov_b32_dpp v20, v8 row_shl:1 row_mask:0xf bank_mask:0xf
	v_mov_b32_dpp v21, v9 row_shl:1 row_mask:0xf bank_mask:0xf
	v_mov_b32_dpp v22, v10 row_shl:1 row_mask:0xf bank_mask:0xf
	v_mov_b32_dpp v23, v11 row_shl:1 row_mask:0xf bank_mask:0xf
	v_mov_b32_dpp v24, v36 row_shl:1 row_mask:0xf bank_mask:0xf
	v_mov_b32_dpp v25, v37 row_shl:1 row_mask:0xf bank_mask:0xf
	v_mov_b32_dpp v26, v38 row_shl:1 row_mask:0xf bank_mask:0xf
	v_mov_b32_dpp v27, v39 row_shl:1 row_mask:0xf bank_mask:0xf
	v_add_u32_e32 v235, 128, v228
	v_cmp_gt_i32_e32 vcc, 0x4000, v235
	s_nop 1
	v_cndmask_b32_e32 v245, v222, v221, vcc
	v_and_b32_e32 v235, v235, v245
	v_cmp_eq_u32_e64 s[34:35], 0, v235
	v_cmp_eq_u32_e64 s[36:37], v235, v245
	s_nop 1
	v_cndmask_b32_e64 v4, v4, 0, s[34:35]
	v_cndmask_b32_e64 v5, v5, 0, s[34:35]
	v_cndmask_b32_e64 v6, v6, 0, s[34:35]
	v_cndmask_b32_e64 v7, v7, 0, s[34:35]
	v_cndmask_b32_e64 v16, v16, 0, s[34:35]
	v_cndmask_b32_e64 v17, v17, 0, s[34:35]
	v_cndmask_b32_e64 v18, v18, 0, s[34:35]
	v_cndmask_b32_e64 v19, v19, 0, s[34:35]
	v_pk_fma_f32 v[4:5], v[44:45], v[4:5], v[164:165]
	v_pk_fma_f32 v[6:7], v[46:47], v[6:7], v[166:167]
	v_pk_fma_f32 v[16:17], v[60:61], v[16:17], v[168:169]
	v_pk_fma_f32 v[18:19], v[62:63], v[18:19], v[170:171]
	v_pk_fma_f32 v[4:5], v[8:9], v[124:125], v[4:5]
	v_pk_fma_f32 v[6:7], v[10:11], v[126:127], v[6:7]
	v_pk_fma_f32 v[16:17], v[36:37], v[132:133], v[16:17]
	v_pk_fma_f32 v[18:19], v[38:39], v[134:135], v[18:19]
	s_mov_b64 s[30:31], exec
	s_andn2_b64 exec, exec, s[36:37]
	v_pk_fma_f32 v[4:5], v[152:153], v[88:89], v[4:5]
	v_pk_fma_f32 v[6:7], v[154:155], v[90:91], v[6:7]
	v_pk_fma_f32 v[16:17], v[156:157], v[76:77], v[16:17]
	v_pk_fma_f32 v[18:19], v[158:159], v[78:79], v[18:19]
	s_mov_b64 exec, s[30:31]
	v_and_b32_e32 v212, 0x7fffffff, v4
	v_and_b32_e32 v213, 0x7fffffff, v5
	v_and_b32_e32 v30, 0x7fffffff, v6
	v_and_b32_e32 v31, 0x7fffffff, v7
	v_pk_fma_f32 v[238:239], v[212:213], s[90:91], 1.0 op_sel_hi:[1,0,0]
	v_pk_fma_f32 v[32:33], v[30:31], s[90:91], 1.0 op_sel_hi:[1,0,0]
	v_pk_mul_f32 v[28:29], v[4:5], v[4:5]
	v_pk_mul_f32 v[48:49], v[6:7], v[6:7]
	v_rcp_f32_e32 v238, v238
	v_rcp_f32_e32 v239, v239
	v_rcp_f32_e32 v32, v32
	v_rcp_f32_e32 v33, v33
	v_pk_mul_f32 v[28:29], v[28:29], s[44:45] op_sel_hi:[1,0]
	v_pk_mul_f32 v[48:49], v[48:49], s[44:45] op_sel_hi:[1,0]
	v_pk_fma_f32 v[246:247], v[238:239], s[92:93], v[236:237] op_sel_hi:[1,0,0]
	v_pk_fma_f32 v[34:35], v[32:33], s[92:93], v[236:237] op_sel_hi:[1,0,0]
	v_exp_f32_e32 v28, v28
	v_exp_f32_e32 v29, v29
	v_exp_f32_e32 v48, v48
	v_exp_f32_e32 v49, v49
	v_pk_fma_f32 v[246:247], v[238:239], v[246:247], s[96:97] op_sel_hi:[1,1,0]
	v_pk_fma_f32 v[34:35], v[32:33], v[34:35], s[96:97] op_sel_hi:[1,1,0]
	v_pk_fma_f32 v[246:247], v[238:239], v[246:247], s[0:1] op_sel_hi:[1,1,0]
	v_pk_fma_f32 v[34:35], v[32:33], v[34:35], s[0:1] op_sel_hi:[1,1,0]
	v_pk_fma_f32 v[246:247], v[238:239], v[246:247], s[4:5] op_sel_hi:[1,1,0]
	v_pk_fma_f32 v[34:35], v[32:33], v[34:35], s[4:5] op_sel_hi:[1,1,0]
	v_pk_mul_f32 v[246:247], v[238:239], v[246:247]
	v_pk_mul_f32 v[34:35], v[32:33], v[34:35]
	v_max_f32_e32 v238, 0, v4
	v_max_f32_e32 v239, 0, v5
	v_max_f32_e32 v32, 0, v6
	v_max_f32_e32 v33, 0, v7
	v_pk_mul_f32 v[246:247], v[28:29], v[246:247]
	v_pk_mul_f32 v[34:35], v[48:49], v[34:35]
	v_pk_fma_f32 v[28:29], v[212:213], v[246:247], v[238:239] neg_lo:[1,0,0] neg_hi:[1,0,0]
	v_pk_fma_f32 v[48:49], v[30:31], v[34:35], v[32:33] neg_lo:[1,0,0] neg_hi:[1,0,0]
	v_pk_mul_f32 v[246:247], v[28:29], v[16:17]
	v_pk_mul_f32 v[34:35], v[48:49], v[18:19]
	v_cvt_pk_bf16_f32 v118, v246, v247
	v_cvt_pk_bf16_f32 v119, v34, v35
	v_add_u32_e32 v235, 127, v227
	v_add_u32_e32 v245, 128, v228
	v_cmp_gt_u32_e64 s[38:39], s64, v235
	v_cmp_gt_u32_e32 vcc, s88, v245
	v_add_u32_e32 v235, 720896, v230
	s_and_b64 s[38:39], s[38:39], vcc
	s_and_saveexec_b64 s[30:31], s[38:39]
	global_store_dwordx4 v235, v[116:119], s[50:51]
	s_mov_b64 exec, s[30:31]
	s_nop 1
	v_add_u32_e32 v235, 129, v228
	v_cmp_gt_i32_e32 vcc, 0x4000, v235
	s_nop 1
	v_cndmask_b32_e32 v245, v222, v221, vcc
	v_and_b32_e32 v235, v235, v245
	v_cmp_eq_u32_e64 s[34:35], 0, v235
	v_cmp_eq_u32_e64 s[36:37], v235, v245
	s_nop 1
	v_cndmask_b32_e64 v8, v8, 0, s[34:35]
	v_cndmask_b32_e64 v9, v9, 0, s[34:35]
	v_cndmask_b32_e64 v10, v10, 0, s[34:35]
	v_cndmask_b32_e64 v11, v11, 0, s[34:35]
	v_cndmask_b32_e64 v36, v36, 0, s[34:35]
	v_cndmask_b32_e64 v37, v37, 0, s[34:35]
	v_cndmask_b32_e64 v38, v38, 0, s[34:35]
	v_cndmask_b32_e64 v39, v39, 0, s[34:35]
	v_pk_fma_f32 v[8:9], v[44:45], v[8:9], v[164:165]
	v_pk_fma_f32 v[10:11], v[46:47], v[10:11], v[166:167]
	v_pk_fma_f32 v[36:37], v[60:61], v[36:37], v[168:169]
	v_pk_fma_f32 v[38:39], v[62:63], v[38:39], v[170:171]
	v_pk_fma_f32 v[8:9], v[88:89], v[124:125], v[8:9]
	v_pk_fma_f32 v[10:11], v[90:91], v[126:127], v[10:11]
	v_pk_fma_f32 v[36:37], v[76:77], v[132:133], v[36:37]
	v_pk_fma_f32 v[38:39], v[78:79], v[134:135], v[38:39]
	s_mov_b64 s[30:31], exec
	s_andn2_b64 exec, exec, s[36:37]
	v_pk_fma_f32 v[8:9], v[152:153], v[72:73], v[8:9]
	v_pk_fma_f32 v[10:11], v[154:155], v[74:75], v[10:11]
	v_pk_fma_f32 v[36:37], v[156:157], v[64:65], v[36:37]
	v_pk_fma_f32 v[38:39], v[158:159], v[66:67], v[38:39]
	s_mov_b64 exec, s[30:31]
	v_and_b32_e32 v212, 0x7fffffff, v8
	v_and_b32_e32 v213, 0x7fffffff, v9
	v_and_b32_e32 v6, 0x7fffffff, v10
	v_and_b32_e32 v7, 0x7fffffff, v11
	v_pk_fma_f32 v[238:239], v[212:213], s[90:91], 1.0 op_sel_hi:[1,0,0]
	v_pk_fma_f32 v[16:17], v[6:7], s[90:91], 1.0 op_sel_hi:[1,0,0]
	v_pk_mul_f32 v[4:5], v[8:9], v[8:9]
	v_pk_mul_f32 v[28:29], v[10:11], v[10:11]
	v_rcp_f32_e32 v238, v238
	v_rcp_f32_e32 v239, v239
	v_rcp_f32_e32 v16, v16
	v_rcp_f32_e32 v17, v17
	v_pk_mul_f32 v[4:5], v[4:5], s[44:45] op_sel_hi:[1,0]
	v_pk_mul_f32 v[28:29], v[28:29], s[44:45] op_sel_hi:[1,0]
	v_pk_fma_f32 v[246:247], v[238:239], s[92:93], v[236:237] op_sel_hi:[1,0,0]
	v_pk_fma_f32 v[18:19], v[16:17], s[92:93], v[236:237] op_sel_hi:[1,0,0]
	v_exp_f32_e32 v4, v4
	v_exp_f32_e32 v5, v5
	v_exp_f32_e32 v28, v28
	v_exp_f32_e32 v29, v29
	v_pk_fma_f32 v[246:247], v[238:239], v[246:247], s[96:97] op_sel_hi:[1,1,0]
	v_pk_fma_f32 v[18:19], v[16:17], v[18:19], s[96:97] op_sel_hi:[1,1,0]
	v_pk_fma_f32 v[246:247], v[238:239], v[246:247], s[0:1] op_sel_hi:[1,1,0]
	v_pk_fma_f32 v[18:19], v[16:17], v[18:19], s[0:1] op_sel_hi:[1,1,0]
	v_pk_fma_f32 v[246:247], v[238:239], v[246:247], s[4:5] op_sel_hi:[1,1,0]
	v_pk_fma_f32 v[18:19], v[16:17], v[18:19], s[4:5] op_sel_hi:[1,1,0]
	v_pk_mul_f32 v[246:247], v[238:239], v[246:247]
	v_pk_mul_f32 v[18:19], v[16:17], v[18:19]
	v_max_f32_e32 v238, 0, v8
	v_max_f32_e32 v239, 0, v9
	v_max_f32_e32 v16, 0, v10
	v_max_f32_e32 v17, 0, v11
	v_pk_mul_f32 v[246:247], v[4:5], v[246:247]
	v_pk_mul_f32 v[18:19], v[28:29], v[18:19]
	v_pk_fma_f32 v[4:5], v[212:213], v[246:247], v[238:239] neg_lo:[1,0,0] neg_hi:[1,0,0]
	v_pk_fma_f32 v[28:29], v[6:7], v[18:19], v[16:17] neg_lo:[1,0,0] neg_hi:[1,0,0]
	v_pk_mul_f32 v[246:247], v[4:5], v[36:37]
	v_pk_mul_f32 v[18:19], v[28:29], v[38:39]
	v_cvt_pk_bf16_f32 v174, v246, v247
	v_cvt_pk_bf16_f32 v175, v18, v19
	v_add_u32_e32 v235, 128, v227
	v_add_u32_e32 v245, 129, v228
	v_cmp_gt_u32_e64 s[38:39], s64, v235
	v_cmp_gt_u32_e32 vcc, s88, v245
	v_add_u32_e32 v235, 726528, v230
	s_and_b64 s[38:39], s[38:39], vcc
	s_and_saveexec_b64 s[30:31], s[38:39]
	global_store_dwordx4 v235, v[172:175], s[50:51]
	s_mov_b64 exec, s[30:31]
	s_nop 1
	v_add_u32_e32 v235, 130, v228
	v_cmp_gt_i32_e32 vcc, 0x4000, v235
	s_nop 1
	v_cndmask_b32_e32 v245, v222, v221, vcc
	v_and_b32_e32 v235, v235, v245
	v_cmp_eq_u32_e64 s[34:35], 0, v235
	v_cmp_eq_u32_e64 s[36:37], v235, v245
	s_nop 1
	v_cndmask_b32_e64 v88, v88, 0, s[34:35]
	v_cndmask_b32_e64 v89, v89, 0, s[34:35]
	v_cndmask_b32_e64 v90, v90, 0, s[34:35]
	v_cndmask_b32_e64 v91, v91, 0, s[34:35]
	v_cndmask_b32_e64 v76, v76, 0, s[34:35]
	v_cndmask_b32_e64 v77, v77, 0, s[34:35]
	v_cndmask_b32_e64 v78, v78, 0, s[34:35]
	v_cndmask_b32_e64 v79, v79, 0, s[34:35]
	v_pk_fma_f32 v[88:89], v[44:45], v[88:89], v[164:165]
	v_pk_fma_f32 v[90:91], v[46:47], v[90:91], v[166:167]
	v_pk_fma_f32 v[76:77], v[60:61], v[76:77], v[168:169]
	v_pk_fma_f32 v[78:79], v[62:63], v[78:79], v[170:171]
	v_pk_fma_f32 v[88:89], v[72:73], v[124:125], v[88:89]
	v_pk_fma_f32 v[90:91], v[74:75], v[126:127], v[90:91]
	v_pk_fma_f32 v[76:77], v[64:65], v[132:133], v[76:77]
	v_pk_fma_f32 v[78:79], v[66:67], v[134:135], v[78:79]
	s_mov_b64 s[30:31], exec
	s_andn2_b64 exec, exec, s[36:37]
	v_pk_fma_f32 v[88:89], v[152:153], v[0:1], v[88:89]
	v_pk_fma_f32 v[90:91], v[154:155], v[2:3], v[90:91]
	v_pk_fma_f32 v[76:77], v[156:157], v[128:129], v[76:77]
	v_pk_fma_f32 v[78:79], v[158:159], v[130:131], v[78:79]
	s_mov_b64 exec, s[30:31]
	v_and_b32_e32 v212, 0x7fffffff, v88
	v_and_b32_e32 v213, 0x7fffffff, v89
	v_and_b32_e32 v6, 0x7fffffff, v90
	v_and_b32_e32 v7, 0x7fffffff, v91
	v_pk_fma_f32 v[238:239], v[212:213], s[90:91], 1.0 op_sel_hi:[1,0,0]
	v_pk_fma_f32 v[8:9], v[6:7], s[90:91], 1.0 op_sel_hi:[1,0,0]
	v_pk_mul_f32 v[4:5], v[88:89], v[88:89]
	v_pk_mul_f32 v[16:17], v[90:91], v[90:91]
	v_rcp_f32_e32 v238, v238
	v_rcp_f32_e32 v239, v239
	v_rcp_f32_e32 v8, v8
	v_rcp_f32_e32 v9, v9
	v_pk_mul_f32 v[4:5], v[4:5], s[44:45] op_sel_hi:[1,0]
	v_pk_mul_f32 v[16:17], v[16:17], s[44:45] op_sel_hi:[1,0]
	v_pk_fma_f32 v[246:247], v[238:239], s[92:93], v[236:237] op_sel_hi:[1,0,0]
	v_pk_fma_f32 v[10:11], v[8:9], s[92:93], v[236:237] op_sel_hi:[1,0,0]
	v_exp_f32_e32 v4, v4
	v_exp_f32_e32 v5, v5
	v_exp_f32_e32 v16, v16
	v_exp_f32_e32 v17, v17
	v_pk_fma_f32 v[246:247], v[238:239], v[246:247], s[96:97] op_sel_hi:[1,1,0]
	v_pk_fma_f32 v[10:11], v[8:9], v[10:11], s[96:97] op_sel_hi:[1,1,0]
	v_pk_fma_f32 v[246:247], v[238:239], v[246:247], s[0:1] op_sel_hi:[1,1,0]
	v_pk_fma_f32 v[10:11], v[8:9], v[10:11], s[0:1] op_sel_hi:[1,1,0]
	v_pk_fma_f32 v[246:247], v[238:239], v[246:247], s[4:5] op_sel_hi:[1,1,0]
	v_pk_fma_f32 v[10:11], v[8:9], v[10:11], s[4:5] op_sel_hi:[1,1,0]
	v_pk_mul_f32 v[246:247], v[238:239], v[246:247]
	v_pk_mul_f32 v[10:11], v[8:9], v[10:11]
	v_max_f32_e32 v238, 0, v88
	v_max_f32_e32 v239, 0, v89
	v_max_f32_e32 v8, 0, v90
	v_max_f32_e32 v9, 0, v91
	v_pk_mul_f32 v[246:247], v[4:5], v[246:247]
	v_pk_mul_f32 v[10:11], v[16:17], v[10:11]
	v_pk_fma_f32 v[4:5], v[212:213], v[246:247], v[238:239] neg_lo:[1,0,0] neg_hi:[1,0,0]
	v_pk_fma_f32 v[16:17], v[6:7], v[10:11], v[8:9] neg_lo:[1,0,0] neg_hi:[1,0,0]
	v_pk_mul_f32 v[246:247], v[4:5], v[76:77]
	v_pk_mul_f32 v[10:11], v[16:17], v[78:79]
	v_cvt_pk_bf16_f32 v14, v246, v247
	v_cvt_pk_bf16_f32 v15, v10, v11
	v_add_u32_e32 v235, 129, v227
	v_add_u32_e32 v245, 130, v228
	v_cmp_gt_u32_e64 s[38:39], s64, v235
	v_cmp_gt_u32_e32 vcc, s88, v245
	v_add_u32_e32 v235, 732160, v230
	s_and_b64 s[38:39], s[38:39], vcc
	s_and_saveexec_b64 s[30:31], s[38:39]
	global_store_dwordx4 v235, v[12:15], s[50:51]
	s_mov_b64 exec, s[30:31]
	s_nop 1
	v_add_u32_e32 v235, 131, v228
	v_cmp_gt_i32_e32 vcc, 0x4000, v235
	s_nop 1
	v_cndmask_b32_e32 v245, v222, v221, vcc
	v_and_b32_e32 v235, v235, v245
	v_cmp_eq_u32_e64 s[34:35], 0, v235
	v_cmp_eq_u32_e64 s[36:37], v235, v245
	s_nop 1
	v_cndmask_b32_e64 v72, v72, 0, s[34:35]
	v_cndmask_b32_e64 v73, v73, 0, s[34:35]
	v_cndmask_b32_e64 v74, v74, 0, s[34:35]
	v_cndmask_b32_e64 v75, v75, 0, s[34:35]
	v_cndmask_b32_e64 v64, v64, 0, s[34:35]
	v_cndmask_b32_e64 v65, v65, 0, s[34:35]
	v_cndmask_b32_e64 v66, v66, 0, s[34:35]
	v_cndmask_b32_e64 v67, v67, 0, s[34:35]
	v_pk_fma_f32 v[72:73], v[44:45], v[72:73], v[164:165]
	v_pk_fma_f32 v[74:75], v[46:47], v[74:75], v[166:167]
	v_pk_fma_f32 v[64:65], v[60:61], v[64:65], v[168:169]
	v_pk_fma_f32 v[66:67], v[62:63], v[66:67], v[170:171]
	v_pk_fma_f32 v[72:73], v[0:1], v[124:125], v[72:73]
	v_pk_fma_f32 v[74:75], v[2:3], v[126:127], v[74:75]
	v_pk_fma_f32 v[64:65], v[128:129], v[132:133], v[64:65]
	v_pk_fma_f32 v[66:67], v[130:131], v[134:135], v[66:67]
	s_mov_b64 s[30:31], exec
	s_andn2_b64 exec, exec, s[36:37]
	v_pk_fma_f32 v[72:73], v[152:153], v[20:21], v[72:73]
	v_pk_fma_f32 v[74:75], v[154:155], v[22:23], v[74:75]
	v_pk_fma_f32 v[64:65], v[156:157], v[24:25], v[64:65]
	v_pk_fma_f32 v[66:67], v[158:159], v[26:27], v[66:67]
	s_mov_b64 exec, s[30:31]
	v_and_b32_e32 v212, 0x7fffffff, v72
	v_and_b32_e32 v213, 0x7fffffff, v73
	v_and_b32_e32 v6, 0x7fffffff, v74
	v_and_b32_e32 v7, 0x7fffffff, v75
	v_pk_fma_f32 v[238:239], v[212:213], s[90:91], 1.0 op_sel_hi:[1,0,0]
	v_pk_fma_f32 v[8:9], v[6:7], s[90:91], 1.0 op_sel_hi:[1,0,0]
	v_pk_mul_f32 v[4:5], v[72:73], v[72:73]
	v_pk_mul_f32 v[12:13], v[74:75], v[74:75]
	v_rcp_f32_e32 v238, v238
	v_rcp_f32_e32 v239, v239
	v_rcp_f32_e32 v8, v8
	v_rcp_f32_e32 v9, v9
	v_pk_mul_f32 v[4:5], v[4:5], s[44:45] op_sel_hi:[1,0]
	v_pk_mul_f32 v[12:13], v[12:13], s[44:45] op_sel_hi:[1,0]
	v_pk_fma_f32 v[246:247], v[238:239], s[92:93], v[236:237] op_sel_hi:[1,0,0]
	v_pk_fma_f32 v[10:11], v[8:9], s[92:93], v[236:237] op_sel_hi:[1,0,0]
	v_exp_f32_e32 v4, v4
	v_exp_f32_e32 v5, v5
	v_exp_f32_e32 v12, v12
	v_exp_f32_e32 v13, v13
	v_pk_fma_f32 v[246:247], v[238:239], v[246:247], s[96:97] op_sel_hi:[1,1,0]
	v_pk_fma_f32 v[10:11], v[8:9], v[10:11], s[96:97] op_sel_hi:[1,1,0]
	v_pk_fma_f32 v[246:247], v[238:239], v[246:247], s[0:1] op_sel_hi:[1,1,0]
	v_pk_fma_f32 v[10:11], v[8:9], v[10:11], s[0:1] op_sel_hi:[1,1,0]
	v_pk_fma_f32 v[246:247], v[238:239], v[246:247], s[4:5] op_sel_hi:[1,1,0]
	v_pk_fma_f32 v[10:11], v[8:9], v[10:11], s[4:5] op_sel_hi:[1,1,0]
	v_pk_mul_f32 v[246:247], v[238:239], v[246:247]
	v_pk_mul_f32 v[10:11], v[8:9], v[10:11]
	v_max_f32_e32 v238, 0, v72
	v_max_f32_e32 v239, 0, v73
	v_max_f32_e32 v8, 0, v74
	v_max_f32_e32 v9, 0, v75
	v_pk_mul_f32 v[246:247], v[4:5], v[246:247]
	v_pk_mul_f32 v[10:11], v[12:13], v[10:11]
	v_pk_fma_f32 v[4:5], v[212:213], v[246:247], v[238:239] neg_lo:[1,0,0] neg_hi:[1,0,0]
	v_pk_fma_f32 v[12:13], v[6:7], v[10:11], v[8:9] neg_lo:[1,0,0] neg_hi:[1,0,0]
	v_pk_mul_f32 v[246:247], v[4:5], v[64:65]
	v_pk_mul_f32 v[10:11], v[12:13], v[66:67]
	v_cvt_pk_bf16_f32 v42, v246, v247
	v_cvt_pk_bf16_f32 v43, v10, v11
	v_add_u32_e32 v235, 130, v227
	v_add_u32_e32 v245, 131, v228
	v_cmp_gt_u32_e64 s[38:39], s64, v235
	v_cmp_gt_u32_e32 vcc, s88, v245
	v_add_u32_e32 v235, 737792, v230
	s_and_b64 s[38:39], s[38:39], vcc
	s_and_saveexec_b64 s[30:31], s[38:39]
	global_store_dwordx4 v235, v[40:43], s[50:51]
	s_mov_b64 exec, s[30:31]
	s_nop 1
.Lp5_done:
	s_and_b64 vcc, exec, s[6:7]
	s_mov_b64 s[6:7], -1
	s_cbranch_vccnz .LBB0_532

	.amdhsa_kernel _Z9hymba_fwd4Args
		.amdhsa_group_segment_fixed_size 0
		.amdhsa_private_segment_fixed_size 0
		.amdhsa_kernarg_size 400
		.amdhsa_user_sgpr_count 2
		.amdhsa_user_sgpr_dispatch_ptr 0
		.amdhsa_user_sgpr_queue_ptr 0
		.amdhsa_user_sgpr_kernarg_segment_ptr 1
		.amdhsa_user_sgpr_dispatch_id 0
		.amdhsa_user_sgpr_kernarg_preload_length 0
		.amdhsa_user_sgpr_kernarg_preload_offset 0
		.amdhsa_user_sgpr_private_segment_size 0
		.amdhsa_uses_dynamic_stack 0
		.amdhsa_enable_private_segment 0
		.amdhsa_system_sgpr_workgroup_id_x 1
		.amdhsa_system_sgpr_workgroup_id_y 0
		.amdhsa_system_sgpr_workgroup_id_z 0
		.amdhsa_system_sgpr_workgroup_info 0
		.amdhsa_system_vgpr_workitem_id 2
		.amdhsa_next_free_vgpr 256
		.amdhsa_next_free_sgpr 98
		.amdhsa_accum_offset 256
		.amdhsa_reserve_vcc 1
		.amdhsa_float_round_mode_32 0
		.amdhsa_float_round_mode_16_64 0
		.amdhsa_float_denorm_mode_32 3
		.amdhsa_float_denorm_mode_16_64 3
		.amdhsa_dx10_clamp 1
		.amdhsa_ieee_mode 1
		.amdhsa_fp16_overflow 0
		.amdhsa_tg_split 0
		.amdhsa_exception_fp_ieee_invalid_op 0
		.amdhsa_exception_fp_denorm_src 0
		.amdhsa_exception_fp_ieee_div_zero 0
		.amdhsa_exception_fp_ieee_overflow 0
		.amdhsa_exception_fp_ieee_underflow 0
		.amdhsa_exception_fp_ieee_inexact 0
		.amdhsa_exception_int_div_zero 0
	.end_amdhsa_kernel

amdhsa.kernels:
  - .agpr_count:     0
    .args:
      - .offset:         0
        .size:           144
        .value_kind:     by_value
      - .offset:         144
        .size:           4
        .value_kind:     hidden_block_count_x
      - .offset:         148
        .size:           4
        .value_kind:     hidden_block_count_y
      - .offset:         152
        .size:           4
        .value_kind:     hidden_block_count_z
      - .offset:         156
        .size:           2
        .value_kind:     hidden_group_size_x
      - .offset:         158
        .size:           2
        .value_kind:     hidden_group_size_y
      - .offset:         160
        .size:           2
        .value_kind:     hidden_group_size_z
      - .offset:         162
        .size:           2
        .value_kind:     hidden_remainder_x
      - .offset:         164
        .size:           2
        .value_kind:     hidden_remainder_y
      - .offset:         166
        .size:           2
        .value_kind:     hidden_remainder_z
      - .offset:         184
        .size:           8
        .value_kind:     hidden_global_offset_x
      - .offset:         192
        .size:           8
        .value_kind:     hidden_global_offset_y
      - .offset:         200
        .size:           8
        .value_kind:     hidden_global_offset_z
      - .offset:         208
        .size:           2
        .value_kind:     hidden_grid_dims
      - .offset:         232
        .size:           8
        .value_kind:     hidden_multigrid_sync_arg
      - .offset:         264
        .size:           4
        .value_kind:     hidden_dynamic_lds_size
    .group_segment_fixed_size: 0
    .kernarg_segment_align: 8
    .kernarg_segment_size: 400
    .language:       OpenCL C
    .language_version:
      - 2
      - 0
    .max_flat_workgroup_size: 512
    .name:           _Z9hymba_fwd4Args
    .private_segment_fixed_size: 0
    .sgpr_count:     104
    .sgpr_spill_count: 63
    .symbol:         _Z9hymba_fwd4Args.kd
    .uniform_work_group_size: 1
    .uses_dynamic_stack: false
    .vgpr_count:     256
    .vgpr_spill_count: 0
    .wavefront_size: 64
